# K-loop: leading wave half defers its vmcnt(8) wait from the pre-MMA barrier to the early barrier inside the MMA block (one more slot of DMA flight); trailing half unchanged
# baseline (speedup 1.0000x reference)
_Z4mega5MArgs:
	v_lshl_add_u32 v1, v0, 2, 0
	v_add_u32_e32 v1, 0x20000, v1
	v_mov_b32_e32 v2, 0
	ds_write2st64_b32 v1, v2, v2 offset1:8
	ds_write2st64_b32 v1, v2, v2 offset0:16 offset1:24
	v_or_b32_e32 v1, 0x800, v0
	s_mov_b64 s[4:5], -1
	s_and_saveexec_b64 s[6:7], s[4:5]
	v_lshl_add_u32 v3, v1, 2, 0
	v_add_u32_e32 v3, 0x20000, v3
	ds_write_b32 v3, v2
	s_or_b64 exec, exec, s[6:7]
	s_and_saveexec_b64 s[6:7], s[4:5]
	s_add_i32 s3, 0, 0x20000
	v_lshl_add_u32 v1, v1, 2, s3
	v_mov_b32_e32 v2, 0
	ds_write_b32 v1, v2 offset:2048
	s_or_b64 exec, exec, s[6:7]
	v_or_b32_e32 v1, 0xc00, v0
	v_cmp_gt_u32_e64 s[4:5], 7, 6
	v_cmp_gt_u32_e64 s[8:9], 7, 5
	s_and_saveexec_b64 s[6:7], s[8:9]
	v_lshl_add_u32 v2, v1, 2, 0
	v_add_u32_e32 v2, 0x20000, v2
	v_mov_b32_e32 v3, 0
	ds_write_b32 v2, v3
	s_or_b64 exec, exec, s[6:7]
	s_and_saveexec_b64 s[6:7], s[4:5]
	s_add_i32 s3, 0, 0x20000
	v_lshl_add_u32 v1, v1, 2, s3
	v_mov_b32_e32 v2, 0
	ds_write_b32 v1, v2 offset:2048
	s_or_b64 exec, exec, s[6:7]
	s_waitcnt lgkmcnt(0)
	s_barrier
	s_load_dwordx2 s[34:35], s[0:1], 0xa0
	s_getreg_b32 s3, hwreg(HW_REG_XCC_ID, 0, 4)
	v_readfirstlane_b32 s33, v0
	s_lshr_b32 s100, s33, 8
	v_cmp_eq_u32_e64 s[10:11], 0, v0
	s_waitcnt lgkmcnt(0)
	s_add_u32 s52, s34, 0x4000
	s_addc_u32 s53, s35, 0
	s_and_b32 s3, s3, 15
	s_and_saveexec_b64 s[4:5], s[10:11]
	s_cbranch_execz .LBB0_11
	s_mov_b64 s[6:7], exec
	v_mbcnt_lo_u32_b32 v0, s6, 0
	v_mbcnt_hi_u32_b32 v0, s7, v0
	v_cmp_eq_u32_e32 vcc, 0, v0
	s_and_b64 s[8:9], exec, vcc
	s_mov_b64 exec, s[8:9]
	s_cbranch_execz .LBB0_11
	s_lshl_b32 s8, s3, 8
	s_bcnt1_i32_b64 s6, s[6:7]
	v_mov_b32_e32 v0, s8
	v_mov_b32_e32 v1, s6
	global_atomic_add v0, v1, s[52:53] offset:1024
	s_and_b32 s8, s2, 7
	s_lshl_b32 s8, s8, 8
	s_add_u32 s8, s8, 0xc000
	v_mov_b32_e32 v0, s8
	v_mov_b32_e32 v1, s3
	global_atomic_umax v0, v1, s[52:53]
	v_sub_u32_e32 v1, 15, v1
	global_atomic_umax v0, v1, s[52:53] offset:128

.LBB0_322:
	s_ashr_i32 s43, s42, 31
	s_lshl_b64 s[46:47], s[42:43], 19
	s_add_u32 s46, s12, s46
	s_addc_u32 s47, s13, s47
	s_and_b64 s[48:49], s[4:5], exec
	s_cselect_b32 s18, s47, s7
	s_cselect_b32 s43, s46, s6
	s_ashr_i32 s45, s44, 31
	s_lshl_b64 s[48:49], s[44:45], 19
	s_add_u32 s48, s59, s48
	s_addc_u32 s49, s60, s49
	s_and_b64 s[50:51], s[4:5], exec
	s_cselect_b32 s45, s49, s9
	s_cselect_b32 s55, s48, s8
	s_add_u32 s6, s6, 0x40080
	s_addc_u32 s7, s7, 0
	s_add_u32 s56, s8, 0x100
	s_addc_u32 s57, s9, 0
	s_mov_b32 s78, -2
	ds_read_b128 v[96:99], v209
	ds_read_b128 v[100:103], v209 offset:1024
	ds_read_b128 v[120:123], v209 offset:2048
	ds_read_b128 v[124:127], v209 offset:3072
	ds_read_b128 v[144:147], v210
	ds_read_b128 v[148:151], v210 offset:1024
	ds_read_b128 v[152:155], v210 offset:2048
	ds_read_b128 v[156:159], v210 offset:3072
	s_add_u32 s8, s6, 0xfffc0080
	s_addc_u32 s9, s7, -1
	s_cmp_eq_u32 s78, 12
	s_cselect_b32 s51, s18, s9
	s_cselect_b32 s50, s43, s8
	s_cselect_b32 s9, s45, s57
	s_cselect_b32 s8, s55, s56
	v_lshl_add_u64 v[206:207], s[6:7], 0, v[170:171]
	s_add_i32 m0, s17, 0xc000
	ds_read_b128 v[178:181], v211
	ds_read_b128 v[182:185], v211 offset:1024
	ds_read_b128 v[186:189], v211 offset:2048
	ds_read_b128 v[190:193], v211 offset:3072
	ds_read_b128 v[194:197], v211 offset:4096
	ds_read_b128 v[198:201], v211 offset:5120
	ds_read_b128 v[202:205], v211 offset:6144
	ds_read_b128 v[218:221], v211 offset:7168
	global_load_lds_dwordx4 v[206:207], off
	s_add_i32 m0, s17, 0xe000
	v_lshl_add_u64 v[206:207], s[6:7], 0, v[172:173]
	global_load_lds_dwordx4 v[206:207], off
	s_cmp_eq_u32 s100, 0
	s_waitcnt lgkmcnt(0)
	s_cbranch_scc1 .Ldw_1
	s_waitcnt vmcnt(8)
.Ldw_1:
	s_barrier
	s_setprio 1
	v_mfma_f32_16x16x32_bf16 v[140:143], v[96:99], v[178:181], 0
	v_mfma_f32_16x16x32_bf16 v[136:139], v[120:123], v[178:181], 0
	v_mfma_f32_16x16x32_bf16 v[116:119], v[96:99], v[186:189], 0
	v_mfma_f32_16x16x32_bf16 v[112:115], v[120:123], v[186:189], 0
	v_mfma_f32_16x16x32_bf16 v[92:95], v[96:99], v[194:197], 0
	v_mfma_f32_16x16x32_bf16 v[88:91], v[120:123], v[194:197], 0
	v_mfma_f32_16x16x32_bf16 v[76:79], v[96:99], v[202:205], 0
	v_mfma_f32_16x16x32_bf16 v[72:75], v[120:123], v[202:205], 0
	v_mfma_f32_16x16x32_bf16 v[140:143], v[100:103], v[182:185], v[140:143]
	v_mfma_f32_16x16x32_bf16 v[136:139], v[124:127], v[182:185], v[136:139]
	v_mfma_f32_16x16x32_bf16 v[116:119], v[100:103], v[190:193], v[116:119]
	v_mfma_f32_16x16x32_bf16 v[112:115], v[124:127], v[190:193], v[112:115]
	v_mfma_f32_16x16x32_bf16 v[92:95], v[100:103], v[198:201], v[92:95]
	v_mfma_f32_16x16x32_bf16 v[88:91], v[124:127], v[198:201], v[88:91]
	v_mfma_f32_16x16x32_bf16 v[76:79], v[100:103], v[218:221], v[76:79]
	v_mfma_f32_16x16x32_bf16 v[72:75], v[124:127], v[218:221], v[72:75]
	s_setprio 0
	s_setprio 1
	v_mfma_f32_16x16x32_bf16 v[132:135], v[144:147], v[178:181], 0
	v_mfma_f32_16x16x32_bf16 v[128:131], v[152:155], v[178:181], 0
	v_mfma_f32_16x16x32_bf16 v[108:111], v[144:147], v[186:189], 0
	v_mfma_f32_16x16x32_bf16 v[104:107], v[152:155], v[186:189], 0
	v_mfma_f32_16x16x32_bf16 v[84:87], v[144:147], v[194:197], 0
	v_mfma_f32_16x16x32_bf16 v[80:83], v[152:155], v[194:197], 0
	v_mfma_f32_16x16x32_bf16 v[68:71], v[144:147], v[202:205], 0
	v_mfma_f32_16x16x32_bf16 v[64:67], v[152:155], v[202:205], 0
	v_mfma_f32_16x16x32_bf16 v[132:135], v[148:151], v[182:185], v[132:135]
	v_mfma_f32_16x16x32_bf16 v[128:131], v[156:159], v[182:185], v[128:131]
	v_mfma_f32_16x16x32_bf16 v[108:111], v[148:151], v[190:193], v[108:111]
	v_mfma_f32_16x16x32_bf16 v[104:107], v[156:159], v[190:193], v[104:107]
	s_waitcnt vmcnt(8)
	s_setprio 2
	s_barrier
	v_mfma_f32_16x16x32_bf16 v[84:87], v[148:151], v[198:201], v[84:87]
	v_mfma_f32_16x16x32_bf16 v[80:83], v[156:159], v[198:201], v[80:83]
	v_mfma_f32_16x16x32_bf16 v[68:71], v[148:151], v[218:221], v[68:71]
	v_mfma_f32_16x16x32_bf16 v[64:67], v[156:159], v[218:221], v[64:67]
	s_setprio 2
	s_add_i32 s79, s73, s61
	v_lshl_add_u64 v[206:207], s[8:9], 0, v[162:163]
	s_mov_b32 m0, s79
	ds_read_b128 v[178:181], v211 offset:16384
	ds_read_b128 v[182:185], v211 offset:17408
	ds_read_b128 v[186:189], v211 offset:18432
	ds_read_b128 v[190:193], v211 offset:19456
	ds_read_b128 v[194:197], v211 offset:20480
	ds_read_b128 v[198:201], v211 offset:21504
	ds_read_b128 v[202:205], v211 offset:22528
	ds_read_b128 v[218:221], v211 offset:23552
	global_load_lds_dwordx4 v[206:207], off
	s_add_i32 m0, s79, 0x2000
	s_add_u32 s80, s8, 0x40000
	v_lshl_add_u64 v[222:223], s[8:9], 0, v[166:167]
	s_addc_u32 s81, s9, 0
	s_add_i32 s79, s74, s61
	global_load_lds_dwordx4 v[222:223], off
	v_lshl_add_u64 v[224:225], s[80:81], 0, v[162:163]
	s_mov_b32 m0, s79
	v_lshl_add_u64 v[226:227], s[50:51], 0, v[164:165]
	global_load_lds_dwordx4 v[224:225], off
	s_add_i32 m0, s79, 0x2000
	v_lshl_add_u64 v[224:225], s[80:81], 0, v[166:167]
	global_load_lds_dwordx4 v[224:225], off
	s_mov_b32 m0, s17
	v_lshl_add_u64 v[224:225], s[50:51], 0, v[160:161]
	global_load_lds_dwordx4 v[224:225], off
	s_mov_b32 m0, s62
	s_nop 0
	global_load_lds_dwordx4 v[226:227], off
	s_cmp_eq_u32 s100, 0
	s_waitcnt lgkmcnt(0)
	s_cbranch_scc1 .Ldw_2
	s_waitcnt vmcnt(8)
.Ldw_2:
	s_barrier
	s_setprio 1
	v_mfma_f32_16x16x32_bf16 v[60:63], v[96:99], v[178:181], 0
	v_mfma_f32_16x16x32_bf16 v[56:59], v[120:123], v[178:181], 0
	v_mfma_f32_16x16x32_bf16 v[44:47], v[96:99], v[186:189], 0
	v_mfma_f32_16x16x32_bf16 v[40:43], v[120:123], v[186:189], 0
	v_mfma_f32_16x16x32_bf16 v[28:31], v[96:99], v[194:197], 0
	v_mfma_f32_16x16x32_bf16 v[24:27], v[120:123], v[194:197], 0
	v_mfma_f32_16x16x32_bf16 v[12:15], v[96:99], v[202:205], 0
	v_mfma_f32_16x16x32_bf16 v[8:11], v[120:123], v[202:205], 0
	v_mfma_f32_16x16x32_bf16 v[60:63], v[100:103], v[182:185], v[60:63]
	v_mfma_f32_16x16x32_bf16 v[56:59], v[124:127], v[182:185], v[56:59]
	v_mfma_f32_16x16x32_bf16 v[44:47], v[100:103], v[190:193], v[44:47]
	v_mfma_f32_16x16x32_bf16 v[40:43], v[124:127], v[190:193], v[40:43]
	v_mfma_f32_16x16x32_bf16 v[28:31], v[100:103], v[198:201], v[28:31]
	v_mfma_f32_16x16x32_bf16 v[24:27], v[124:127], v[198:201], v[24:27]
	v_mfma_f32_16x16x32_bf16 v[12:15], v[100:103], v[218:221], v[12:15]
	v_mfma_f32_16x16x32_bf16 v[8:11], v[124:127], v[218:221], v[8:11]
	s_setprio 0
	s_setprio 1
	v_mfma_f32_16x16x32_bf16 v[52:55], v[144:147], v[178:181], 0
	v_mfma_f32_16x16x32_bf16 v[48:51], v[152:155], v[178:181], 0
	v_mfma_f32_16x16x32_bf16 v[36:39], v[144:147], v[186:189], 0
	v_mfma_f32_16x16x32_bf16 v[32:35], v[152:155], v[186:189], 0
	v_mfma_f32_16x16x32_bf16 v[20:23], v[144:147], v[194:197], 0
	v_mfma_f32_16x16x32_bf16 v[16:19], v[152:155], v[194:197], 0
	v_mfma_f32_16x16x32_bf16 v[4:7], v[144:147], v[202:205], 0
	v_mfma_f32_16x16x32_bf16 v[0:3], v[152:155], v[202:205], 0
	v_mfma_f32_16x16x32_bf16 v[52:55], v[148:151], v[182:185], v[52:55]
	v_mfma_f32_16x16x32_bf16 v[48:51], v[156:159], v[182:185], v[48:51]
	v_mfma_f32_16x16x32_bf16 v[36:39], v[148:151], v[190:193], v[36:39]
	v_mfma_f32_16x16x32_bf16 v[32:35], v[156:159], v[190:193], v[32:35]
	s_waitcnt vmcnt(8)
	s_setprio 2
	s_barrier
	v_mfma_f32_16x16x32_bf16 v[20:23], v[148:151], v[198:201], v[20:23]
	v_mfma_f32_16x16x32_bf16 v[16:19], v[156:159], v[198:201], v[16:19]
	v_mfma_f32_16x16x32_bf16 v[4:7], v[148:151], v[218:221], v[4:7]
	v_mfma_f32_16x16x32_bf16 v[0:3], v[156:159], v[218:221], v[0:3]
	s_setprio 0
	s_add_i32 s79, 0, 0x18000
	s_add_i32 s80, 0, 0x1c000
	v_add_u32_e32 v124, s79, v208
	v_add_u32_e32 v156, s80, v208
	ds_read_b128 v[96:99], v124
	ds_read_b128 v[100:103], v124 offset:1024
	ds_read_b128 v[120:123], v124 offset:2048
	ds_read_b128 v[124:127], v124 offset:3072
	ds_read_b128 v[144:147], v156
	ds_read_b128 v[148:151], v156 offset:1024
	ds_read_b128 v[152:155], v156 offset:2048
	ds_read_b128 v[156:159], v156 offset:3072
	s_add_u32 s50, s50, 0x40000
	s_addc_u32 s51, s51, 0
	s_mov_b32 m0, s63
	v_lshl_add_u64 v[228:229], s[50:51], 0, v[160:161]
	ds_read_b128 v[178:181], v211 offset:32768
	ds_read_b128 v[182:185], v211 offset:33792
	ds_read_b128 v[186:189], v211 offset:34816
	ds_read_b128 v[190:193], v211 offset:35840
	ds_read_b128 v[194:197], v211 offset:36864
	ds_read_b128 v[198:201], v211 offset:37888
	ds_read_b128 v[202:205], v211 offset:38912
	ds_read_b128 v[218:221], v211 offset:39936
	global_load_lds_dwordx4 v[228:229], off
	s_mov_b32 m0, s64
	v_lshl_add_u64 v[228:229], s[50:51], 0, v[164:165]
	global_load_lds_dwordx4 v[228:229], off
	s_cmp_eq_u32 s100, 0
	s_waitcnt lgkmcnt(0)
	s_cbranch_scc1 .Ldw_3
	s_waitcnt vmcnt(8)
.Ldw_3:
	s_barrier
	s_setprio 1
	v_mfma_f32_16x16x32_bf16 v[140:143], v[96:99], v[178:181], v[140:143]
	v_mfma_f32_16x16x32_bf16 v[136:139], v[120:123], v[178:181], v[136:139]
	v_mfma_f32_16x16x32_bf16 v[116:119], v[96:99], v[186:189], v[116:119]
	v_mfma_f32_16x16x32_bf16 v[112:115], v[120:123], v[186:189], v[112:115]
	v_mfma_f32_16x16x32_bf16 v[92:95], v[96:99], v[194:197], v[92:95]
	v_mfma_f32_16x16x32_bf16 v[88:91], v[120:123], v[194:197], v[88:91]
	v_mfma_f32_16x16x32_bf16 v[76:79], v[96:99], v[202:205], v[76:79]
	v_mfma_f32_16x16x32_bf16 v[72:75], v[120:123], v[202:205], v[72:75]
	v_mfma_f32_16x16x32_bf16 v[140:143], v[100:103], v[182:185], v[140:143]
	v_mfma_f32_16x16x32_bf16 v[136:139], v[124:127], v[182:185], v[136:139]
	v_mfma_f32_16x16x32_bf16 v[116:119], v[100:103], v[190:193], v[116:119]
	v_mfma_f32_16x16x32_bf16 v[112:115], v[124:127], v[190:193], v[112:115]
	v_mfma_f32_16x16x32_bf16 v[92:95], v[100:103], v[198:201], v[92:95]
	v_mfma_f32_16x16x32_bf16 v[88:91], v[124:127], v[198:201], v[88:91]
	v_mfma_f32_16x16x32_bf16 v[76:79], v[100:103], v[218:221], v[76:79]
	v_mfma_f32_16x16x32_bf16 v[72:75], v[124:127], v[218:221], v[72:75]
	s_setprio 0
	s_setprio 1
	v_mfma_f32_16x16x32_bf16 v[132:135], v[144:147], v[178:181], v[132:135]
	v_mfma_f32_16x16x32_bf16 v[128:131], v[152:155], v[178:181], v[128:131]
	v_mfma_f32_16x16x32_bf16 v[108:111], v[144:147], v[186:189], v[108:111]
	v_mfma_f32_16x16x32_bf16 v[104:107], v[152:155], v[186:189], v[104:107]
	v_mfma_f32_16x16x32_bf16 v[84:87], v[144:147], v[194:197], v[84:87]
	v_mfma_f32_16x16x32_bf16 v[80:83], v[152:155], v[194:197], v[80:83]
	v_mfma_f32_16x16x32_bf16 v[68:71], v[144:147], v[202:205], v[68:71]
	v_mfma_f32_16x16x32_bf16 v[64:67], v[152:155], v[202:205], v[64:67]
	v_mfma_f32_16x16x32_bf16 v[132:135], v[148:151], v[182:185], v[132:135]
	v_mfma_f32_16x16x32_bf16 v[128:131], v[156:159], v[182:185], v[128:131]
	v_mfma_f32_16x16x32_bf16 v[108:111], v[148:151], v[190:193], v[108:111]
	v_mfma_f32_16x16x32_bf16 v[104:107], v[156:159], v[190:193], v[104:107]
	s_waitcnt vmcnt(8)
	s_setprio 2
	s_barrier
	v_mfma_f32_16x16x32_bf16 v[84:87], v[148:151], v[198:201], v[84:87]
	v_mfma_f32_16x16x32_bf16 v[80:83], v[156:159], v[198:201], v[80:83]
	v_mfma_f32_16x16x32_bf16 v[68:71], v[148:151], v[218:221], v[68:71]
	v_mfma_f32_16x16x32_bf16 v[64:67], v[156:159], v[218:221], v[64:67]
	s_setprio 2
	s_add_i32 s50, s79, s61
	v_lshl_add_u64 v[206:207], v[206:207], 0, s[36:37]
	s_mov_b32 m0, s50
	ds_read_b128 v[178:181], v211 offset:49152
	ds_read_b128 v[182:185], v211 offset:50176
	ds_read_b128 v[186:189], v211 offset:51200
	ds_read_b128 v[190:193], v211 offset:52224
	ds_read_b128 v[194:197], v211 offset:53248
	ds_read_b128 v[198:201], v211 offset:54272
	ds_read_b128 v[202:205], v211 offset:55296
	ds_read_b128 v[218:221], v211 offset:56320
	global_load_lds_dwordx4 v[206:207], off
	s_add_i32 m0, s50, 0x2000
	s_add_u32 s8, s8, 0x40080
	v_lshl_add_u64 v[206:207], v[222:223], 0, s[36:37]
	s_addc_u32 s9, s9, 0
	s_add_i32 s50, s80, s61
	global_load_lds_dwordx4 v[206:207], off
	s_mov_b32 m0, s50
	v_lshl_add_u64 v[206:207], s[8:9], 0, v[162:163]
	global_load_lds_dwordx4 v[206:207], off
	s_add_i32 m0, s50, 0x2000
	v_lshl_add_u64 v[206:207], s[8:9], 0, v[166:167]
	global_load_lds_dwordx4 v[206:207], off
	s_mov_b32 m0, s68
	v_lshl_add_u64 v[206:207], v[224:225], 0, s[36:37]
	global_load_lds_dwordx4 v[206:207], off
	s_mov_b32 m0, s69
	v_lshl_add_u64 v[206:207], v[226:227], 0, s[36:37]
	global_load_lds_dwordx4 v[206:207], off
	s_cmp_eq_u32 s100, 0
	s_waitcnt lgkmcnt(0)
	s_cbranch_scc1 .Ldw_4
	s_waitcnt vmcnt(8)
.Ldw_4:
	s_barrier
	s_setprio 1
	v_mfma_f32_16x16x32_bf16 v[60:63], v[96:99], v[178:181], v[60:63]
	v_mfma_f32_16x16x32_bf16 v[56:59], v[120:123], v[178:181], v[56:59]
	v_mfma_f32_16x16x32_bf16 v[44:47], v[96:99], v[186:189], v[44:47]
	v_mfma_f32_16x16x32_bf16 v[40:43], v[120:123], v[186:189], v[40:43]
	v_mfma_f32_16x16x32_bf16 v[28:31], v[96:99], v[194:197], v[28:31]
	v_mfma_f32_16x16x32_bf16 v[24:27], v[120:123], v[194:197], v[24:27]
	v_mfma_f32_16x16x32_bf16 v[12:15], v[96:99], v[202:205], v[12:15]
	v_mfma_f32_16x16x32_bf16 v[8:11], v[120:123], v[202:205], v[8:11]
	v_mfma_f32_16x16x32_bf16 v[60:63], v[100:103], v[182:185], v[60:63]
	v_mfma_f32_16x16x32_bf16 v[56:59], v[124:127], v[182:185], v[56:59]
	v_mfma_f32_16x16x32_bf16 v[44:47], v[100:103], v[190:193], v[44:47]
	v_mfma_f32_16x16x32_bf16 v[40:43], v[124:127], v[190:193], v[40:43]
	v_mfma_f32_16x16x32_bf16 v[28:31], v[100:103], v[198:201], v[28:31]
	v_mfma_f32_16x16x32_bf16 v[24:27], v[124:127], v[198:201], v[24:27]
	v_mfma_f32_16x16x32_bf16 v[12:15], v[100:103], v[218:221], v[12:15]
	v_mfma_f32_16x16x32_bf16 v[8:11], v[124:127], v[218:221], v[8:11]
	s_setprio 0
	s_setprio 1
	v_mfma_f32_16x16x32_bf16 v[52:55], v[144:147], v[178:181], v[52:55]
	v_mfma_f32_16x16x32_bf16 v[48:51], v[152:155], v[178:181], v[48:51]
	v_mfma_f32_16x16x32_bf16 v[36:39], v[144:147], v[186:189], v[36:39]
	v_mfma_f32_16x16x32_bf16 v[32:35], v[152:155], v[186:189], v[32:35]
	v_mfma_f32_16x16x32_bf16 v[20:23], v[144:147], v[194:197], v[20:23]
	v_mfma_f32_16x16x32_bf16 v[16:19], v[152:155], v[194:197], v[16:19]
	v_mfma_f32_16x16x32_bf16 v[4:7], v[144:147], v[202:205], v[4:7]
	v_mfma_f32_16x16x32_bf16 v[0:3], v[152:155], v[202:205], v[0:3]
	v_mfma_f32_16x16x32_bf16 v[52:55], v[148:151], v[182:185], v[52:55]
	v_mfma_f32_16x16x32_bf16 v[48:51], v[156:159], v[182:185], v[48:51]
	v_mfma_f32_16x16x32_bf16 v[36:39], v[148:151], v[190:193], v[36:39]
	v_mfma_f32_16x16x32_bf16 v[32:35], v[156:159], v[190:193], v[32:35]
	s_waitcnt vmcnt(8)
	s_setprio 2
	s_barrier
	v_mfma_f32_16x16x32_bf16 v[20:23], v[148:151], v[198:201], v[20:23]
	v_mfma_f32_16x16x32_bf16 v[16:19], v[156:159], v[198:201], v[16:19]
	v_mfma_f32_16x16x32_bf16 v[4:7], v[148:151], v[218:221], v[4:7]
	v_mfma_f32_16x16x32_bf16 v[0:3], v[156:159], v[218:221], v[0:3]
	s_setprio 0
	s_add_i32 s78, s78, 2
	s_add_u32 s6, s6, 0x100
	s_addc_u32 s7, s7, 0
	s_add_u32 s56, s56, 0x100
	s_addc_u32 s57, s57, 0
	s_cmp_gt_u32 s78, 13
.LBB0_323:
	ds_read_b128 v[96:99], v209
	ds_read_b128 v[100:103], v209 offset:1024
	ds_read_b128 v[120:123], v209 offset:2048
	ds_read_b128 v[124:127], v209 offset:3072
	ds_read_b128 v[144:147], v210
	ds_read_b128 v[148:151], v210 offset:1024
	ds_read_b128 v[152:155], v210 offset:2048
	ds_read_b128 v[156:159], v210 offset:3072
	s_add_u32 s8, s6, 0xfffc0080
	s_addc_u32 s9, s7, -1
	s_cmp_eq_u32 s78, 12
	s_cselect_b32 s51, s18, s9
	s_cselect_b32 s50, s43, s8
	s_cselect_b32 s9, s45, s57
	s_cselect_b32 s8, s55, s56
	v_lshl_add_u64 v[206:207], s[6:7], 0, v[170:171]
	s_add_i32 m0, s17, 0xc000
	ds_read_b128 v[178:181], v211
	ds_read_b128 v[182:185], v211 offset:1024
	ds_read_b128 v[186:189], v211 offset:2048
	ds_read_b128 v[190:193], v211 offset:3072
	ds_read_b128 v[194:197], v211 offset:4096
	ds_read_b128 v[198:201], v211 offset:5120
	ds_read_b128 v[202:205], v211 offset:6144
	ds_read_b128 v[218:221], v211 offset:7168
	global_load_lds_dwordx4 v[206:207], off
	s_add_i32 m0, s17, 0xe000
	v_lshl_add_u64 v[206:207], s[6:7], 0, v[172:173]
	global_load_lds_dwordx4 v[206:207], off
	s_cmp_eq_u32 s100, 0
	s_waitcnt lgkmcnt(0)
	s_cbranch_scc1 .Ldw_5
	s_waitcnt vmcnt(8)
.Ldw_5:
	s_barrier
	s_setprio 1
	v_mfma_f32_16x16x32_bf16 v[140:143], v[96:99], v[178:181], v[140:143]
	v_mfma_f32_16x16x32_bf16 v[136:139], v[120:123], v[178:181], v[136:139]
	v_mfma_f32_16x16x32_bf16 v[116:119], v[96:99], v[186:189], v[116:119]
	v_mfma_f32_16x16x32_bf16 v[112:115], v[120:123], v[186:189], v[112:115]
	v_mfma_f32_16x16x32_bf16 v[92:95], v[96:99], v[194:197], v[92:95]
	v_mfma_f32_16x16x32_bf16 v[88:91], v[120:123], v[194:197], v[88:91]
	v_mfma_f32_16x16x32_bf16 v[76:79], v[96:99], v[202:205], v[76:79]
	v_mfma_f32_16x16x32_bf16 v[72:75], v[120:123], v[202:205], v[72:75]
	v_mfma_f32_16x16x32_bf16 v[140:143], v[100:103], v[182:185], v[140:143]
	v_mfma_f32_16x16x32_bf16 v[136:139], v[124:127], v[182:185], v[136:139]
	v_mfma_f32_16x16x32_bf16 v[116:119], v[100:103], v[190:193], v[116:119]
	v_mfma_f32_16x16x32_bf16 v[112:115], v[124:127], v[190:193], v[112:115]
	v_mfma_f32_16x16x32_bf16 v[92:95], v[100:103], v[198:201], v[92:95]
	v_mfma_f32_16x16x32_bf16 v[88:91], v[124:127], v[198:201], v[88:91]
	v_mfma_f32_16x16x32_bf16 v[76:79], v[100:103], v[218:221], v[76:79]
	v_mfma_f32_16x16x32_bf16 v[72:75], v[124:127], v[218:221], v[72:75]
	s_setprio 0
	s_setprio 1
	v_mfma_f32_16x16x32_bf16 v[132:135], v[144:147], v[178:181], v[132:135]
	v_mfma_f32_16x16x32_bf16 v[128:131], v[152:155], v[178:181], v[128:131]
	v_mfma_f32_16x16x32_bf16 v[108:111], v[144:147], v[186:189], v[108:111]
	v_mfma_f32_16x16x32_bf16 v[104:107], v[152:155], v[186:189], v[104:107]
	v_mfma_f32_16x16x32_bf16 v[84:87], v[144:147], v[194:197], v[84:87]
	v_mfma_f32_16x16x32_bf16 v[80:83], v[152:155], v[194:197], v[80:83]
	v_mfma_f32_16x16x32_bf16 v[68:71], v[144:147], v[202:205], v[68:71]
	v_mfma_f32_16x16x32_bf16 v[64:67], v[152:155], v[202:205], v[64:67]
	v_mfma_f32_16x16x32_bf16 v[132:135], v[148:151], v[182:185], v[132:135]
	v_mfma_f32_16x16x32_bf16 v[128:131], v[156:159], v[182:185], v[128:131]
	v_mfma_f32_16x16x32_bf16 v[108:111], v[148:151], v[190:193], v[108:111]
	v_mfma_f32_16x16x32_bf16 v[104:107], v[156:159], v[190:193], v[104:107]
	s_waitcnt vmcnt(8)
	s_setprio 2
	s_barrier
	v_mfma_f32_16x16x32_bf16 v[84:87], v[148:151], v[198:201], v[84:87]
	v_mfma_f32_16x16x32_bf16 v[80:83], v[156:159], v[198:201], v[80:83]
	v_mfma_f32_16x16x32_bf16 v[68:71], v[148:151], v[218:221], v[68:71]
	v_mfma_f32_16x16x32_bf16 v[64:67], v[156:159], v[218:221], v[64:67]
	s_setprio 2
	s_add_i32 s79, s73, s61
	v_lshl_add_u64 v[206:207], s[8:9], 0, v[162:163]
	s_mov_b32 m0, s79
	ds_read_b128 v[178:181], v211 offset:16384
	ds_read_b128 v[182:185], v211 offset:17408
	ds_read_b128 v[186:189], v211 offset:18432
	ds_read_b128 v[190:193], v211 offset:19456
	ds_read_b128 v[194:197], v211 offset:20480
	ds_read_b128 v[198:201], v211 offset:21504
	ds_read_b128 v[202:205], v211 offset:22528
	ds_read_b128 v[218:221], v211 offset:23552
	global_load_lds_dwordx4 v[206:207], off
	s_add_i32 m0, s79, 0x2000
	s_add_u32 s80, s8, 0x40000
	v_lshl_add_u64 v[222:223], s[8:9], 0, v[166:167]
	s_addc_u32 s81, s9, 0
	s_add_i32 s79, s74, s61
	global_load_lds_dwordx4 v[222:223], off
	v_lshl_add_u64 v[224:225], s[80:81], 0, v[162:163]
	s_mov_b32 m0, s79
	v_lshl_add_u64 v[226:227], s[50:51], 0, v[164:165]
	global_load_lds_dwordx4 v[224:225], off
	s_add_i32 m0, s79, 0x2000
	v_lshl_add_u64 v[224:225], s[80:81], 0, v[166:167]
	global_load_lds_dwordx4 v[224:225], off
	s_mov_b32 m0, s17
	v_lshl_add_u64 v[224:225], s[50:51], 0, v[160:161]
	global_load_lds_dwordx4 v[224:225], off
	s_mov_b32 m0, s62
	s_nop 0
	global_load_lds_dwordx4 v[226:227], off
	s_cmp_eq_u32 s100, 0
	s_waitcnt lgkmcnt(0)
	s_cbranch_scc1 .Ldw_6
	s_waitcnt vmcnt(8)
.Ldw_6:
	s_barrier
	s_setprio 1
	v_mfma_f32_16x16x32_bf16 v[60:63], v[96:99], v[178:181], v[60:63]
	v_mfma_f32_16x16x32_bf16 v[56:59], v[120:123], v[178:181], v[56:59]
	v_mfma_f32_16x16x32_bf16 v[44:47], v[96:99], v[186:189], v[44:47]
	v_mfma_f32_16x16x32_bf16 v[40:43], v[120:123], v[186:189], v[40:43]
	v_mfma_f32_16x16x32_bf16 v[28:31], v[96:99], v[194:197], v[28:31]
	v_mfma_f32_16x16x32_bf16 v[24:27], v[120:123], v[194:197], v[24:27]
	v_mfma_f32_16x16x32_bf16 v[12:15], v[96:99], v[202:205], v[12:15]
	v_mfma_f32_16x16x32_bf16 v[8:11], v[120:123], v[202:205], v[8:11]
	v_mfma_f32_16x16x32_bf16 v[60:63], v[100:103], v[182:185], v[60:63]
	v_mfma_f32_16x16x32_bf16 v[56:59], v[124:127], v[182:185], v[56:59]
	v_mfma_f32_16x16x32_bf16 v[44:47], v[100:103], v[190:193], v[44:47]
	v_mfma_f32_16x16x32_bf16 v[40:43], v[124:127], v[190:193], v[40:43]
	v_mfma_f32_16x16x32_bf16 v[28:31], v[100:103], v[198:201], v[28:31]
	v_mfma_f32_16x16x32_bf16 v[24:27], v[124:127], v[198:201], v[24:27]
	v_mfma_f32_16x16x32_bf16 v[12:15], v[100:103], v[218:221], v[12:15]
	v_mfma_f32_16x16x32_bf16 v[8:11], v[124:127], v[218:221], v[8:11]
	s_setprio 0
	s_setprio 1
	v_mfma_f32_16x16x32_bf16 v[52:55], v[144:147], v[178:181], v[52:55]
	v_mfma_f32_16x16x32_bf16 v[48:51], v[152:155], v[178:181], v[48:51]
	v_mfma_f32_16x16x32_bf16 v[36:39], v[144:147], v[186:189], v[36:39]
	v_mfma_f32_16x16x32_bf16 v[32:35], v[152:155], v[186:189], v[32:35]
	v_mfma_f32_16x16x32_bf16 v[20:23], v[144:147], v[194:197], v[20:23]
	v_mfma_f32_16x16x32_bf16 v[16:19], v[152:155], v[194:197], v[16:19]
	v_mfma_f32_16x16x32_bf16 v[4:7], v[144:147], v[202:205], v[4:7]
	v_mfma_f32_16x16x32_bf16 v[0:3], v[152:155], v[202:205], v[0:3]
	v_mfma_f32_16x16x32_bf16 v[52:55], v[148:151], v[182:185], v[52:55]
	v_mfma_f32_16x16x32_bf16 v[48:51], v[156:159], v[182:185], v[48:51]
	v_mfma_f32_16x16x32_bf16 v[36:39], v[148:151], v[190:193], v[36:39]
	v_mfma_f32_16x16x32_bf16 v[32:35], v[156:159], v[190:193], v[32:35]
	s_waitcnt vmcnt(8)
	s_setprio 2
	s_barrier
	v_mfma_f32_16x16x32_bf16 v[20:23], v[148:151], v[198:201], v[20:23]
	v_mfma_f32_16x16x32_bf16 v[16:19], v[156:159], v[198:201], v[16:19]
	v_mfma_f32_16x16x32_bf16 v[4:7], v[148:151], v[218:221], v[4:7]
	v_mfma_f32_16x16x32_bf16 v[0:3], v[156:159], v[218:221], v[0:3]
	s_setprio 0
	s_add_i32 s79, 0, 0x18000
	s_add_i32 s80, 0, 0x1c000
	v_add_u32_e32 v124, s79, v208
	v_add_u32_e32 v156, s80, v208
	ds_read_b128 v[96:99], v124
	ds_read_b128 v[100:103], v124 offset:1024
	ds_read_b128 v[120:123], v124 offset:2048
	ds_read_b128 v[124:127], v124 offset:3072
	ds_read_b128 v[144:147], v156
	ds_read_b128 v[148:151], v156 offset:1024
	ds_read_b128 v[152:155], v156 offset:2048
	ds_read_b128 v[156:159], v156 offset:3072
	s_add_u32 s50, s50, 0x40000
	s_addc_u32 s51, s51, 0
	s_mov_b32 m0, s63
	v_lshl_add_u64 v[228:229], s[50:51], 0, v[160:161]
	ds_read_b128 v[178:181], v211 offset:32768
	ds_read_b128 v[182:185], v211 offset:33792
	ds_read_b128 v[186:189], v211 offset:34816
	ds_read_b128 v[190:193], v211 offset:35840
	ds_read_b128 v[194:197], v211 offset:36864
	ds_read_b128 v[198:201], v211 offset:37888
	ds_read_b128 v[202:205], v211 offset:38912
	ds_read_b128 v[218:221], v211 offset:39936
	global_load_lds_dwordx4 v[228:229], off
	s_mov_b32 m0, s64
	v_lshl_add_u64 v[228:229], s[50:51], 0, v[164:165]
	global_load_lds_dwordx4 v[228:229], off
	s_cmp_eq_u32 s100, 0
	s_waitcnt lgkmcnt(0)
	s_cbranch_scc1 .Ldw_7
	s_waitcnt vmcnt(8)

.Ldw_8:
	s_barrier
	s_setprio 1
	v_mfma_f32_16x16x32_bf16 v[60:63], v[96:99], v[178:181], v[60:63]
	v_mfma_f32_16x16x32_bf16 v[56:59], v[120:123], v[178:181], v[56:59]
	v_mfma_f32_16x16x32_bf16 v[44:47], v[96:99], v[186:189], v[44:47]
	v_mfma_f32_16x16x32_bf16 v[40:43], v[120:123], v[186:189], v[40:43]
	v_mfma_f32_16x16x32_bf16 v[28:31], v[96:99], v[194:197], v[28:31]
	v_mfma_f32_16x16x32_bf16 v[24:27], v[120:123], v[194:197], v[24:27]
	v_mfma_f32_16x16x32_bf16 v[12:15], v[96:99], v[202:205], v[12:15]
	v_mfma_f32_16x16x32_bf16 v[8:11], v[120:123], v[202:205], v[8:11]
	v_mfma_f32_16x16x32_bf16 v[60:63], v[100:103], v[182:185], v[60:63]
	v_mfma_f32_16x16x32_bf16 v[56:59], v[124:127], v[182:185], v[56:59]
	v_mfma_f32_16x16x32_bf16 v[44:47], v[100:103], v[190:193], v[44:47]
	v_mfma_f32_16x16x32_bf16 v[40:43], v[124:127], v[190:193], v[40:43]
	v_mfma_f32_16x16x32_bf16 v[28:31], v[100:103], v[198:201], v[28:31]
	v_mfma_f32_16x16x32_bf16 v[24:27], v[124:127], v[198:201], v[24:27]
	v_mfma_f32_16x16x32_bf16 v[12:15], v[100:103], v[218:221], v[12:15]
	v_mfma_f32_16x16x32_bf16 v[8:11], v[124:127], v[218:221], v[8:11]
	s_setprio 0
	s_setprio 1
	v_mfma_f32_16x16x32_bf16 v[52:55], v[144:147], v[178:181], v[52:55]
	v_mfma_f32_16x16x32_bf16 v[48:51], v[152:155], v[178:181], v[48:51]
	v_mfma_f32_16x16x32_bf16 v[36:39], v[144:147], v[186:189], v[36:39]
	v_mfma_f32_16x16x32_bf16 v[32:35], v[152:155], v[186:189], v[32:35]
	v_mfma_f32_16x16x32_bf16 v[20:23], v[144:147], v[194:197], v[20:23]
	v_mfma_f32_16x16x32_bf16 v[16:19], v[152:155], v[194:197], v[16:19]
	v_mfma_f32_16x16x32_bf16 v[4:7], v[144:147], v[202:205], v[4:7]
	v_mfma_f32_16x16x32_bf16 v[0:3], v[152:155], v[202:205], v[0:3]
	v_mfma_f32_16x16x32_bf16 v[52:55], v[148:151], v[182:185], v[52:55]
	v_mfma_f32_16x16x32_bf16 v[48:51], v[156:159], v[182:185], v[48:51]
	v_mfma_f32_16x16x32_bf16 v[36:39], v[148:151], v[190:193], v[36:39]
	v_mfma_f32_16x16x32_bf16 v[32:35], v[156:159], v[190:193], v[32:35]
	s_waitcnt vmcnt(8)
	s_setprio 2
	s_barrier
	v_mfma_f32_16x16x32_bf16 v[20:23], v[148:151], v[198:201], v[20:23]
	v_mfma_f32_16x16x32_bf16 v[16:19], v[156:159], v[198:201], v[16:19]
	v_mfma_f32_16x16x32_bf16 v[4:7], v[148:151], v[218:221], v[4:7]
	v_mfma_f32_16x16x32_bf16 v[0:3], v[156:159], v[218:221], v[0:3]
	s_setprio 0
	s_add_i32 s78, s78, 2
	s_add_u32 s6, s6, 0x100
	s_addc_u32 s7, s7, 0
	s_add_u32 s56, s56, 0x100
	s_addc_u32 s57, s57, 0
	s_cmp_gt_u32 s78, 13
	s_cbranch_scc0 .LBB0_323

.LBB0_697:
	s_and_b32 s29, s69, 0x1000
	s_add_i32 s70, s66, s29
	s_ashr_i32 s29, s28, 31
	ds_read_b128 v[0:3], v195 offset:3072
	ds_read_b128 v[4:7], v195 offset:2048
	ds_read_b128 v[8:11], v195 offset:1024
	ds_read_b128 v[12:15], v195
	ds_read_b128 v[16:19], v203 offset:3072
	ds_read_b128 v[20:23], v203 offset:2048
	ds_read_b128 v[24:27], v203 offset:1024
	ds_read_b128 v[28:31], v203
	s_lshl_b64 s[36:37], s[28:29], 20
	s_add_u32 s36, s50, s36
	s_addc_u32 s37, s51, s37
	s_and_b64 s[38:39], s[4:5], exec
	s_cselect_b32 s29, s37, s45
	s_cselect_b32 s71, s36, s44
	s_ashr_i32 s31, s30, 31
	s_lshl_b64 s[38:39], s[30:31], 20
	s_add_u32 s38, s54, s38
	s_addc_u32 s39, s55, s39
	s_and_b64 s[48:49], s[4:5], exec
	s_cselect_b32 s31, s39, s47
	s_cselect_b32 s72, s38, s46
	s_add_u32 s48, s44, 0x80080
	s_addc_u32 s49, s45, 0
	s_add_i32 s73, s56, 0xc000
	v_lshl_add_u64 v[64:65], s[48:49], 0, v[176:177]
	s_mov_b32 m0, s73
	s_add_i32 s74, s56, 0xe000
	ds_read_b128 v[32:35], v211
	ds_read_b128 v[36:39], v211 offset:1024
	ds_read_b128 v[40:43], v211 offset:2048
	ds_read_b128 v[44:47], v211 offset:3072
	ds_read_b128 v[48:51], v211 offset:4096
	ds_read_b128 v[52:55], v211 offset:5120
	ds_read_b128 v[56:59], v211 offset:6144
	ds_read_b128 v[60:63], v211 offset:7168
	global_load_lds_dwordx4 v[64:65], off
	s_mov_b32 m0, s74
	v_lshl_add_u64 v[64:65], s[48:49], 0, v[178:179]
	global_load_lds_dwordx4 v[64:65], off
	s_cmp_eq_u32 s100, 0
	s_waitcnt lgkmcnt(0)
	s_cbranch_scc1 .Ldw_9
	s_waitcnt vmcnt(8)
.Ldw_9:
	s_barrier
	s_setprio 1
	v_mfma_f32_16x16x32_bf16 v[88:91], v[28:31], v[56:59], 0
	v_mfma_f32_16x16x32_bf16 v[64:67], v[28:31], v[32:35], 0
	v_mfma_f32_16x16x32_bf16 v[68:71], v[20:23], v[32:35], 0
	v_mfma_f32_16x16x32_bf16 v[72:75], v[28:31], v[40:43], 0
	v_mfma_f32_16x16x32_bf16 v[76:79], v[20:23], v[40:43], 0
	v_mfma_f32_16x16x32_bf16 v[80:83], v[28:31], v[48:51], 0
	v_mfma_f32_16x16x32_bf16 v[84:87], v[20:23], v[48:51], 0
	v_mfma_f32_16x16x32_bf16 v[96:99], v[24:27], v[60:63], v[88:91]
	v_mfma_f32_16x16x32_bf16 v[88:91], v[20:23], v[56:59], 0
	v_mfma_f32_16x16x32_bf16 v[64:67], v[24:27], v[36:39], v[64:67]
	v_mfma_f32_16x16x32_bf16 v[68:71], v[16:19], v[36:39], v[68:71]
	v_mfma_f32_16x16x32_bf16 v[72:75], v[24:27], v[44:47], v[72:75]
	v_mfma_f32_16x16x32_bf16 v[76:79], v[16:19], v[44:47], v[76:79]
	v_mfma_f32_16x16x32_bf16 v[80:83], v[24:27], v[52:55], v[80:83]
	v_mfma_f32_16x16x32_bf16 v[84:87], v[16:19], v[52:55], v[84:87]
	v_mfma_f32_16x16x32_bf16 v[100:103], v[16:19], v[60:63], v[88:91]
	s_setprio 0
	s_setprio 1
	v_mfma_f32_16x16x32_bf16 v[88:91], v[12:15], v[32:35], 0
	v_mfma_f32_16x16x32_bf16 v[32:35], v[4:7], v[32:35], 0
	v_mfma_f32_16x16x32_bf16 v[112:115], v[8:11], v[36:39], v[88:91]
	v_mfma_f32_16x16x32_bf16 v[32:35], v[0:3], v[36:39], v[32:35]
	v_mfma_f32_16x16x32_bf16 v[36:39], v[12:15], v[40:43], 0
	v_mfma_f32_16x16x32_bf16 v[40:43], v[4:7], v[40:43], 0
	v_mfma_f32_16x16x32_bf16 v[36:39], v[8:11], v[44:47], v[36:39]
	v_mfma_f32_16x16x32_bf16 v[40:43], v[0:3], v[44:47], v[40:43]
	v_mfma_f32_16x16x32_bf16 v[44:47], v[12:15], v[48:51], 0
	v_mfma_f32_16x16x32_bf16 v[48:51], v[4:7], v[48:51], 0
	v_mfma_f32_16x16x32_bf16 v[44:47], v[8:11], v[52:55], v[44:47]
	v_mfma_f32_16x16x32_bf16 v[48:51], v[0:3], v[52:55], v[48:51]
	s_waitcnt vmcnt(8)
	s_setprio 2
	s_barrier
	v_mfma_f32_16x16x32_bf16 v[52:55], v[12:15], v[56:59], 0
	v_mfma_f32_16x16x32_bf16 v[56:59], v[4:7], v[56:59], 0
	v_mfma_f32_16x16x32_bf16 v[52:55], v[8:11], v[60:63], v[52:55]
	v_mfma_f32_16x16x32_bf16 v[56:59], v[0:3], v[60:63], v[56:59]
	s_setprio 2
	s_add_i32 s75, s68, s43
	v_lshl_add_u64 v[174:175], s[46:47], 0, v[176:177]
	s_add_i32 s76, s75, 0x2000
	v_lshl_add_u64 v[128:129], v[174:175], 0, s[24:25]
	s_mov_b32 m0, s75
	v_lshl_add_u64 v[200:201], s[46:47], 0, v[178:179]
	s_add_u32 s48, s46, 0x80100
	ds_read_b128 v[60:63], v211 offset:16384
	ds_read_b128 v[88:91], v211 offset:17408
	ds_read_b128 v[92:95], v211 offset:18432
	ds_read_b128 v[104:107], v211 offset:19456
	ds_read_b128 v[108:111], v211 offset:20480
	ds_read_b128 v[116:119], v211 offset:21504
	ds_read_b128 v[120:123], v211 offset:22528
	ds_read_b128 v[124:127], v211 offset:23552
	global_load_lds_dwordx4 v[128:129], off
	v_lshl_add_u64 v[128:129], v[200:201], 0, s[24:25]
	s_mov_b32 m0, s76
	s_addc_u32 s49, s47, 0
	s_add_i32 s77, s67, s43
	global_load_lds_dwordx4 v[128:129], off
	v_lshl_add_u64 v[128:129], s[48:49], 0, v[176:177]
	s_mov_b32 m0, s77
	s_add_i32 s78, s77, 0x2000
	global_load_lds_dwordx4 v[128:129], off
	v_lshl_add_u64 v[128:129], s[48:49], 0, v[178:179]
	s_mov_b32 m0, s78
	v_lshl_add_u64 v[208:209], s[44:45], 0, v[176:177]
	global_load_lds_dwordx4 v[128:129], off
	v_lshl_add_u64 v[128:129], v[208:209], 0, s[24:25]
	s_mov_b32 m0, s56
	v_lshl_add_u64 v[252:253], s[44:45], 0, v[178:179]
	global_load_lds_dwordx4 v[128:129], off
	s_mov_b32 m0, s57
	v_lshl_add_u64 v[128:129], v[252:253], 0, s[24:25]
	global_load_lds_dwordx4 v[128:129], off
	s_cmp_eq_u32 s100, 0
	s_waitcnt lgkmcnt(0)
	s_cbranch_scc1 .Ldw_10
	s_waitcnt vmcnt(8)
.Ldw_10:
	s_barrier
	s_setprio 1
	v_mfma_f32_16x16x32_bf16 v[134:137], v[20:23], v[60:63], 0
	v_mfma_f32_16x16x32_bf16 v[142:145], v[20:23], v[92:95], 0
	v_mfma_f32_16x16x32_bf16 v[150:153], v[20:23], v[108:111], 0
	v_mfma_f32_16x16x32_bf16 v[20:23], v[20:23], v[120:123], 0
	v_mfma_f32_16x16x32_bf16 v[128:131], v[28:31], v[60:63], 0
	v_mfma_f32_16x16x32_bf16 v[134:137], v[16:19], v[88:91], v[134:137]
	v_mfma_f32_16x16x32_bf16 v[138:141], v[28:31], v[92:95], 0
	v_mfma_f32_16x16x32_bf16 v[142:145], v[16:19], v[104:107], v[142:145]
	v_mfma_f32_16x16x32_bf16 v[146:149], v[28:31], v[108:111], 0
	v_mfma_f32_16x16x32_bf16 v[150:153], v[16:19], v[116:119], v[150:153]
	v_mfma_f32_16x16x32_bf16 v[28:31], v[28:31], v[120:123], 0
	v_mfma_f32_16x16x32_bf16 v[16:19], v[16:19], v[124:127], v[20:23]
	v_mfma_f32_16x16x32_bf16 v[130:133], v[24:27], v[88:91], v[128:131]
	v_mfma_f32_16x16x32_bf16 v[138:141], v[24:27], v[104:107], v[138:141]
	v_mfma_f32_16x16x32_bf16 v[146:149], v[24:27], v[116:119], v[146:149]
	v_mfma_f32_16x16x32_bf16 v[154:157], v[24:27], v[124:127], v[28:31]
	s_setprio 0
	s_setprio 1
	v_mfma_f32_16x16x32_bf16 v[24:27], v[4:7], v[60:63], 0
	v_mfma_f32_16x16x32_bf16 v[158:161], v[0:3], v[88:91], v[24:27]
	v_mfma_f32_16x16x32_bf16 v[24:27], v[12:15], v[92:95], 0
	v_mfma_f32_16x16x32_bf16 v[162:165], v[8:11], v[104:107], v[24:27]
	v_mfma_f32_16x16x32_bf16 v[24:27], v[4:7], v[92:95], 0
	v_mfma_f32_16x16x32_bf16 v[166:169], v[0:3], v[104:107], v[24:27]
	v_mfma_f32_16x16x32_bf16 v[24:27], v[12:15], v[108:111], 0
	v_mfma_f32_16x16x32_bf16 v[20:23], v[12:15], v[60:63], 0
	v_mfma_f32_16x16x32_bf16 v[170:173], v[8:11], v[116:119], v[24:27]
	v_mfma_f32_16x16x32_bf16 v[24:27], v[4:7], v[108:111], 0
	v_mfma_f32_16x16x32_bf16 v[4:7], v[4:7], v[120:123], 0
	v_mfma_f32_16x16x32_bf16 v[20:23], v[8:11], v[88:91], v[20:23]
	s_waitcnt vmcnt(8)
	s_setprio 2
	s_barrier
	v_mfma_f32_16x16x32_bf16 v[190:193], v[0:3], v[116:119], v[24:27]
	v_mfma_f32_16x16x32_bf16 v[12:15], v[12:15], v[120:123], 0
	v_mfma_f32_16x16x32_bf16 v[0:3], v[0:3], v[124:127], v[4:7]
	v_mfma_f32_16x16x32_bf16 v[196:199], v[8:11], v[124:127], v[12:15]
	s_setprio 0
	s_add_i32 s79, 0, 0x18000
	s_add_i32 s81, 0, 0x1c000
	v_add_u32_e32 v128, s79, v189
	v_add_u32_e32 v129, s81, v189
	ds_read_b128 v[4:7], v128
	ds_read_b128 v[8:11], v128 offset:1024
	ds_read_b128 v[204:207], v128 offset:2048
	ds_read_b128 v[212:215], v128 offset:3072
	ds_read_b128 v[216:219], v129
	ds_read_b128 v[220:223], v129 offset:1024
	ds_read_b128 v[224:227], v129 offset:2048
	ds_read_b128 v[228:231], v129 offset:3072
	s_add_u32 s48, s44, 0x80100
	s_addc_u32 s49, s45, 0
	s_mov_b32 m0, s58
	v_lshl_add_u64 v[88:89], s[48:49], 0, v[176:177]
	ds_read_b128 v[12:15], v211 offset:32768
	ds_read_b128 v[24:27], v211 offset:33792
	ds_read_b128 v[28:31], v211 offset:34816
	ds_read_b128 v[60:63], v211 offset:35840
	ds_read_b128 v[232:235], v211 offset:36864
	ds_read_b128 v[236:239], v211 offset:37888
	ds_read_b128 v[240:243], v211 offset:38912
	ds_read_b128 v[244:247], v211 offset:39936
	global_load_lds_dwordx4 v[88:89], off
	s_mov_b32 m0, s59
	v_lshl_add_u64 v[88:89], s[48:49], 0, v[178:179]
	global_load_lds_dwordx4 v[88:89], off
	s_cmp_eq_u32 s100, 0
	s_waitcnt lgkmcnt(0)
	s_cbranch_scc1 .Ldw_11
	s_waitcnt vmcnt(8)
.Ldw_11:
	s_barrier
	s_setprio 1
	v_mfma_f32_16x16x32_bf16 v[64:67], v[4:7], v[12:15], v[64:67]
	v_mfma_f32_16x16x32_bf16 v[124:127], v[8:11], v[24:27], v[64:67]
	v_mfma_f32_16x16x32_bf16 v[64:67], v[204:207], v[12:15], v[68:71]
	v_mfma_f32_16x16x32_bf16 v[120:123], v[212:215], v[24:27], v[64:67]
	v_mfma_f32_16x16x32_bf16 v[64:67], v[4:7], v[28:31], v[72:75]
	v_mfma_f32_16x16x32_bf16 v[108:111], v[8:11], v[60:63], v[64:67]
	v_mfma_f32_16x16x32_bf16 v[64:67], v[204:207], v[28:31], v[76:79]
	v_mfma_f32_16x16x32_bf16 v[104:107], v[212:215], v[60:63], v[64:67]
	v_mfma_f32_16x16x32_bf16 v[64:67], v[4:7], v[232:235], v[80:83]
	v_mfma_f32_16x16x32_bf16 v[92:95], v[8:11], v[236:239], v[64:67]
	v_mfma_f32_16x16x32_bf16 v[64:67], v[204:207], v[232:235], v[84:87]
	v_mfma_f32_16x16x32_bf16 v[88:91], v[212:215], v[236:239], v[64:67]
	v_mfma_f32_16x16x32_bf16 v[64:67], v[4:7], v[240:243], v[96:99]
	v_mfma_f32_16x16x32_bf16 v[76:79], v[8:11], v[244:247], v[64:67]
	v_mfma_f32_16x16x32_bf16 v[64:67], v[204:207], v[240:243], v[100:103]
	v_mfma_f32_16x16x32_bf16 v[72:75], v[212:215], v[244:247], v[64:67]
	s_setprio 0
	s_setprio 1
	v_mfma_f32_16x16x32_bf16 v[64:67], v[216:219], v[12:15], v[112:115]
	v_mfma_f32_16x16x32_bf16 v[12:15], v[224:227], v[12:15], v[32:35]
	v_mfma_f32_16x16x32_bf16 v[112:115], v[228:231], v[24:27], v[12:15]
	v_mfma_f32_16x16x32_bf16 v[12:15], v[216:219], v[28:31], v[36:39]
	v_mfma_f32_16x16x32_bf16 v[100:103], v[220:223], v[60:63], v[12:15]
	v_mfma_f32_16x16x32_bf16 v[12:15], v[224:227], v[28:31], v[40:43]
	v_mfma_f32_16x16x32_bf16 v[96:99], v[228:231], v[60:63], v[12:15]
	v_mfma_f32_16x16x32_bf16 v[12:15], v[216:219], v[232:235], v[44:47]
	v_mfma_f32_16x16x32_bf16 v[84:87], v[220:223], v[236:239], v[12:15]
	v_mfma_f32_16x16x32_bf16 v[12:15], v[224:227], v[232:235], v[48:51]
	v_mfma_f32_16x16x32_bf16 v[80:83], v[228:231], v[236:239], v[12:15]
	v_mfma_f32_16x16x32_bf16 v[12:15], v[216:219], v[240:243], v[52:55]
	s_waitcnt vmcnt(8)
	s_setprio 2
	s_barrier
	v_mfma_f32_16x16x32_bf16 v[68:71], v[220:223], v[244:247], v[12:15]
	v_mfma_f32_16x16x32_bf16 v[12:15], v[224:227], v[240:243], v[56:59]
	v_mfma_f32_16x16x32_bf16 v[116:119], v[220:223], v[24:27], v[64:67]
	v_mfma_f32_16x16x32_bf16 v[64:67], v[228:231], v[244:247], v[12:15]
	s_setprio 2
	s_add_i32 s79, s79, s43
	s_add_i32 s80, s79, 0x2000
	s_nop 1
	v_lshl_add_u64 v[12:13], v[174:175], 0, s[26:27]
	s_mov_b32 m0, s79
	s_add_u32 s48, s46, 0x80180
	ds_read_b128 v[32:35], v211 offset:49152
	ds_read_b128 v[36:39], v211 offset:50176
	ds_read_b128 v[232:235], v211 offset:51200
	ds_read_b128 v[236:239], v211 offset:52224
	ds_read_b128 v[240:243], v211 offset:53248
	ds_read_b128 v[244:247], v211 offset:54272
	ds_read_b128 v[248:251], v211 offset:55296
	ds_read_b128 v[184:187], v211 offset:56320
	global_load_lds_dwordx4 v[12:13], off
	v_lshl_add_u64 v[12:13], v[200:201], 0, s[26:27]
	s_mov_b32 m0, s80
	s_addc_u32 s49, s47, 0
	s_add_i32 s81, s81, s43
	global_load_lds_dwordx4 v[12:13], off
	v_lshl_add_u64 v[12:13], s[48:49], 0, v[176:177]
	s_mov_b32 m0, s81
	s_add_i32 s82, s81, 0x2000
	global_load_lds_dwordx4 v[12:13], off
	s_mov_b32 m0, s82
	v_lshl_add_u64 v[12:13], s[48:49], 0, v[178:179]
	global_load_lds_dwordx4 v[12:13], off
	s_mov_b32 m0, s61
	v_lshl_add_u64 v[12:13], v[208:209], 0, s[26:27]
	global_load_lds_dwordx4 v[12:13], off
	s_mov_b32 m0, s62
	v_lshl_add_u64 v[12:13], v[252:253], 0, s[26:27]
	global_load_lds_dwordx4 v[12:13], off
	s_cmp_eq_u32 s100, 0
	s_waitcnt lgkmcnt(0)
	s_cbranch_scc1 .Ldw_12
	s_waitcnt vmcnt(8)
.Ldw_12:
	s_barrier
	s_setprio 1
	v_mfma_f32_16x16x32_bf16 v[12:15], v[4:7], v[32:35], v[130:133]
	v_mfma_f32_16x16x32_bf16 v[60:63], v[8:11], v[36:39], v[12:15]
	v_mfma_f32_16x16x32_bf16 v[12:15], v[204:207], v[32:35], v[134:137]
	v_mfma_f32_16x16x32_bf16 v[56:59], v[212:215], v[36:39], v[12:15]
	v_mfma_f32_16x16x32_bf16 v[12:15], v[4:7], v[232:235], v[138:141]
	v_mfma_f32_16x16x32_bf16 v[44:47], v[8:11], v[236:239], v[12:15]
	v_mfma_f32_16x16x32_bf16 v[12:15], v[204:207], v[232:235], v[142:145]
	v_mfma_f32_16x16x32_bf16 v[40:43], v[212:215], v[236:239], v[12:15]
	v_mfma_f32_16x16x32_bf16 v[12:15], v[4:7], v[240:243], v[146:149]
	v_mfma_f32_16x16x32_bf16 v[28:31], v[8:11], v[244:247], v[12:15]
	v_mfma_f32_16x16x32_bf16 v[12:15], v[204:207], v[240:243], v[150:153]
	v_mfma_f32_16x16x32_bf16 v[4:7], v[4:7], v[248:251], v[154:157]
	v_mfma_f32_16x16x32_bf16 v[24:27], v[212:215], v[244:247], v[12:15]
	v_mfma_f32_16x16x32_bf16 v[12:15], v[8:11], v[184:187], v[4:7]
	v_mfma_f32_16x16x32_bf16 v[4:7], v[204:207], v[248:251], v[16:19]
	v_mfma_f32_16x16x32_bf16 v[8:11], v[212:215], v[184:187], v[4:7]
	s_setprio 0
	s_setprio 1
	v_mfma_f32_16x16x32_bf16 v[4:7], v[216:219], v[32:35], v[20:23]
	v_mfma_f32_16x16x32_bf16 v[52:55], v[220:223], v[36:39], v[4:7]
	v_mfma_f32_16x16x32_bf16 v[4:7], v[224:227], v[32:35], v[158:161]
	v_mfma_f32_16x16x32_bf16 v[48:51], v[228:231], v[36:39], v[4:7]
	v_mfma_f32_16x16x32_bf16 v[4:7], v[216:219], v[232:235], v[162:165]
	v_mfma_f32_16x16x32_bf16 v[36:39], v[220:223], v[236:239], v[4:7]
	v_mfma_f32_16x16x32_bf16 v[4:7], v[224:227], v[232:235], v[166:169]
	v_mfma_f32_16x16x32_bf16 v[32:35], v[228:231], v[236:239], v[4:7]
	v_mfma_f32_16x16x32_bf16 v[4:7], v[216:219], v[240:243], v[170:173]
	v_mfma_f32_16x16x32_bf16 v[20:23], v[220:223], v[244:247], v[4:7]
	v_mfma_f32_16x16x32_bf16 v[4:7], v[224:227], v[240:243], v[190:193]
	v_mfma_f32_16x16x32_bf16 v[16:19], v[228:231], v[244:247], v[4:7]
	s_waitcnt vmcnt(8)
	s_setprio 2
	s_barrier
	v_mfma_f32_16x16x32_bf16 v[4:7], v[216:219], v[248:251], v[196:199]
	v_mfma_f32_16x16x32_bf16 v[0:3], v[224:227], v[248:251], v[0:3]
	v_mfma_f32_16x16x32_bf16 v[4:7], v[220:223], v[184:187], v[4:7]
	v_mfma_f32_16x16x32_bf16 v[0:3], v[228:231], v[184:187], v[0:3]
	s_setprio 0
	s_add_u32 s44, s44, 0x80180
	s_addc_u32 s45, s45, 0
	s_add_u32 s83, s46, 0x200
	s_addc_u32 s84, s47, 0
	s_mov_b32 s46, 0
	s_add_i32 s85, s46, 2
	s_and_b32 s47, s85, 6
	s_cmp_lg_u32 s47, 0
	s_cbranch_scc1 .LBB0_700
	s_branch .LBB0_699

.LBB0_700:
	ds_read_b128 v[130:133], v203
	ds_read_b128 v[134:137], v203 offset:1024
	ds_read_b128 v[138:141], v203 offset:2048
	ds_read_b128 v[142:145], v203 offset:3072
	ds_read_b128 v[146:149], v195
	ds_read_b128 v[150:153], v195 offset:1024
	ds_read_b128 v[154:157], v195 offset:2048
	ds_read_b128 v[158:161], v195 offset:3072
	s_add_u32 s47, s44, 0xfff80080
	s_addc_u32 s48, s45, -1
	s_cmp_eq_u32 s46, 28
	s_cselect_b32 s49, s29, s48
	s_cselect_b32 s48, s71, s47
	s_cselect_b32 s47, s31, s84
	s_cselect_b32 s46, s72, s83
	s_mov_b32 m0, s73
	v_lshl_add_u64 v[174:175], s[44:45], 0, v[180:181]
	ds_read_b128 v[162:165], v211
	ds_read_b128 v[166:169], v211 offset:1024
	ds_read_b128 v[170:173], v211 offset:2048
	ds_read_b128 v[184:187], v211 offset:3072
	ds_read_b128 v[190:193], v211 offset:4096
	ds_read_b128 v[196:199], v211 offset:5120
	ds_read_b128 v[204:207], v211 offset:6144
	ds_read_b128 v[212:215], v211 offset:7168
	global_load_lds_dwordx4 v[174:175], off
	s_mov_b32 m0, s74
	v_lshl_add_u64 v[174:175], s[44:45], 0, v[182:183]
	global_load_lds_dwordx4 v[174:175], off
	s_cmp_eq_u32 s100, 0
	s_waitcnt lgkmcnt(0)
	s_cbranch_scc1 .Ldw_13
	s_waitcnt vmcnt(8)
.Ldw_13:
	s_barrier
	s_setprio 1
	v_mfma_f32_16x16x32_bf16 v[124:127], v[130:133], v[162:165], v[124:127]
	v_mfma_f32_16x16x32_bf16 v[120:123], v[138:141], v[162:165], v[120:123]
	v_mfma_f32_16x16x32_bf16 v[108:111], v[130:133], v[170:173], v[108:111]
	v_mfma_f32_16x16x32_bf16 v[104:107], v[138:141], v[170:173], v[104:107]
	v_mfma_f32_16x16x32_bf16 v[92:95], v[130:133], v[190:193], v[92:95]
	v_mfma_f32_16x16x32_bf16 v[88:91], v[138:141], v[190:193], v[88:91]
	v_mfma_f32_16x16x32_bf16 v[76:79], v[130:133], v[204:207], v[76:79]
	v_mfma_f32_16x16x32_bf16 v[72:75], v[138:141], v[204:207], v[72:75]
	v_mfma_f32_16x16x32_bf16 v[124:127], v[134:137], v[166:169], v[124:127]
	v_mfma_f32_16x16x32_bf16 v[120:123], v[142:145], v[166:169], v[120:123]
	v_mfma_f32_16x16x32_bf16 v[108:111], v[134:137], v[184:187], v[108:111]
	v_mfma_f32_16x16x32_bf16 v[104:107], v[142:145], v[184:187], v[104:107]
	v_mfma_f32_16x16x32_bf16 v[92:95], v[134:137], v[196:199], v[92:95]
	v_mfma_f32_16x16x32_bf16 v[88:91], v[142:145], v[196:199], v[88:91]
	v_mfma_f32_16x16x32_bf16 v[76:79], v[134:137], v[212:215], v[76:79]
	v_mfma_f32_16x16x32_bf16 v[72:75], v[142:145], v[212:215], v[72:75]
	s_setprio 0
	s_setprio 1
	v_mfma_f32_16x16x32_bf16 v[116:119], v[146:149], v[162:165], v[116:119]
	v_mfma_f32_16x16x32_bf16 v[112:115], v[154:157], v[162:165], v[112:115]
	v_mfma_f32_16x16x32_bf16 v[100:103], v[146:149], v[170:173], v[100:103]
	v_mfma_f32_16x16x32_bf16 v[96:99], v[154:157], v[170:173], v[96:99]
	v_mfma_f32_16x16x32_bf16 v[84:87], v[146:149], v[190:193], v[84:87]
	v_mfma_f32_16x16x32_bf16 v[80:83], v[154:157], v[190:193], v[80:83]
	v_mfma_f32_16x16x32_bf16 v[68:71], v[146:149], v[204:207], v[68:71]
	v_mfma_f32_16x16x32_bf16 v[64:67], v[154:157], v[204:207], v[64:67]
	v_mfma_f32_16x16x32_bf16 v[116:119], v[150:153], v[166:169], v[116:119]
	v_mfma_f32_16x16x32_bf16 v[112:115], v[158:161], v[166:169], v[112:115]
	v_mfma_f32_16x16x32_bf16 v[100:103], v[150:153], v[184:187], v[100:103]
	v_mfma_f32_16x16x32_bf16 v[96:99], v[158:161], v[184:187], v[96:99]
	s_waitcnt vmcnt(8)
	s_setprio 2
	s_barrier
	v_mfma_f32_16x16x32_bf16 v[84:87], v[150:153], v[196:199], v[84:87]
	v_mfma_f32_16x16x32_bf16 v[80:83], v[158:161], v[196:199], v[80:83]
	v_mfma_f32_16x16x32_bf16 v[68:71], v[150:153], v[212:215], v[68:71]
	v_mfma_f32_16x16x32_bf16 v[64:67], v[158:161], v[212:215], v[64:67]
	s_setprio 2
	s_mov_b32 m0, s75
	v_lshl_add_u64 v[174:175], s[46:47], 0, v[176:177]
	s_add_u32 s86, s46, 0x80000
	ds_read_b128 v[162:165], v211 offset:16384
	ds_read_b128 v[166:169], v211 offset:17408
	ds_read_b128 v[170:173], v211 offset:18432
	ds_read_b128 v[184:187], v211 offset:19456
	ds_read_b128 v[190:193], v211 offset:20480
	ds_read_b128 v[196:199], v211 offset:21504
	ds_read_b128 v[204:207], v211 offset:22528
	ds_read_b128 v[212:215], v211 offset:23552
	global_load_lds_dwordx4 v[174:175], off
	v_lshl_add_u64 v[200:201], s[46:47], 0, v[178:179]
	s_mov_b32 m0, s76
	s_addc_u32 s87, s47, 0
	global_load_lds_dwordx4 v[200:201], off
	v_lshl_add_u64 v[208:209], s[86:87], 0, v[176:177]
	s_mov_b32 m0, s77
	v_lshl_add_u64 v[216:217], s[48:49], 0, v[178:179]
	global_load_lds_dwordx4 v[208:209], off
	s_mov_b32 m0, s78
	v_lshl_add_u64 v[208:209], s[86:87], 0, v[178:179]
	global_load_lds_dwordx4 v[208:209], off
	s_mov_b32 m0, s56
	v_lshl_add_u64 v[208:209], s[48:49], 0, v[176:177]
	global_load_lds_dwordx4 v[208:209], off
	s_mov_b32 m0, s57
	s_nop 0
	global_load_lds_dwordx4 v[216:217], off
	s_cmp_eq_u32 s100, 0
	s_waitcnt lgkmcnt(0)
	s_cbranch_scc1 .Ldw_14
	s_waitcnt vmcnt(8)
.Ldw_14:
	s_barrier
	s_setprio 1
	v_mfma_f32_16x16x32_bf16 v[60:63], v[130:133], v[162:165], v[60:63]
	v_mfma_f32_16x16x32_bf16 v[56:59], v[138:141], v[162:165], v[56:59]
	v_mfma_f32_16x16x32_bf16 v[44:47], v[130:133], v[170:173], v[44:47]
	v_mfma_f32_16x16x32_bf16 v[40:43], v[138:141], v[170:173], v[40:43]
	v_mfma_f32_16x16x32_bf16 v[28:31], v[130:133], v[190:193], v[28:31]
	v_mfma_f32_16x16x32_bf16 v[24:27], v[138:141], v[190:193], v[24:27]
	v_mfma_f32_16x16x32_bf16 v[12:15], v[130:133], v[204:207], v[12:15]
	v_mfma_f32_16x16x32_bf16 v[8:11], v[138:141], v[204:207], v[8:11]
	v_mfma_f32_16x16x32_bf16 v[60:63], v[134:137], v[166:169], v[60:63]
	v_mfma_f32_16x16x32_bf16 v[56:59], v[142:145], v[166:169], v[56:59]
	v_mfma_f32_16x16x32_bf16 v[44:47], v[134:137], v[184:187], v[44:47]
	v_mfma_f32_16x16x32_bf16 v[40:43], v[142:145], v[184:187], v[40:43]
	v_mfma_f32_16x16x32_bf16 v[28:31], v[134:137], v[196:199], v[28:31]
	v_mfma_f32_16x16x32_bf16 v[24:27], v[142:145], v[196:199], v[24:27]
	v_mfma_f32_16x16x32_bf16 v[12:15], v[134:137], v[212:215], v[12:15]
	v_mfma_f32_16x16x32_bf16 v[8:11], v[142:145], v[212:215], v[8:11]
	s_setprio 0
	s_setprio 1
	v_mfma_f32_16x16x32_bf16 v[52:55], v[146:149], v[162:165], v[52:55]
	v_mfma_f32_16x16x32_bf16 v[48:51], v[154:157], v[162:165], v[48:51]
	v_mfma_f32_16x16x32_bf16 v[36:39], v[146:149], v[170:173], v[36:39]
	v_mfma_f32_16x16x32_bf16 v[32:35], v[154:157], v[170:173], v[32:35]
	v_mfma_f32_16x16x32_bf16 v[20:23], v[146:149], v[190:193], v[20:23]
	v_mfma_f32_16x16x32_bf16 v[16:19], v[154:157], v[190:193], v[16:19]
	v_mfma_f32_16x16x32_bf16 v[4:7], v[146:149], v[204:207], v[4:7]
	v_mfma_f32_16x16x32_bf16 v[0:3], v[154:157], v[204:207], v[0:3]
	v_mfma_f32_16x16x32_bf16 v[52:55], v[150:153], v[166:169], v[52:55]
	v_mfma_f32_16x16x32_bf16 v[48:51], v[158:161], v[166:169], v[48:51]
	v_mfma_f32_16x16x32_bf16 v[36:39], v[150:153], v[184:187], v[36:39]
	v_mfma_f32_16x16x32_bf16 v[32:35], v[158:161], v[184:187], v[32:35]
	s_waitcnt vmcnt(8)
	s_setprio 2
	s_barrier
	v_mfma_f32_16x16x32_bf16 v[20:23], v[150:153], v[196:199], v[20:23]
	v_mfma_f32_16x16x32_bf16 v[16:19], v[158:161], v[196:199], v[16:19]
	v_mfma_f32_16x16x32_bf16 v[4:7], v[150:153], v[212:215], v[4:7]
	v_mfma_f32_16x16x32_bf16 v[0:3], v[158:161], v[212:215], v[0:3]
	s_setprio 0
	ds_read_b128 v[130:133], v128
	ds_read_b128 v[134:137], v128 offset:1024
	ds_read_b128 v[138:141], v128 offset:2048
	ds_read_b128 v[142:145], v128 offset:3072
	ds_read_b128 v[146:149], v129
	ds_read_b128 v[150:153], v129 offset:1024
	ds_read_b128 v[154:157], v129 offset:2048
	ds_read_b128 v[158:161], v129 offset:3072
	s_add_u32 s48, s48, 0x80000
	s_addc_u32 s49, s49, 0
	s_mov_b32 m0, s58
	v_lshl_add_u64 v[218:219], s[48:49], 0, v[176:177]
	ds_read_b128 v[162:165], v211 offset:32768
	ds_read_b128 v[166:169], v211 offset:33792
	ds_read_b128 v[170:173], v211 offset:34816
	ds_read_b128 v[184:187], v211 offset:35840
	ds_read_b128 v[190:193], v211 offset:36864
	ds_read_b128 v[196:199], v211 offset:37888
	ds_read_b128 v[204:207], v211 offset:38912
	ds_read_b128 v[212:215], v211 offset:39936
	global_load_lds_dwordx4 v[218:219], off
	s_mov_b32 m0, s59
	v_lshl_add_u64 v[218:219], s[48:49], 0, v[178:179]
	global_load_lds_dwordx4 v[218:219], off
	s_cmp_eq_u32 s100, 0
	s_waitcnt lgkmcnt(0)
	s_cbranch_scc1 .Ldw_15
	s_waitcnt vmcnt(8)
.Ldw_15:
	s_barrier
	s_setprio 1
	v_mfma_f32_16x16x32_bf16 v[124:127], v[130:133], v[162:165], v[124:127]
	v_mfma_f32_16x16x32_bf16 v[120:123], v[138:141], v[162:165], v[120:123]
	v_mfma_f32_16x16x32_bf16 v[108:111], v[130:133], v[170:173], v[108:111]
	v_mfma_f32_16x16x32_bf16 v[104:107], v[138:141], v[170:173], v[104:107]
	v_mfma_f32_16x16x32_bf16 v[92:95], v[130:133], v[190:193], v[92:95]
	v_mfma_f32_16x16x32_bf16 v[88:91], v[138:141], v[190:193], v[88:91]
	v_mfma_f32_16x16x32_bf16 v[76:79], v[130:133], v[204:207], v[76:79]
	v_mfma_f32_16x16x32_bf16 v[72:75], v[138:141], v[204:207], v[72:75]
	v_mfma_f32_16x16x32_bf16 v[124:127], v[134:137], v[166:169], v[124:127]
	v_mfma_f32_16x16x32_bf16 v[120:123], v[142:145], v[166:169], v[120:123]
	v_mfma_f32_16x16x32_bf16 v[108:111], v[134:137], v[184:187], v[108:111]
	v_mfma_f32_16x16x32_bf16 v[104:107], v[142:145], v[184:187], v[104:107]
	v_mfma_f32_16x16x32_bf16 v[92:95], v[134:137], v[196:199], v[92:95]
	v_mfma_f32_16x16x32_bf16 v[88:91], v[142:145], v[196:199], v[88:91]
	v_mfma_f32_16x16x32_bf16 v[76:79], v[134:137], v[212:215], v[76:79]
	v_mfma_f32_16x16x32_bf16 v[72:75], v[142:145], v[212:215], v[72:75]
	s_setprio 0
	s_setprio 1
	v_mfma_f32_16x16x32_bf16 v[116:119], v[146:149], v[162:165], v[116:119]
	v_mfma_f32_16x16x32_bf16 v[112:115], v[154:157], v[162:165], v[112:115]
	v_mfma_f32_16x16x32_bf16 v[100:103], v[146:149], v[170:173], v[100:103]
	v_mfma_f32_16x16x32_bf16 v[96:99], v[154:157], v[170:173], v[96:99]
	v_mfma_f32_16x16x32_bf16 v[84:87], v[146:149], v[190:193], v[84:87]
	v_mfma_f32_16x16x32_bf16 v[80:83], v[154:157], v[190:193], v[80:83]
	v_mfma_f32_16x16x32_bf16 v[68:71], v[146:149], v[204:207], v[68:71]
	v_mfma_f32_16x16x32_bf16 v[64:67], v[154:157], v[204:207], v[64:67]
	v_mfma_f32_16x16x32_bf16 v[116:119], v[150:153], v[166:169], v[116:119]
	v_mfma_f32_16x16x32_bf16 v[112:115], v[158:161], v[166:169], v[112:115]
	v_mfma_f32_16x16x32_bf16 v[100:103], v[150:153], v[184:187], v[100:103]
	v_mfma_f32_16x16x32_bf16 v[96:99], v[158:161], v[184:187], v[96:99]
	s_waitcnt vmcnt(8)
	s_setprio 2
	s_barrier
	v_mfma_f32_16x16x32_bf16 v[84:87], v[150:153], v[196:199], v[84:87]
	v_mfma_f32_16x16x32_bf16 v[80:83], v[158:161], v[196:199], v[80:83]
	v_mfma_f32_16x16x32_bf16 v[68:71], v[150:153], v[212:215], v[68:71]
	v_mfma_f32_16x16x32_bf16 v[64:67], v[158:161], v[212:215], v[64:67]
	s_setprio 2
	s_mov_b32 m0, s79
	v_lshl_add_u64 v[174:175], v[174:175], 0, s[20:21]
	s_add_u32 s46, s46, 0x80080
	ds_read_b128 v[162:165], v211 offset:49152
	ds_read_b128 v[166:169], v211 offset:50176
	ds_read_b128 v[170:173], v211 offset:51200
	ds_read_b128 v[184:187], v211 offset:52224
	ds_read_b128 v[190:193], v211 offset:53248
	ds_read_b128 v[196:199], v211 offset:54272
	ds_read_b128 v[204:207], v211 offset:55296
	ds_read_b128 v[212:215], v211 offset:56320
	global_load_lds_dwordx4 v[174:175], off
	v_lshl_add_u64 v[174:175], v[200:201], 0, s[20:21]
	s_mov_b32 m0, s80
	s_addc_u32 s47, s47, 0
	global_load_lds_dwordx4 v[174:175], off
	s_mov_b32 m0, s81
	v_lshl_add_u64 v[174:175], s[46:47], 0, v[176:177]
	global_load_lds_dwordx4 v[174:175], off
	s_mov_b32 m0, s82
	v_lshl_add_u64 v[174:175], s[46:47], 0, v[178:179]
	global_load_lds_dwordx4 v[174:175], off
	s_mov_b32 m0, s61
	v_lshl_add_u64 v[174:175], v[208:209], 0, s[20:21]
	global_load_lds_dwordx4 v[174:175], off
	s_mov_b32 m0, s62
	v_lshl_add_u64 v[174:175], v[216:217], 0, s[20:21]
	global_load_lds_dwordx4 v[174:175], off
	s_cmp_eq_u32 s100, 0
	s_waitcnt lgkmcnt(0)
	s_cbranch_scc1 .Ldw_16
	s_waitcnt vmcnt(8)
.Ldw_16:
	s_barrier
	s_setprio 1
	v_mfma_f32_16x16x32_bf16 v[60:63], v[130:133], v[162:165], v[60:63]
	v_mfma_f32_16x16x32_bf16 v[56:59], v[138:141], v[162:165], v[56:59]
	v_mfma_f32_16x16x32_bf16 v[44:47], v[130:133], v[170:173], v[44:47]
	v_mfma_f32_16x16x32_bf16 v[40:43], v[138:141], v[170:173], v[40:43]
	v_mfma_f32_16x16x32_bf16 v[28:31], v[130:133], v[190:193], v[28:31]
	v_mfma_f32_16x16x32_bf16 v[24:27], v[138:141], v[190:193], v[24:27]
	v_mfma_f32_16x16x32_bf16 v[12:15], v[130:133], v[204:207], v[12:15]
	v_mfma_f32_16x16x32_bf16 v[8:11], v[138:141], v[204:207], v[8:11]
	v_mfma_f32_16x16x32_bf16 v[60:63], v[134:137], v[166:169], v[60:63]
	v_mfma_f32_16x16x32_bf16 v[56:59], v[142:145], v[166:169], v[56:59]
	v_mfma_f32_16x16x32_bf16 v[44:47], v[134:137], v[184:187], v[44:47]
	v_mfma_f32_16x16x32_bf16 v[40:43], v[142:145], v[184:187], v[40:43]
	v_mfma_f32_16x16x32_bf16 v[28:31], v[134:137], v[196:199], v[28:31]
	v_mfma_f32_16x16x32_bf16 v[24:27], v[142:145], v[196:199], v[24:27]
	v_mfma_f32_16x16x32_bf16 v[12:15], v[134:137], v[212:215], v[12:15]
	v_mfma_f32_16x16x32_bf16 v[8:11], v[142:145], v[212:215], v[8:11]
	s_setprio 0
	s_setprio 1
	v_mfma_f32_16x16x32_bf16 v[52:55], v[146:149], v[162:165], v[52:55]
	v_mfma_f32_16x16x32_bf16 v[48:51], v[154:157], v[162:165], v[48:51]
	v_mfma_f32_16x16x32_bf16 v[36:39], v[146:149], v[170:173], v[36:39]
	v_mfma_f32_16x16x32_bf16 v[32:35], v[154:157], v[170:173], v[32:35]
	v_mfma_f32_16x16x32_bf16 v[20:23], v[146:149], v[190:193], v[20:23]
	v_mfma_f32_16x16x32_bf16 v[16:19], v[154:157], v[190:193], v[16:19]
	v_mfma_f32_16x16x32_bf16 v[4:7], v[146:149], v[204:207], v[4:7]
	v_mfma_f32_16x16x32_bf16 v[0:3], v[154:157], v[204:207], v[0:3]
	v_mfma_f32_16x16x32_bf16 v[52:55], v[150:153], v[166:169], v[52:55]
	v_mfma_f32_16x16x32_bf16 v[48:51], v[158:161], v[166:169], v[48:51]
	v_mfma_f32_16x16x32_bf16 v[36:39], v[150:153], v[184:187], v[36:39]
	v_mfma_f32_16x16x32_bf16 v[32:35], v[158:161], v[184:187], v[32:35]
	s_waitcnt vmcnt(8)
	s_setprio 2
	s_barrier
	v_mfma_f32_16x16x32_bf16 v[20:23], v[150:153], v[196:199], v[20:23]
	v_mfma_f32_16x16x32_bf16 v[16:19], v[158:161], v[196:199], v[16:19]
	v_mfma_f32_16x16x32_bf16 v[4:7], v[150:153], v[212:215], v[4:7]
	v_mfma_f32_16x16x32_bf16 v[0:3], v[158:161], v[212:215], v[0:3]
	s_setprio 0
	s_add_i32 s70, s70, 1
	s_add_u32 s44, s44, 0x100
	s_addc_u32 s45, s45, 0
	s_add_u32 s83, s83, 0x100
	s_addc_u32 s84, s84, 0
	s_cmp_gt_u32 s85, 29
	s_cbranch_scc0 .LBB0_698
	s_lshl_b32 s29, s41, 12
	s_and_b32 s29, s29, 0x1000
	s_add_i32 s29, s29, 0
	v_mbcnt_lo_u32_b32 v128, -1, 0
	v_mbcnt_hi_u32_b32 v128, -1, v128
	s_add_i32 s29, s29, s63
	v_lshlrev_b32_e32 v128, 4, v128
	s_add_i32 s29, s29, 0x20400
	v_and_b32_e32 v128, 0xf0, v128
	v_add_u32_e32 v128, s29, v128
	ds_read2_b32 v[214:215], v128 offset0:3 offset1:67
	ds_read2_b32 v[206:207], v128 offset0:131 offset1:195
	v_add_u32_e32 v128, 12, v128
	ds_read2st64_b32 v[196:197], v128 offset0:8 offset1:9
	ds_read2st64_b32 v[190:191], v128 offset0:10 offset1:11
	s_and_b64 vcc, exec, s[22:23]
	s_waitcnt lgkmcnt(0)
	v_mov_b32_e32 v210, v215
	v_mov_b32_e32 v202, v207
	v_mov_b32_e32 v194, v197
	v_mov_b32_e32 v188, v191
	s_cbranch_vccz .LBB0_703
	s_barrier

.LBB0_783:
	s_ashr_i32 s23, s22, 31
	s_lshl_b64 s[26:27], s[22:23], 19
	s_add_u32 s26, s43, s26
	s_addc_u32 s27, s44, s27
	s_and_b64 s[28:29], s[4:5], exec
	s_cselect_b32 s23, s27, s37
	s_cselect_b32 s31, s26, s36
	s_ashr_i32 s25, s24, 31
	s_lshl_b64 s[28:29], s[24:25], 19
	s_add_u32 s28, s45, s28
	s_addc_u32 s29, s46, s29
	s_and_b64 s[40:41], s[4:5], exec
	s_cselect_b32 s25, s29, s39
	s_cselect_b32 s62, s28, s38
	s_add_u32 s36, s36, 0x40080
	s_addc_u32 s37, s37, 0
	s_add_u32 s63, s38, 0x100
	s_addc_u32 s64, s39, 0
	s_mov_b32 s65, -2
	ds_read_b128 v[144:147], v163
	ds_read_b128 v[148:151], v163 offset:1024
	ds_read_b128 v[152:155], v163 offset:2048
	ds_read_b128 v[156:159], v163 offset:3072
	ds_read_b128 v[168:171], v164
	ds_read_b128 v[172:175], v164 offset:1024
	ds_read_b128 v[176:179], v164 offset:2048
	ds_read_b128 v[180:183], v164 offset:3072
	s_add_u32 s38, s36, 0xfffc0080
	s_addc_u32 s39, s37, -1
	s_cmp_eq_u32 s65, 12
	s_cselect_b32 s41, s23, s39
	s_cselect_b32 s40, s31, s38
	s_cselect_b32 s39, s25, s64
	s_cselect_b32 s38, s62, s63
	v_lshl_add_u64 v[160:161], s[36:37], 0, v[136:137]
	s_add_i32 m0, s50, 0xc000
	ds_read_b128 v[184:187], v165
	ds_read_b128 v[188:191], v165 offset:1024
	ds_read_b128 v[192:195], v165 offset:2048
	ds_read_b128 v[196:199], v165 offset:3072
	ds_read_b128 v[200:203], v165 offset:4096
	ds_read_b128 v[204:207], v165 offset:5120
	ds_read_b128 v[208:211], v165 offset:6144
	ds_read_b128 v[212:215], v165 offset:7168
	global_load_lds_dwordx4 v[160:161], off
	s_add_i32 m0, s50, 0xe000
	v_lshl_add_u64 v[160:161], s[36:37], 0, v[138:139]
	global_load_lds_dwordx4 v[160:161], off
	s_cmp_eq_u32 s100, 0
	s_waitcnt lgkmcnt(0)
	s_cbranch_scc1 .Ldw_17
	s_waitcnt vmcnt(8)
.Ldw_17:
	s_barrier
	s_setprio 1
	v_mfma_f32_16x16x32_bf16 v[124:127], v[144:147], v[184:187], 0
	v_mfma_f32_16x16x32_bf16 v[120:123], v[152:155], v[184:187], 0
	v_mfma_f32_16x16x32_bf16 v[108:111], v[144:147], v[192:195], 0
	v_mfma_f32_16x16x32_bf16 v[104:107], v[152:155], v[192:195], 0
	v_mfma_f32_16x16x32_bf16 v[92:95], v[144:147], v[200:203], 0
	v_mfma_f32_16x16x32_bf16 v[88:91], v[152:155], v[200:203], 0
	v_mfma_f32_16x16x32_bf16 v[76:79], v[144:147], v[208:211], 0
	v_mfma_f32_16x16x32_bf16 v[72:75], v[152:155], v[208:211], 0
	v_mfma_f32_16x16x32_bf16 v[124:127], v[148:151], v[188:191], v[124:127]
	v_mfma_f32_16x16x32_bf16 v[120:123], v[156:159], v[188:191], v[120:123]
	v_mfma_f32_16x16x32_bf16 v[108:111], v[148:151], v[196:199], v[108:111]
	v_mfma_f32_16x16x32_bf16 v[104:107], v[156:159], v[196:199], v[104:107]
	v_mfma_f32_16x16x32_bf16 v[92:95], v[148:151], v[204:207], v[92:95]
	v_mfma_f32_16x16x32_bf16 v[88:91], v[156:159], v[204:207], v[88:91]
	v_mfma_f32_16x16x32_bf16 v[76:79], v[148:151], v[212:215], v[76:79]
	v_mfma_f32_16x16x32_bf16 v[72:75], v[156:159], v[212:215], v[72:75]
	s_setprio 0
	s_setprio 1
	v_mfma_f32_16x16x32_bf16 v[116:119], v[168:171], v[184:187], 0
	v_mfma_f32_16x16x32_bf16 v[112:115], v[176:179], v[184:187], 0
	v_mfma_f32_16x16x32_bf16 v[100:103], v[168:171], v[192:195], 0
	v_mfma_f32_16x16x32_bf16 v[96:99], v[176:179], v[192:195], 0
	v_mfma_f32_16x16x32_bf16 v[84:87], v[168:171], v[200:203], 0
	v_mfma_f32_16x16x32_bf16 v[80:83], v[176:179], v[200:203], 0
	v_mfma_f32_16x16x32_bf16 v[68:71], v[168:171], v[208:211], 0
	v_mfma_f32_16x16x32_bf16 v[64:67], v[176:179], v[208:211], 0
	v_mfma_f32_16x16x32_bf16 v[116:119], v[172:175], v[188:191], v[116:119]
	v_mfma_f32_16x16x32_bf16 v[112:115], v[180:183], v[188:191], v[112:115]
	v_mfma_f32_16x16x32_bf16 v[100:103], v[172:175], v[196:199], v[100:103]
	v_mfma_f32_16x16x32_bf16 v[96:99], v[180:183], v[196:199], v[96:99]
	s_waitcnt vmcnt(8)
	s_setprio 2
	s_barrier
	v_mfma_f32_16x16x32_bf16 v[84:87], v[172:175], v[204:207], v[84:87]
	v_mfma_f32_16x16x32_bf16 v[80:83], v[180:183], v[204:207], v[80:83]
	v_mfma_f32_16x16x32_bf16 v[68:71], v[172:175], v[212:215], v[68:71]
	v_mfma_f32_16x16x32_bf16 v[64:67], v[180:183], v[212:215], v[64:67]
	s_setprio 2
	s_add_i32 s66, s59, s47
	v_lshl_add_u64 v[160:161], s[38:39], 0, v[132:133]
	s_mov_b32 m0, s66
	ds_read_b128 v[184:187], v165 offset:16384
	ds_read_b128 v[188:191], v165 offset:17408
	ds_read_b128 v[192:195], v165 offset:18432
	ds_read_b128 v[196:199], v165 offset:19456
	ds_read_b128 v[200:203], v165 offset:20480
	ds_read_b128 v[204:207], v165 offset:21504
	ds_read_b128 v[208:211], v165 offset:22528
	ds_read_b128 v[212:215], v165 offset:23552
	global_load_lds_dwordx4 v[160:161], off
	s_add_i32 m0, s66, 0x2000
	s_add_u32 s66, s38, 0x40000
	v_lshl_add_u64 v[216:217], s[38:39], 0, v[128:129]
	s_addc_u32 s67, s39, 0
	s_add_i32 s68, s60, s47
	global_load_lds_dwordx4 v[216:217], off
	v_lshl_add_u64 v[218:219], s[66:67], 0, v[132:133]
	s_mov_b32 m0, s68
	v_lshl_add_u64 v[220:221], s[40:41], 0, v[130:131]
	global_load_lds_dwordx4 v[218:219], off
	s_add_i32 m0, s68, 0x2000
	v_lshl_add_u64 v[218:219], s[66:67], 0, v[128:129]
	global_load_lds_dwordx4 v[218:219], off
	s_mov_b32 m0, s50
	v_lshl_add_u64 v[218:219], s[40:41], 0, v[134:135]
	global_load_lds_dwordx4 v[218:219], off
	s_mov_b32 m0, s51
	s_nop 0
	global_load_lds_dwordx4 v[220:221], off
	s_cmp_eq_u32 s100, 0
	s_waitcnt lgkmcnt(0)
	s_cbranch_scc1 .Ldw_18
	s_waitcnt vmcnt(8)
.Ldw_18:
	s_barrier
	s_setprio 1
	v_mfma_f32_16x16x32_bf16 v[60:63], v[144:147], v[184:187], 0
	v_mfma_f32_16x16x32_bf16 v[56:59], v[152:155], v[184:187], 0
	v_mfma_f32_16x16x32_bf16 v[44:47], v[144:147], v[192:195], 0
	v_mfma_f32_16x16x32_bf16 v[40:43], v[152:155], v[192:195], 0
	v_mfma_f32_16x16x32_bf16 v[28:31], v[144:147], v[200:203], 0
	v_mfma_f32_16x16x32_bf16 v[24:27], v[152:155], v[200:203], 0
	v_mfma_f32_16x16x32_bf16 v[12:15], v[144:147], v[208:211], 0
	v_mfma_f32_16x16x32_bf16 v[8:11], v[152:155], v[208:211], 0
	v_mfma_f32_16x16x32_bf16 v[60:63], v[148:151], v[188:191], v[60:63]
	v_mfma_f32_16x16x32_bf16 v[56:59], v[156:159], v[188:191], v[56:59]
	v_mfma_f32_16x16x32_bf16 v[44:47], v[148:151], v[196:199], v[44:47]
	v_mfma_f32_16x16x32_bf16 v[40:43], v[156:159], v[196:199], v[40:43]
	v_mfma_f32_16x16x32_bf16 v[28:31], v[148:151], v[204:207], v[28:31]
	v_mfma_f32_16x16x32_bf16 v[24:27], v[156:159], v[204:207], v[24:27]
	v_mfma_f32_16x16x32_bf16 v[12:15], v[148:151], v[212:215], v[12:15]
	v_mfma_f32_16x16x32_bf16 v[8:11], v[156:159], v[212:215], v[8:11]
	s_setprio 0
	s_setprio 1
	v_mfma_f32_16x16x32_bf16 v[52:55], v[168:171], v[184:187], 0
	v_mfma_f32_16x16x32_bf16 v[48:51], v[176:179], v[184:187], 0
	v_mfma_f32_16x16x32_bf16 v[36:39], v[168:171], v[192:195], 0
	v_mfma_f32_16x16x32_bf16 v[32:35], v[176:179], v[192:195], 0
	v_mfma_f32_16x16x32_bf16 v[20:23], v[168:171], v[200:203], 0
	v_mfma_f32_16x16x32_bf16 v[16:19], v[176:179], v[200:203], 0
	v_mfma_f32_16x16x32_bf16 v[4:7], v[168:171], v[208:211], 0
	v_mfma_f32_16x16x32_bf16 v[0:3], v[176:179], v[208:211], 0
	v_mfma_f32_16x16x32_bf16 v[52:55], v[172:175], v[188:191], v[52:55]
	v_mfma_f32_16x16x32_bf16 v[48:51], v[180:183], v[188:191], v[48:51]
	v_mfma_f32_16x16x32_bf16 v[36:39], v[172:175], v[196:199], v[36:39]
	v_mfma_f32_16x16x32_bf16 v[32:35], v[180:183], v[196:199], v[32:35]
	s_waitcnt vmcnt(8)
	s_setprio 2
	s_barrier
	v_mfma_f32_16x16x32_bf16 v[20:23], v[172:175], v[204:207], v[20:23]
	v_mfma_f32_16x16x32_bf16 v[16:19], v[180:183], v[204:207], v[16:19]
	v_mfma_f32_16x16x32_bf16 v[4:7], v[172:175], v[212:215], v[4:7]
	v_mfma_f32_16x16x32_bf16 v[0:3], v[180:183], v[212:215], v[0:3]
	s_setprio 0
	s_add_i32 s66, 0, 0x18000
	s_add_i32 s67, 0, 0x1c000
	v_add_u32_e32 v156, s66, v162
	v_add_u32_e32 v167, s67, v162
	ds_read_b128 v[144:147], v156
	ds_read_b128 v[148:151], v156 offset:1024
	ds_read_b128 v[152:155], v156 offset:2048
	ds_read_b128 v[156:159], v156 offset:3072
	ds_read_b128 v[168:171], v167
	ds_read_b128 v[172:175], v167 offset:1024
	ds_read_b128 v[176:179], v167 offset:2048
	ds_read_b128 v[180:183], v167 offset:3072
	s_add_u32 s40, s40, 0x40000
	s_addc_u32 s41, s41, 0
	s_mov_b32 m0, s54
	v_lshl_add_u64 v[222:223], s[40:41], 0, v[134:135]
	ds_read_b128 v[184:187], v165 offset:32768
	ds_read_b128 v[188:191], v165 offset:33792
	ds_read_b128 v[192:195], v165 offset:34816
	ds_read_b128 v[196:199], v165 offset:35840
	ds_read_b128 v[200:203], v165 offset:36864
	ds_read_b128 v[204:207], v165 offset:37888
	ds_read_b128 v[208:211], v165 offset:38912
	ds_read_b128 v[212:215], v165 offset:39936
	global_load_lds_dwordx4 v[222:223], off
	s_mov_b32 m0, s55
	v_lshl_add_u64 v[222:223], s[40:41], 0, v[130:131]
	global_load_lds_dwordx4 v[222:223], off
	s_cmp_eq_u32 s100, 0
	s_waitcnt lgkmcnt(0)
	s_cbranch_scc1 .Ldw_19
	s_waitcnt vmcnt(8)
.Ldw_19:
	s_barrier
	s_setprio 1
	v_mfma_f32_16x16x32_bf16 v[124:127], v[144:147], v[184:187], v[124:127]
	v_mfma_f32_16x16x32_bf16 v[120:123], v[152:155], v[184:187], v[120:123]
	v_mfma_f32_16x16x32_bf16 v[108:111], v[144:147], v[192:195], v[108:111]
	v_mfma_f32_16x16x32_bf16 v[104:107], v[152:155], v[192:195], v[104:107]
	v_mfma_f32_16x16x32_bf16 v[92:95], v[144:147], v[200:203], v[92:95]
	v_mfma_f32_16x16x32_bf16 v[88:91], v[152:155], v[200:203], v[88:91]
	v_mfma_f32_16x16x32_bf16 v[76:79], v[144:147], v[208:211], v[76:79]
	v_mfma_f32_16x16x32_bf16 v[72:75], v[152:155], v[208:211], v[72:75]
	v_mfma_f32_16x16x32_bf16 v[124:127], v[148:151], v[188:191], v[124:127]
	v_mfma_f32_16x16x32_bf16 v[120:123], v[156:159], v[188:191], v[120:123]
	v_mfma_f32_16x16x32_bf16 v[108:111], v[148:151], v[196:199], v[108:111]
	v_mfma_f32_16x16x32_bf16 v[104:107], v[156:159], v[196:199], v[104:107]
	v_mfma_f32_16x16x32_bf16 v[92:95], v[148:151], v[204:207], v[92:95]
	v_mfma_f32_16x16x32_bf16 v[88:91], v[156:159], v[204:207], v[88:91]
	v_mfma_f32_16x16x32_bf16 v[76:79], v[148:151], v[212:215], v[76:79]
	v_mfma_f32_16x16x32_bf16 v[72:75], v[156:159], v[212:215], v[72:75]
	s_setprio 0
	s_setprio 1
	v_mfma_f32_16x16x32_bf16 v[116:119], v[168:171], v[184:187], v[116:119]
	v_mfma_f32_16x16x32_bf16 v[112:115], v[176:179], v[184:187], v[112:115]
	v_mfma_f32_16x16x32_bf16 v[100:103], v[168:171], v[192:195], v[100:103]
	v_mfma_f32_16x16x32_bf16 v[96:99], v[176:179], v[192:195], v[96:99]
	v_mfma_f32_16x16x32_bf16 v[84:87], v[168:171], v[200:203], v[84:87]
	v_mfma_f32_16x16x32_bf16 v[80:83], v[176:179], v[200:203], v[80:83]
	v_mfma_f32_16x16x32_bf16 v[68:71], v[168:171], v[208:211], v[68:71]
	v_mfma_f32_16x16x32_bf16 v[64:67], v[176:179], v[208:211], v[64:67]
	v_mfma_f32_16x16x32_bf16 v[116:119], v[172:175], v[188:191], v[116:119]
	v_mfma_f32_16x16x32_bf16 v[112:115], v[180:183], v[188:191], v[112:115]
	v_mfma_f32_16x16x32_bf16 v[100:103], v[172:175], v[196:199], v[100:103]
	v_mfma_f32_16x16x32_bf16 v[96:99], v[180:183], v[196:199], v[96:99]
	s_waitcnt vmcnt(8)
	s_setprio 2
	s_barrier
	v_mfma_f32_16x16x32_bf16 v[84:87], v[172:175], v[204:207], v[84:87]
	v_mfma_f32_16x16x32_bf16 v[80:83], v[180:183], v[204:207], v[80:83]
	v_mfma_f32_16x16x32_bf16 v[68:71], v[172:175], v[212:215], v[68:71]
	v_mfma_f32_16x16x32_bf16 v[64:67], v[180:183], v[212:215], v[64:67]
	s_setprio 2
	s_add_i32 s40, s66, s47
	v_lshl_add_u64 v[160:161], v[160:161], 0, s[16:17]
	s_mov_b32 m0, s40
	ds_read_b128 v[184:187], v165 offset:49152
	ds_read_b128 v[188:191], v165 offset:50176
	ds_read_b128 v[192:195], v165 offset:51200
	ds_read_b128 v[196:199], v165 offset:52224
	ds_read_b128 v[200:203], v165 offset:53248
	ds_read_b128 v[204:207], v165 offset:54272
	ds_read_b128 v[208:211], v165 offset:55296
	ds_read_b128 v[212:215], v165 offset:56320
	global_load_lds_dwordx4 v[160:161], off
	s_add_i32 m0, s40, 0x2000
	s_add_u32 s38, s38, 0x40080
	v_lshl_add_u64 v[160:161], v[216:217], 0, s[16:17]
	s_addc_u32 s39, s39, 0
	s_add_i32 s40, s67, s47
	global_load_lds_dwordx4 v[160:161], off
	s_mov_b32 m0, s40
	v_lshl_add_u64 v[160:161], s[38:39], 0, v[132:133]
	global_load_lds_dwordx4 v[160:161], off
	s_add_i32 m0, s40, 0x2000
	v_lshl_add_u64 v[160:161], s[38:39], 0, v[128:129]
	global_load_lds_dwordx4 v[160:161], off
	s_mov_b32 m0, s57
	v_lshl_add_u64 v[160:161], v[218:219], 0, s[16:17]
	global_load_lds_dwordx4 v[160:161], off
	s_mov_b32 m0, s58
	v_lshl_add_u64 v[160:161], v[220:221], 0, s[16:17]
	global_load_lds_dwordx4 v[160:161], off
	s_cmp_eq_u32 s100, 0
	s_waitcnt lgkmcnt(0)
	s_cbranch_scc1 .Ldw_20
	s_waitcnt vmcnt(8)
.Ldw_20:
	s_barrier
	s_setprio 1
	v_mfma_f32_16x16x32_bf16 v[60:63], v[144:147], v[184:187], v[60:63]
	v_mfma_f32_16x16x32_bf16 v[56:59], v[152:155], v[184:187], v[56:59]
	v_mfma_f32_16x16x32_bf16 v[44:47], v[144:147], v[192:195], v[44:47]
	v_mfma_f32_16x16x32_bf16 v[40:43], v[152:155], v[192:195], v[40:43]
	v_mfma_f32_16x16x32_bf16 v[28:31], v[144:147], v[200:203], v[28:31]
	v_mfma_f32_16x16x32_bf16 v[24:27], v[152:155], v[200:203], v[24:27]
	v_mfma_f32_16x16x32_bf16 v[12:15], v[144:147], v[208:211], v[12:15]
	v_mfma_f32_16x16x32_bf16 v[8:11], v[152:155], v[208:211], v[8:11]
	v_mfma_f32_16x16x32_bf16 v[60:63], v[148:151], v[188:191], v[60:63]
	v_mfma_f32_16x16x32_bf16 v[56:59], v[156:159], v[188:191], v[56:59]
	v_mfma_f32_16x16x32_bf16 v[44:47], v[148:151], v[196:199], v[44:47]
	v_mfma_f32_16x16x32_bf16 v[40:43], v[156:159], v[196:199], v[40:43]
	v_mfma_f32_16x16x32_bf16 v[28:31], v[148:151], v[204:207], v[28:31]
	v_mfma_f32_16x16x32_bf16 v[24:27], v[156:159], v[204:207], v[24:27]
	v_mfma_f32_16x16x32_bf16 v[12:15], v[148:151], v[212:215], v[12:15]
	v_mfma_f32_16x16x32_bf16 v[8:11], v[156:159], v[212:215], v[8:11]
	s_setprio 0
	s_setprio 1
	v_mfma_f32_16x16x32_bf16 v[52:55], v[168:171], v[184:187], v[52:55]
	v_mfma_f32_16x16x32_bf16 v[48:51], v[176:179], v[184:187], v[48:51]
	v_mfma_f32_16x16x32_bf16 v[36:39], v[168:171], v[192:195], v[36:39]
	v_mfma_f32_16x16x32_bf16 v[32:35], v[176:179], v[192:195], v[32:35]
	v_mfma_f32_16x16x32_bf16 v[20:23], v[168:171], v[200:203], v[20:23]
	v_mfma_f32_16x16x32_bf16 v[16:19], v[176:179], v[200:203], v[16:19]
	v_mfma_f32_16x16x32_bf16 v[4:7], v[168:171], v[208:211], v[4:7]
	v_mfma_f32_16x16x32_bf16 v[0:3], v[176:179], v[208:211], v[0:3]
	v_mfma_f32_16x16x32_bf16 v[52:55], v[172:175], v[188:191], v[52:55]
	v_mfma_f32_16x16x32_bf16 v[48:51], v[180:183], v[188:191], v[48:51]
	v_mfma_f32_16x16x32_bf16 v[36:39], v[172:175], v[196:199], v[36:39]
	v_mfma_f32_16x16x32_bf16 v[32:35], v[180:183], v[196:199], v[32:35]
	s_waitcnt vmcnt(8)
	s_setprio 2
	s_barrier
	v_mfma_f32_16x16x32_bf16 v[20:23], v[172:175], v[204:207], v[20:23]
	v_mfma_f32_16x16x32_bf16 v[16:19], v[180:183], v[204:207], v[16:19]
	v_mfma_f32_16x16x32_bf16 v[4:7], v[172:175], v[212:215], v[4:7]
	v_mfma_f32_16x16x32_bf16 v[0:3], v[180:183], v[212:215], v[0:3]
	s_setprio 0
	s_add_i32 s65, s65, 2
	s_add_u32 s36, s36, 0x100
	s_addc_u32 s37, s37, 0
	s_add_u32 s63, s63, 0x100
	s_addc_u32 s64, s64, 0
	s_cmp_gt_u32 s65, 13
.LBB0_784:
	ds_read_b128 v[144:147], v163
	ds_read_b128 v[148:151], v163 offset:1024
	ds_read_b128 v[152:155], v163 offset:2048
	ds_read_b128 v[156:159], v163 offset:3072
	ds_read_b128 v[168:171], v164
	ds_read_b128 v[172:175], v164 offset:1024
	ds_read_b128 v[176:179], v164 offset:2048
	ds_read_b128 v[180:183], v164 offset:3072
	s_add_u32 s38, s36, 0xfffc0080
	s_addc_u32 s39, s37, -1
	s_cmp_eq_u32 s65, 12
	s_cselect_b32 s41, s23, s39
	s_cselect_b32 s40, s31, s38
	s_cselect_b32 s39, s25, s64
	s_cselect_b32 s38, s62, s63
	v_lshl_add_u64 v[160:161], s[36:37], 0, v[136:137]
	s_add_i32 m0, s50, 0xc000
	ds_read_b128 v[184:187], v165
	ds_read_b128 v[188:191], v165 offset:1024
	ds_read_b128 v[192:195], v165 offset:2048
	ds_read_b128 v[196:199], v165 offset:3072
	ds_read_b128 v[200:203], v165 offset:4096
	ds_read_b128 v[204:207], v165 offset:5120
	ds_read_b128 v[208:211], v165 offset:6144
	ds_read_b128 v[212:215], v165 offset:7168
	global_load_lds_dwordx4 v[160:161], off
	s_add_i32 m0, s50, 0xe000
	v_lshl_add_u64 v[160:161], s[36:37], 0, v[138:139]
	global_load_lds_dwordx4 v[160:161], off
	s_cmp_eq_u32 s100, 0
	s_waitcnt lgkmcnt(0)
	s_cbranch_scc1 .Ldw_21
	s_waitcnt vmcnt(8)
.Ldw_21:
	s_barrier
	s_setprio 1
	v_mfma_f32_16x16x32_bf16 v[124:127], v[144:147], v[184:187], v[124:127]
	v_mfma_f32_16x16x32_bf16 v[120:123], v[152:155], v[184:187], v[120:123]
	v_mfma_f32_16x16x32_bf16 v[108:111], v[144:147], v[192:195], v[108:111]
	v_mfma_f32_16x16x32_bf16 v[104:107], v[152:155], v[192:195], v[104:107]
	v_mfma_f32_16x16x32_bf16 v[92:95], v[144:147], v[200:203], v[92:95]
	v_mfma_f32_16x16x32_bf16 v[88:91], v[152:155], v[200:203], v[88:91]
	v_mfma_f32_16x16x32_bf16 v[76:79], v[144:147], v[208:211], v[76:79]
	v_mfma_f32_16x16x32_bf16 v[72:75], v[152:155], v[208:211], v[72:75]
	v_mfma_f32_16x16x32_bf16 v[124:127], v[148:151], v[188:191], v[124:127]
	v_mfma_f32_16x16x32_bf16 v[120:123], v[156:159], v[188:191], v[120:123]
	v_mfma_f32_16x16x32_bf16 v[108:111], v[148:151], v[196:199], v[108:111]
	v_mfma_f32_16x16x32_bf16 v[104:107], v[156:159], v[196:199], v[104:107]
	v_mfma_f32_16x16x32_bf16 v[92:95], v[148:151], v[204:207], v[92:95]
	v_mfma_f32_16x16x32_bf16 v[88:91], v[156:159], v[204:207], v[88:91]
	v_mfma_f32_16x16x32_bf16 v[76:79], v[148:151], v[212:215], v[76:79]
	v_mfma_f32_16x16x32_bf16 v[72:75], v[156:159], v[212:215], v[72:75]
	s_setprio 0
	s_setprio 1
	v_mfma_f32_16x16x32_bf16 v[116:119], v[168:171], v[184:187], v[116:119]
	v_mfma_f32_16x16x32_bf16 v[112:115], v[176:179], v[184:187], v[112:115]
	v_mfma_f32_16x16x32_bf16 v[100:103], v[168:171], v[192:195], v[100:103]
	v_mfma_f32_16x16x32_bf16 v[96:99], v[176:179], v[192:195], v[96:99]
	v_mfma_f32_16x16x32_bf16 v[84:87], v[168:171], v[200:203], v[84:87]
	v_mfma_f32_16x16x32_bf16 v[80:83], v[176:179], v[200:203], v[80:83]
	v_mfma_f32_16x16x32_bf16 v[68:71], v[168:171], v[208:211], v[68:71]
	v_mfma_f32_16x16x32_bf16 v[64:67], v[176:179], v[208:211], v[64:67]
	v_mfma_f32_16x16x32_bf16 v[116:119], v[172:175], v[188:191], v[116:119]
	v_mfma_f32_16x16x32_bf16 v[112:115], v[180:183], v[188:191], v[112:115]
	v_mfma_f32_16x16x32_bf16 v[100:103], v[172:175], v[196:199], v[100:103]
	v_mfma_f32_16x16x32_bf16 v[96:99], v[180:183], v[196:199], v[96:99]
	s_waitcnt vmcnt(8)
	s_setprio 2
	s_barrier
	v_mfma_f32_16x16x32_bf16 v[84:87], v[172:175], v[204:207], v[84:87]
	v_mfma_f32_16x16x32_bf16 v[80:83], v[180:183], v[204:207], v[80:83]
	v_mfma_f32_16x16x32_bf16 v[68:71], v[172:175], v[212:215], v[68:71]
	v_mfma_f32_16x16x32_bf16 v[64:67], v[180:183], v[212:215], v[64:67]
	s_setprio 2
	s_add_i32 s66, s59, s47
	v_lshl_add_u64 v[160:161], s[38:39], 0, v[132:133]
	s_mov_b32 m0, s66
	ds_read_b128 v[184:187], v165 offset:16384
	ds_read_b128 v[188:191], v165 offset:17408
	ds_read_b128 v[192:195], v165 offset:18432
	ds_read_b128 v[196:199], v165 offset:19456
	ds_read_b128 v[200:203], v165 offset:20480
	ds_read_b128 v[204:207], v165 offset:21504
	ds_read_b128 v[208:211], v165 offset:22528
	ds_read_b128 v[212:215], v165 offset:23552
	global_load_lds_dwordx4 v[160:161], off
	s_add_i32 m0, s66, 0x2000
	s_add_u32 s66, s38, 0x40000
	v_lshl_add_u64 v[216:217], s[38:39], 0, v[128:129]
	s_addc_u32 s67, s39, 0
	s_add_i32 s68, s60, s47
	global_load_lds_dwordx4 v[216:217], off
	v_lshl_add_u64 v[218:219], s[66:67], 0, v[132:133]
	s_mov_b32 m0, s68
	v_lshl_add_u64 v[220:221], s[40:41], 0, v[130:131]
	global_load_lds_dwordx4 v[218:219], off
	s_add_i32 m0, s68, 0x2000
	v_lshl_add_u64 v[218:219], s[66:67], 0, v[128:129]
	global_load_lds_dwordx4 v[218:219], off
	s_mov_b32 m0, s50
	v_lshl_add_u64 v[218:219], s[40:41], 0, v[134:135]
	global_load_lds_dwordx4 v[218:219], off
	s_mov_b32 m0, s51
	s_nop 0
	global_load_lds_dwordx4 v[220:221], off
	s_cmp_eq_u32 s100, 0
	s_waitcnt lgkmcnt(0)
	s_cbranch_scc1 .Ldw_22
	s_waitcnt vmcnt(8)
.Ldw_22:
	s_barrier
	s_setprio 1
	v_mfma_f32_16x16x32_bf16 v[60:63], v[144:147], v[184:187], v[60:63]
	v_mfma_f32_16x16x32_bf16 v[56:59], v[152:155], v[184:187], v[56:59]
	v_mfma_f32_16x16x32_bf16 v[44:47], v[144:147], v[192:195], v[44:47]
	v_mfma_f32_16x16x32_bf16 v[40:43], v[152:155], v[192:195], v[40:43]
	v_mfma_f32_16x16x32_bf16 v[28:31], v[144:147], v[200:203], v[28:31]
	v_mfma_f32_16x16x32_bf16 v[24:27], v[152:155], v[200:203], v[24:27]
	v_mfma_f32_16x16x32_bf16 v[12:15], v[144:147], v[208:211], v[12:15]
	v_mfma_f32_16x16x32_bf16 v[8:11], v[152:155], v[208:211], v[8:11]
	v_mfma_f32_16x16x32_bf16 v[60:63], v[148:151], v[188:191], v[60:63]
	v_mfma_f32_16x16x32_bf16 v[56:59], v[156:159], v[188:191], v[56:59]
	v_mfma_f32_16x16x32_bf16 v[44:47], v[148:151], v[196:199], v[44:47]
	v_mfma_f32_16x16x32_bf16 v[40:43], v[156:159], v[196:199], v[40:43]
	v_mfma_f32_16x16x32_bf16 v[28:31], v[148:151], v[204:207], v[28:31]
	v_mfma_f32_16x16x32_bf16 v[24:27], v[156:159], v[204:207], v[24:27]
	v_mfma_f32_16x16x32_bf16 v[12:15], v[148:151], v[212:215], v[12:15]
	v_mfma_f32_16x16x32_bf16 v[8:11], v[156:159], v[212:215], v[8:11]
	s_setprio 0
	s_setprio 1
	v_mfma_f32_16x16x32_bf16 v[52:55], v[168:171], v[184:187], v[52:55]
	v_mfma_f32_16x16x32_bf16 v[48:51], v[176:179], v[184:187], v[48:51]
	v_mfma_f32_16x16x32_bf16 v[36:39], v[168:171], v[192:195], v[36:39]
	v_mfma_f32_16x16x32_bf16 v[32:35], v[176:179], v[192:195], v[32:35]
	v_mfma_f32_16x16x32_bf16 v[20:23], v[168:171], v[200:203], v[20:23]
	v_mfma_f32_16x16x32_bf16 v[16:19], v[176:179], v[200:203], v[16:19]
	v_mfma_f32_16x16x32_bf16 v[4:7], v[168:171], v[208:211], v[4:7]
	v_mfma_f32_16x16x32_bf16 v[0:3], v[176:179], v[208:211], v[0:3]
	v_mfma_f32_16x16x32_bf16 v[52:55], v[172:175], v[188:191], v[52:55]
	v_mfma_f32_16x16x32_bf16 v[48:51], v[180:183], v[188:191], v[48:51]
	v_mfma_f32_16x16x32_bf16 v[36:39], v[172:175], v[196:199], v[36:39]
	v_mfma_f32_16x16x32_bf16 v[32:35], v[180:183], v[196:199], v[32:35]
	s_waitcnt vmcnt(8)
	s_setprio 2
	s_barrier
	v_mfma_f32_16x16x32_bf16 v[20:23], v[172:175], v[204:207], v[20:23]
	v_mfma_f32_16x16x32_bf16 v[16:19], v[180:183], v[204:207], v[16:19]
	v_mfma_f32_16x16x32_bf16 v[4:7], v[172:175], v[212:215], v[4:7]
	v_mfma_f32_16x16x32_bf16 v[0:3], v[180:183], v[212:215], v[0:3]
	s_setprio 0
	s_add_i32 s66, 0, 0x18000
	s_add_i32 s67, 0, 0x1c000
	v_add_u32_e32 v156, s66, v162
	v_add_u32_e32 v167, s67, v162
	ds_read_b128 v[144:147], v156
	ds_read_b128 v[148:151], v156 offset:1024
	ds_read_b128 v[152:155], v156 offset:2048
	ds_read_b128 v[156:159], v156 offset:3072
	ds_read_b128 v[168:171], v167
	ds_read_b128 v[172:175], v167 offset:1024
	ds_read_b128 v[176:179], v167 offset:2048
	ds_read_b128 v[180:183], v167 offset:3072
	s_add_u32 s40, s40, 0x40000
	s_addc_u32 s41, s41, 0
	s_mov_b32 m0, s54
	v_lshl_add_u64 v[222:223], s[40:41], 0, v[134:135]
	ds_read_b128 v[184:187], v165 offset:32768
	ds_read_b128 v[188:191], v165 offset:33792
	ds_read_b128 v[192:195], v165 offset:34816
	ds_read_b128 v[196:199], v165 offset:35840
	ds_read_b128 v[200:203], v165 offset:36864
	ds_read_b128 v[204:207], v165 offset:37888
	ds_read_b128 v[208:211], v165 offset:38912
	ds_read_b128 v[212:215], v165 offset:39936
	global_load_lds_dwordx4 v[222:223], off
	s_mov_b32 m0, s55
	v_lshl_add_u64 v[222:223], s[40:41], 0, v[130:131]
	global_load_lds_dwordx4 v[222:223], off
	s_cmp_eq_u32 s100, 0
	s_waitcnt lgkmcnt(0)
	s_cbranch_scc1 .Ldw_23
	s_waitcnt vmcnt(8)

.Ldw_24:
	s_barrier
	s_setprio 1
	v_mfma_f32_16x16x32_bf16 v[60:63], v[144:147], v[184:187], v[60:63]
	v_mfma_f32_16x16x32_bf16 v[56:59], v[152:155], v[184:187], v[56:59]
	v_mfma_f32_16x16x32_bf16 v[44:47], v[144:147], v[192:195], v[44:47]
	v_mfma_f32_16x16x32_bf16 v[40:43], v[152:155], v[192:195], v[40:43]
	v_mfma_f32_16x16x32_bf16 v[28:31], v[144:147], v[200:203], v[28:31]
	v_mfma_f32_16x16x32_bf16 v[24:27], v[152:155], v[200:203], v[24:27]
	v_mfma_f32_16x16x32_bf16 v[12:15], v[144:147], v[208:211], v[12:15]
	v_mfma_f32_16x16x32_bf16 v[8:11], v[152:155], v[208:211], v[8:11]
	v_mfma_f32_16x16x32_bf16 v[60:63], v[148:151], v[188:191], v[60:63]
	v_mfma_f32_16x16x32_bf16 v[56:59], v[156:159], v[188:191], v[56:59]
	v_mfma_f32_16x16x32_bf16 v[44:47], v[148:151], v[196:199], v[44:47]
	v_mfma_f32_16x16x32_bf16 v[40:43], v[156:159], v[196:199], v[40:43]
	v_mfma_f32_16x16x32_bf16 v[28:31], v[148:151], v[204:207], v[28:31]
	v_mfma_f32_16x16x32_bf16 v[24:27], v[156:159], v[204:207], v[24:27]
	v_mfma_f32_16x16x32_bf16 v[12:15], v[148:151], v[212:215], v[12:15]
	v_mfma_f32_16x16x32_bf16 v[8:11], v[156:159], v[212:215], v[8:11]
	s_setprio 0
	s_setprio 1
	v_mfma_f32_16x16x32_bf16 v[52:55], v[168:171], v[184:187], v[52:55]
	v_mfma_f32_16x16x32_bf16 v[48:51], v[176:179], v[184:187], v[48:51]
	v_mfma_f32_16x16x32_bf16 v[36:39], v[168:171], v[192:195], v[36:39]
	v_mfma_f32_16x16x32_bf16 v[32:35], v[176:179], v[192:195], v[32:35]
	v_mfma_f32_16x16x32_bf16 v[20:23], v[168:171], v[200:203], v[20:23]
	v_mfma_f32_16x16x32_bf16 v[16:19], v[176:179], v[200:203], v[16:19]
	v_mfma_f32_16x16x32_bf16 v[4:7], v[168:171], v[208:211], v[4:7]
	v_mfma_f32_16x16x32_bf16 v[0:3], v[176:179], v[208:211], v[0:3]
	v_mfma_f32_16x16x32_bf16 v[52:55], v[172:175], v[188:191], v[52:55]
	v_mfma_f32_16x16x32_bf16 v[48:51], v[180:183], v[188:191], v[48:51]
	v_mfma_f32_16x16x32_bf16 v[36:39], v[172:175], v[196:199], v[36:39]
	v_mfma_f32_16x16x32_bf16 v[32:35], v[180:183], v[196:199], v[32:35]
	s_waitcnt vmcnt(8)
	s_setprio 2
	s_barrier
	v_mfma_f32_16x16x32_bf16 v[20:23], v[172:175], v[204:207], v[20:23]
	v_mfma_f32_16x16x32_bf16 v[16:19], v[180:183], v[204:207], v[16:19]
	v_mfma_f32_16x16x32_bf16 v[4:7], v[172:175], v[212:215], v[4:7]
	v_mfma_f32_16x16x32_bf16 v[0:3], v[180:183], v[212:215], v[0:3]
	s_setprio 0
	s_add_i32 s65, s65, 2
	s_add_u32 s36, s36, 0x100
	s_addc_u32 s37, s37, 0
	s_add_u32 s63, s63, 0x100
	s_addc_u32 s64, s64, 0
	s_cmp_gt_u32 s65, 13
	s_cbranch_scc0 .LBB0_784

.LBB0_865:
	s_add_u32 s62, s28, 0x100
	s_addc_u32 s63, s29, 0
	s_mov_b32 s64, -2
	ds_read_b128 v[120:123], v233
	ds_read_b128 v[124:127], v233 offset:1024
	ds_read_b128 v[136:139], v233 offset:2048
	ds_read_b128 v[140:143], v233 offset:3072
	ds_read_b128 v[144:147], v234
	ds_read_b128 v[148:151], v234 offset:1024
	ds_read_b128 v[152:155], v234 offset:2048
	ds_read_b128 v[156:159], v234 offset:3072
	s_add_u32 s28, s26, 0x100
	s_addc_u32 s29, s27, 0
	s_cmp_eq_u32 s64, 40
	s_cselect_b32 s37, s7, s29
	s_cselect_b32 s36, s6, s28
	s_cselect_b32 s31, s25, s63
	s_cselect_b32 s30, s24, s62
	v_lshl_add_u64 v[208:209], s[26:27], 0, v[192:193]
	s_add_i32 m0, s44, 0xc000
	ds_read_b128 v[160:163], v235
	ds_read_b128 v[164:167], v235 offset:1024
	ds_read_b128 v[168:171], v235 offset:2048
	ds_read_b128 v[172:175], v235 offset:3072
	ds_read_b128 v[176:179], v235 offset:4096
	ds_read_b128 v[180:183], v235 offset:5120
	ds_read_b128 v[200:203], v235 offset:6144
	ds_read_b128 v[204:207], v235 offset:7168
	global_load_lds_dwordx4 v[208:209], off
	s_add_i32 m0, s44, 0xe000
	v_lshl_add_u64 v[208:209], s[26:27], 0, v[194:195]
	global_load_lds_dwordx4 v[208:209], off
	s_cmp_eq_u32 s100, 0
	s_waitcnt lgkmcnt(0)
	s_cbranch_scc1 .Ldw_25
	s_waitcnt vmcnt(8)
.Ldw_25:
	s_barrier
	s_setprio 1
	v_mfma_f32_16x16x32_bf16 v[132:135], v[120:123], v[160:163], 0
	v_mfma_f32_16x16x32_bf16 v[128:131], v[136:139], v[160:163], 0
	v_mfma_f32_16x16x32_bf16 v[108:111], v[120:123], v[168:171], 0
	v_mfma_f32_16x16x32_bf16 v[104:107], v[136:139], v[168:171], 0
	v_mfma_f32_16x16x32_bf16 v[92:95], v[120:123], v[176:179], 0
	v_mfma_f32_16x16x32_bf16 v[88:91], v[136:139], v[176:179], 0
	v_mfma_f32_16x16x32_bf16 v[76:79], v[120:123], v[200:203], 0
	v_mfma_f32_16x16x32_bf16 v[72:75], v[136:139], v[200:203], 0
	v_mfma_f32_16x16x32_bf16 v[132:135], v[124:127], v[164:167], v[132:135]
	v_mfma_f32_16x16x32_bf16 v[128:131], v[140:143], v[164:167], v[128:131]
	v_mfma_f32_16x16x32_bf16 v[108:111], v[124:127], v[172:175], v[108:111]
	v_mfma_f32_16x16x32_bf16 v[104:107], v[140:143], v[172:175], v[104:107]
	v_mfma_f32_16x16x32_bf16 v[92:95], v[124:127], v[180:183], v[92:95]
	v_mfma_f32_16x16x32_bf16 v[88:91], v[140:143], v[180:183], v[88:91]
	v_mfma_f32_16x16x32_bf16 v[76:79], v[124:127], v[204:207], v[76:79]
	v_mfma_f32_16x16x32_bf16 v[72:75], v[140:143], v[204:207], v[72:75]
	s_setprio 0
	s_setprio 1
	v_mfma_f32_16x16x32_bf16 v[116:119], v[144:147], v[160:163], 0
	v_mfma_f32_16x16x32_bf16 v[112:115], v[152:155], v[160:163], 0
	v_mfma_f32_16x16x32_bf16 v[100:103], v[144:147], v[168:171], 0
	v_mfma_f32_16x16x32_bf16 v[96:99], v[152:155], v[168:171], 0
	v_mfma_f32_16x16x32_bf16 v[84:87], v[144:147], v[176:179], 0
	v_mfma_f32_16x16x32_bf16 v[80:83], v[152:155], v[176:179], 0
	v_mfma_f32_16x16x32_bf16 v[68:71], v[144:147], v[200:203], 0
	v_mfma_f32_16x16x32_bf16 v[64:67], v[152:155], v[200:203], 0
	v_mfma_f32_16x16x32_bf16 v[116:119], v[148:151], v[164:167], v[116:119]
	v_mfma_f32_16x16x32_bf16 v[112:115], v[156:159], v[164:167], v[112:115]
	v_mfma_f32_16x16x32_bf16 v[100:103], v[148:151], v[172:175], v[100:103]
	v_mfma_f32_16x16x32_bf16 v[96:99], v[156:159], v[172:175], v[96:99]
	s_waitcnt vmcnt(8)
	s_setprio 2
	s_barrier
	v_mfma_f32_16x16x32_bf16 v[84:87], v[148:151], v[180:183], v[84:87]
	v_mfma_f32_16x16x32_bf16 v[80:83], v[156:159], v[180:183], v[80:83]
	v_mfma_f32_16x16x32_bf16 v[68:71], v[148:151], v[204:207], v[68:71]
	v_mfma_f32_16x16x32_bf16 v[64:67], v[156:159], v[204:207], v[64:67]
	s_setprio 2
	s_add_i32 s26, s56, s43
	v_lshl_add_u64 v[208:209], s[30:31], 0, v[186:187]
	s_mov_b32 m0, s26
	ds_read_b128 v[160:163], v235 offset:16384
	ds_read_b128 v[164:167], v235 offset:17408
	ds_read_b128 v[168:171], v235 offset:18432
	ds_read_b128 v[172:175], v235 offset:19456
	ds_read_b128 v[176:179], v235 offset:20480
	ds_read_b128 v[180:183], v235 offset:21504
	ds_read_b128 v[200:203], v235 offset:22528
	ds_read_b128 v[204:207], v235 offset:23552
	global_load_lds_dwordx4 v[208:209], off
	s_add_i32 m0, s26, 0x2000
	s_add_u32 s26, s30, 0xb0000
	v_lshl_add_u64 v[210:211], s[30:31], 0, v[190:191]
	s_addc_u32 s27, s31, 0
	s_add_i32 s65, s57, s43
	global_load_lds_dwordx4 v[210:211], off
	v_lshl_add_u64 v[212:213], s[26:27], 0, v[186:187]
	s_mov_b32 m0, s65
	v_lshl_add_u64 v[214:215], s[36:37], 0, v[188:189]
	global_load_lds_dwordx4 v[212:213], off
	s_add_i32 m0, s65, 0x2000
	v_lshl_add_u64 v[212:213], s[26:27], 0, v[190:191]
	global_load_lds_dwordx4 v[212:213], off
	s_mov_b32 m0, s44
	v_lshl_add_u64 v[212:213], s[36:37], 0, v[184:185]
	global_load_lds_dwordx4 v[212:213], off
	s_mov_b32 m0, s45
	s_nop 0
	global_load_lds_dwordx4 v[214:215], off
	s_cmp_eq_u32 s100, 0
	s_waitcnt lgkmcnt(0)
	s_cbranch_scc1 .Ldw_26
	s_waitcnt vmcnt(8)
.Ldw_26:
	s_barrier
	s_setprio 1
	v_mfma_f32_16x16x32_bf16 v[60:63], v[120:123], v[160:163], 0
	v_mfma_f32_16x16x32_bf16 v[56:59], v[136:139], v[160:163], 0
	v_mfma_f32_16x16x32_bf16 v[44:47], v[120:123], v[168:171], 0
	v_mfma_f32_16x16x32_bf16 v[40:43], v[136:139], v[168:171], 0
	v_mfma_f32_16x16x32_bf16 v[28:31], v[120:123], v[176:179], 0
	v_mfma_f32_16x16x32_bf16 v[24:27], v[136:139], v[176:179], 0
	v_mfma_f32_16x16x32_bf16 v[12:15], v[120:123], v[200:203], 0
	v_mfma_f32_16x16x32_bf16 v[8:11], v[136:139], v[200:203], 0
	v_mfma_f32_16x16x32_bf16 v[60:63], v[124:127], v[164:167], v[60:63]
	v_mfma_f32_16x16x32_bf16 v[56:59], v[140:143], v[164:167], v[56:59]
	v_mfma_f32_16x16x32_bf16 v[44:47], v[124:127], v[172:175], v[44:47]
	v_mfma_f32_16x16x32_bf16 v[40:43], v[140:143], v[172:175], v[40:43]
	v_mfma_f32_16x16x32_bf16 v[28:31], v[124:127], v[180:183], v[28:31]
	v_mfma_f32_16x16x32_bf16 v[24:27], v[140:143], v[180:183], v[24:27]
	v_mfma_f32_16x16x32_bf16 v[12:15], v[124:127], v[204:207], v[12:15]
	v_mfma_f32_16x16x32_bf16 v[8:11], v[140:143], v[204:207], v[8:11]
	s_setprio 0
	s_setprio 1
	v_mfma_f32_16x16x32_bf16 v[52:55], v[144:147], v[160:163], 0
	v_mfma_f32_16x16x32_bf16 v[48:51], v[152:155], v[160:163], 0
	v_mfma_f32_16x16x32_bf16 v[36:39], v[144:147], v[168:171], 0
	v_mfma_f32_16x16x32_bf16 v[32:35], v[152:155], v[168:171], 0
	v_mfma_f32_16x16x32_bf16 v[20:23], v[144:147], v[176:179], 0
	v_mfma_f32_16x16x32_bf16 v[16:19], v[152:155], v[176:179], 0
	v_mfma_f32_16x16x32_bf16 v[4:7], v[144:147], v[200:203], 0
	v_mfma_f32_16x16x32_bf16 v[0:3], v[152:155], v[200:203], 0
	v_mfma_f32_16x16x32_bf16 v[52:55], v[148:151], v[164:167], v[52:55]
	v_mfma_f32_16x16x32_bf16 v[48:51], v[156:159], v[164:167], v[48:51]
	v_mfma_f32_16x16x32_bf16 v[36:39], v[148:151], v[172:175], v[36:39]
	v_mfma_f32_16x16x32_bf16 v[32:35], v[156:159], v[172:175], v[32:35]
	s_waitcnt vmcnt(8)
	s_setprio 2
	s_barrier
	v_mfma_f32_16x16x32_bf16 v[20:23], v[148:151], v[180:183], v[20:23]
	v_mfma_f32_16x16x32_bf16 v[16:19], v[156:159], v[180:183], v[16:19]
	v_mfma_f32_16x16x32_bf16 v[4:7], v[148:151], v[204:207], v[4:7]
	v_mfma_f32_16x16x32_bf16 v[0:3], v[156:159], v[204:207], v[0:3]
	s_setprio 0
	s_add_i32 s65, 0, 0x18000
	s_add_i32 s66, 0, 0x1c000
	v_add_u32_e32 v140, s65, v232
	v_add_u32_e32 v156, s66, v232
	ds_read_b128 v[120:123], v140
	ds_read_b128 v[124:127], v140 offset:1024
	ds_read_b128 v[136:139], v140 offset:2048
	ds_read_b128 v[140:143], v140 offset:3072
	ds_read_b128 v[144:147], v156
	ds_read_b128 v[148:151], v156 offset:1024
	ds_read_b128 v[152:155], v156 offset:2048
	ds_read_b128 v[156:159], v156 offset:3072
	s_add_u32 s26, s36, 0xb0000
	s_addc_u32 s27, s37, 0
	s_mov_b32 m0, s46
	v_lshl_add_u64 v[216:217], s[26:27], 0, v[184:185]
	ds_read_b128 v[160:163], v235 offset:32768
	ds_read_b128 v[164:167], v235 offset:33792
	ds_read_b128 v[168:171], v235 offset:34816
	ds_read_b128 v[172:175], v235 offset:35840
	ds_read_b128 v[176:179], v235 offset:36864
	ds_read_b128 v[180:183], v235 offset:37888
	ds_read_b128 v[200:203], v235 offset:38912
	ds_read_b128 v[204:207], v235 offset:39936
	global_load_lds_dwordx4 v[216:217], off
	s_mov_b32 m0, s47
	v_lshl_add_u64 v[216:217], s[26:27], 0, v[188:189]
	global_load_lds_dwordx4 v[216:217], off
	s_cmp_eq_u32 s100, 0
	s_waitcnt lgkmcnt(0)
	s_cbranch_scc1 .Ldw_27
	s_waitcnt vmcnt(8)
.Ldw_27:
	s_barrier
	s_setprio 1
	v_mfma_f32_16x16x32_bf16 v[132:135], v[120:123], v[160:163], v[132:135]
	v_mfma_f32_16x16x32_bf16 v[128:131], v[136:139], v[160:163], v[128:131]
	v_mfma_f32_16x16x32_bf16 v[108:111], v[120:123], v[168:171], v[108:111]
	v_mfma_f32_16x16x32_bf16 v[104:107], v[136:139], v[168:171], v[104:107]
	v_mfma_f32_16x16x32_bf16 v[92:95], v[120:123], v[176:179], v[92:95]
	v_mfma_f32_16x16x32_bf16 v[88:91], v[136:139], v[176:179], v[88:91]
	v_mfma_f32_16x16x32_bf16 v[76:79], v[120:123], v[200:203], v[76:79]
	v_mfma_f32_16x16x32_bf16 v[72:75], v[136:139], v[200:203], v[72:75]
	v_mfma_f32_16x16x32_bf16 v[132:135], v[124:127], v[164:167], v[132:135]
	v_mfma_f32_16x16x32_bf16 v[128:131], v[140:143], v[164:167], v[128:131]
	v_mfma_f32_16x16x32_bf16 v[108:111], v[124:127], v[172:175], v[108:111]
	v_mfma_f32_16x16x32_bf16 v[104:107], v[140:143], v[172:175], v[104:107]
	v_mfma_f32_16x16x32_bf16 v[92:95], v[124:127], v[180:183], v[92:95]
	v_mfma_f32_16x16x32_bf16 v[88:91], v[140:143], v[180:183], v[88:91]
	v_mfma_f32_16x16x32_bf16 v[76:79], v[124:127], v[204:207], v[76:79]
	v_mfma_f32_16x16x32_bf16 v[72:75], v[140:143], v[204:207], v[72:75]
	s_setprio 0
	s_setprio 1
	v_mfma_f32_16x16x32_bf16 v[116:119], v[144:147], v[160:163], v[116:119]
	v_mfma_f32_16x16x32_bf16 v[112:115], v[152:155], v[160:163], v[112:115]
	v_mfma_f32_16x16x32_bf16 v[100:103], v[144:147], v[168:171], v[100:103]
	v_mfma_f32_16x16x32_bf16 v[96:99], v[152:155], v[168:171], v[96:99]
	v_mfma_f32_16x16x32_bf16 v[84:87], v[144:147], v[176:179], v[84:87]
	v_mfma_f32_16x16x32_bf16 v[80:83], v[152:155], v[176:179], v[80:83]
	v_mfma_f32_16x16x32_bf16 v[68:71], v[144:147], v[200:203], v[68:71]
	v_mfma_f32_16x16x32_bf16 v[64:67], v[152:155], v[200:203], v[64:67]
	v_mfma_f32_16x16x32_bf16 v[116:119], v[148:151], v[164:167], v[116:119]
	v_mfma_f32_16x16x32_bf16 v[112:115], v[156:159], v[164:167], v[112:115]
	v_mfma_f32_16x16x32_bf16 v[100:103], v[148:151], v[172:175], v[100:103]
	v_mfma_f32_16x16x32_bf16 v[96:99], v[156:159], v[172:175], v[96:99]
	s_waitcnt vmcnt(8)
	s_setprio 2
	s_barrier
	v_mfma_f32_16x16x32_bf16 v[84:87], v[148:151], v[180:183], v[84:87]
	v_mfma_f32_16x16x32_bf16 v[80:83], v[156:159], v[180:183], v[80:83]
	v_mfma_f32_16x16x32_bf16 v[68:71], v[148:151], v[204:207], v[68:71]
	v_mfma_f32_16x16x32_bf16 v[64:67], v[156:159], v[204:207], v[64:67]
	s_setprio 2
	s_add_i32 s26, s65, s43
	v_lshl_add_u64 v[208:209], v[208:209], 0, s[20:21]
	s_mov_b32 m0, s26
	ds_read_b128 v[160:163], v235 offset:49152
	ds_read_b128 v[164:167], v235 offset:50176
	ds_read_b128 v[168:171], v235 offset:51200
	ds_read_b128 v[172:175], v235 offset:52224
	ds_read_b128 v[176:179], v235 offset:53248
	ds_read_b128 v[180:183], v235 offset:54272
	ds_read_b128 v[200:203], v235 offset:55296
	ds_read_b128 v[204:207], v235 offset:56320
	global_load_lds_dwordx4 v[208:209], off
	s_add_i32 m0, s26, 0x2000
	s_add_u32 s26, s30, 0xb0080
	v_lshl_add_u64 v[208:209], v[210:211], 0, s[20:21]
	s_addc_u32 s27, s31, 0
	s_add_i32 s30, s66, s43
	global_load_lds_dwordx4 v[208:209], off
	s_mov_b32 m0, s30
	v_lshl_add_u64 v[208:209], s[26:27], 0, v[186:187]
	global_load_lds_dwordx4 v[208:209], off
	s_add_i32 m0, s30, 0x2000
	v_lshl_add_u64 v[208:209], s[26:27], 0, v[190:191]
	global_load_lds_dwordx4 v[208:209], off
	s_mov_b32 m0, s49
	v_lshl_add_u64 v[208:209], v[212:213], 0, s[20:21]
	global_load_lds_dwordx4 v[208:209], off
	s_mov_b32 m0, s50
	v_lshl_add_u64 v[208:209], v[214:215], 0, s[20:21]
	global_load_lds_dwordx4 v[208:209], off
	s_cmp_eq_u32 s100, 0
	s_waitcnt lgkmcnt(0)
	s_cbranch_scc1 .Ldw_28
	s_waitcnt vmcnt(8)
.Ldw_28:
	s_barrier
	s_setprio 1
	v_mfma_f32_16x16x32_bf16 v[60:63], v[120:123], v[160:163], v[60:63]
	v_mfma_f32_16x16x32_bf16 v[56:59], v[136:139], v[160:163], v[56:59]
	v_mfma_f32_16x16x32_bf16 v[44:47], v[120:123], v[168:171], v[44:47]
	v_mfma_f32_16x16x32_bf16 v[40:43], v[136:139], v[168:171], v[40:43]
	v_mfma_f32_16x16x32_bf16 v[28:31], v[120:123], v[176:179], v[28:31]
	v_mfma_f32_16x16x32_bf16 v[24:27], v[136:139], v[176:179], v[24:27]
	v_mfma_f32_16x16x32_bf16 v[12:15], v[120:123], v[200:203], v[12:15]
	v_mfma_f32_16x16x32_bf16 v[8:11], v[136:139], v[200:203], v[8:11]
	v_mfma_f32_16x16x32_bf16 v[60:63], v[124:127], v[164:167], v[60:63]
	v_mfma_f32_16x16x32_bf16 v[56:59], v[140:143], v[164:167], v[56:59]
	v_mfma_f32_16x16x32_bf16 v[44:47], v[124:127], v[172:175], v[44:47]
	v_mfma_f32_16x16x32_bf16 v[40:43], v[140:143], v[172:175], v[40:43]
	v_mfma_f32_16x16x32_bf16 v[28:31], v[124:127], v[180:183], v[28:31]
	v_mfma_f32_16x16x32_bf16 v[24:27], v[140:143], v[180:183], v[24:27]
	v_mfma_f32_16x16x32_bf16 v[12:15], v[124:127], v[204:207], v[12:15]
	v_mfma_f32_16x16x32_bf16 v[8:11], v[140:143], v[204:207], v[8:11]
	s_setprio 0
	s_setprio 1
	v_mfma_f32_16x16x32_bf16 v[52:55], v[144:147], v[160:163], v[52:55]
	v_mfma_f32_16x16x32_bf16 v[48:51], v[152:155], v[160:163], v[48:51]
	v_mfma_f32_16x16x32_bf16 v[36:39], v[144:147], v[168:171], v[36:39]
	v_mfma_f32_16x16x32_bf16 v[32:35], v[152:155], v[168:171], v[32:35]
	v_mfma_f32_16x16x32_bf16 v[20:23], v[144:147], v[176:179], v[20:23]
	v_mfma_f32_16x16x32_bf16 v[16:19], v[152:155], v[176:179], v[16:19]
	v_mfma_f32_16x16x32_bf16 v[4:7], v[144:147], v[200:203], v[4:7]
	v_mfma_f32_16x16x32_bf16 v[0:3], v[152:155], v[200:203], v[0:3]
	v_mfma_f32_16x16x32_bf16 v[52:55], v[148:151], v[164:167], v[52:55]
	v_mfma_f32_16x16x32_bf16 v[48:51], v[156:159], v[164:167], v[48:51]
	v_mfma_f32_16x16x32_bf16 v[36:39], v[148:151], v[172:175], v[36:39]
	v_mfma_f32_16x16x32_bf16 v[32:35], v[156:159], v[172:175], v[32:35]
	s_waitcnt vmcnt(8)
	s_setprio 2
	s_barrier
	v_mfma_f32_16x16x32_bf16 v[20:23], v[148:151], v[180:183], v[20:23]
	v_mfma_f32_16x16x32_bf16 v[16:19], v[156:159], v[180:183], v[16:19]
	v_mfma_f32_16x16x32_bf16 v[4:7], v[148:151], v[204:207], v[4:7]
	v_mfma_f32_16x16x32_bf16 v[0:3], v[156:159], v[204:207], v[0:3]
	s_setprio 0
	s_add_i32 s64, s64, 2
	s_add_u32 s62, s62, 0x100
	s_addc_u32 s63, s63, 0
	s_cmp_gt_u32 s64, 41
	s_mov_b64 s[26:27], s[28:29]
.LBB0_866:
	ds_read_b128 v[120:123], v233
	ds_read_b128 v[124:127], v233 offset:1024
	ds_read_b128 v[136:139], v233 offset:2048
	ds_read_b128 v[140:143], v233 offset:3072
	ds_read_b128 v[144:147], v234
	ds_read_b128 v[148:151], v234 offset:1024
	ds_read_b128 v[152:155], v234 offset:2048
	ds_read_b128 v[156:159], v234 offset:3072
	s_add_u32 s28, s26, 0x100
	s_addc_u32 s29, s27, 0
	s_cmp_eq_u32 s64, 40
	s_cselect_b32 s37, s7, s29
	s_cselect_b32 s36, s6, s28
	s_cselect_b32 s31, s25, s63
	s_cselect_b32 s30, s24, s62
	v_lshl_add_u64 v[208:209], s[26:27], 0, v[192:193]
	s_add_i32 m0, s44, 0xc000
	ds_read_b128 v[160:163], v235
	ds_read_b128 v[164:167], v235 offset:1024
	ds_read_b128 v[168:171], v235 offset:2048
	ds_read_b128 v[172:175], v235 offset:3072
	ds_read_b128 v[176:179], v235 offset:4096
	ds_read_b128 v[180:183], v235 offset:5120
	ds_read_b128 v[200:203], v235 offset:6144
	ds_read_b128 v[204:207], v235 offset:7168
	global_load_lds_dwordx4 v[208:209], off
	s_add_i32 m0, s44, 0xe000
	v_lshl_add_u64 v[208:209], s[26:27], 0, v[194:195]
	global_load_lds_dwordx4 v[208:209], off
	s_cmp_eq_u32 s100, 0
	s_waitcnt lgkmcnt(0)
	s_cbranch_scc1 .Ldw_29
	s_waitcnt vmcnt(8)
.Ldw_29:
	s_barrier
	s_setprio 1
	v_mfma_f32_16x16x32_bf16 v[132:135], v[120:123], v[160:163], v[132:135]
	v_mfma_f32_16x16x32_bf16 v[128:131], v[136:139], v[160:163], v[128:131]
	v_mfma_f32_16x16x32_bf16 v[108:111], v[120:123], v[168:171], v[108:111]
	v_mfma_f32_16x16x32_bf16 v[104:107], v[136:139], v[168:171], v[104:107]
	v_mfma_f32_16x16x32_bf16 v[92:95], v[120:123], v[176:179], v[92:95]
	v_mfma_f32_16x16x32_bf16 v[88:91], v[136:139], v[176:179], v[88:91]
	v_mfma_f32_16x16x32_bf16 v[76:79], v[120:123], v[200:203], v[76:79]
	v_mfma_f32_16x16x32_bf16 v[72:75], v[136:139], v[200:203], v[72:75]
	v_mfma_f32_16x16x32_bf16 v[132:135], v[124:127], v[164:167], v[132:135]
	v_mfma_f32_16x16x32_bf16 v[128:131], v[140:143], v[164:167], v[128:131]
	v_mfma_f32_16x16x32_bf16 v[108:111], v[124:127], v[172:175], v[108:111]
	v_mfma_f32_16x16x32_bf16 v[104:107], v[140:143], v[172:175], v[104:107]
	v_mfma_f32_16x16x32_bf16 v[92:95], v[124:127], v[180:183], v[92:95]
	v_mfma_f32_16x16x32_bf16 v[88:91], v[140:143], v[180:183], v[88:91]
	v_mfma_f32_16x16x32_bf16 v[76:79], v[124:127], v[204:207], v[76:79]
	v_mfma_f32_16x16x32_bf16 v[72:75], v[140:143], v[204:207], v[72:75]
	s_setprio 0
	s_setprio 1
	v_mfma_f32_16x16x32_bf16 v[116:119], v[144:147], v[160:163], v[116:119]
	v_mfma_f32_16x16x32_bf16 v[112:115], v[152:155], v[160:163], v[112:115]
	v_mfma_f32_16x16x32_bf16 v[100:103], v[144:147], v[168:171], v[100:103]
	v_mfma_f32_16x16x32_bf16 v[96:99], v[152:155], v[168:171], v[96:99]
	v_mfma_f32_16x16x32_bf16 v[84:87], v[144:147], v[176:179], v[84:87]
	v_mfma_f32_16x16x32_bf16 v[80:83], v[152:155], v[176:179], v[80:83]
	v_mfma_f32_16x16x32_bf16 v[68:71], v[144:147], v[200:203], v[68:71]
	v_mfma_f32_16x16x32_bf16 v[64:67], v[152:155], v[200:203], v[64:67]
	v_mfma_f32_16x16x32_bf16 v[116:119], v[148:151], v[164:167], v[116:119]
	v_mfma_f32_16x16x32_bf16 v[112:115], v[156:159], v[164:167], v[112:115]
	v_mfma_f32_16x16x32_bf16 v[100:103], v[148:151], v[172:175], v[100:103]
	v_mfma_f32_16x16x32_bf16 v[96:99], v[156:159], v[172:175], v[96:99]
	s_waitcnt vmcnt(8)
	s_setprio 2
	s_barrier
	v_mfma_f32_16x16x32_bf16 v[84:87], v[148:151], v[180:183], v[84:87]
	v_mfma_f32_16x16x32_bf16 v[80:83], v[156:159], v[180:183], v[80:83]
	v_mfma_f32_16x16x32_bf16 v[68:71], v[148:151], v[204:207], v[68:71]
	v_mfma_f32_16x16x32_bf16 v[64:67], v[156:159], v[204:207], v[64:67]
	s_setprio 2
	s_add_i32 s26, s56, s43
	v_lshl_add_u64 v[208:209], s[30:31], 0, v[186:187]
	s_mov_b32 m0, s26
	ds_read_b128 v[160:163], v235 offset:16384
	ds_read_b128 v[164:167], v235 offset:17408
	ds_read_b128 v[168:171], v235 offset:18432
	ds_read_b128 v[172:175], v235 offset:19456
	ds_read_b128 v[176:179], v235 offset:20480
	ds_read_b128 v[180:183], v235 offset:21504
	ds_read_b128 v[200:203], v235 offset:22528
	ds_read_b128 v[204:207], v235 offset:23552
	global_load_lds_dwordx4 v[208:209], off
	s_add_i32 m0, s26, 0x2000
	s_add_u32 s26, s30, 0xb0000
	v_lshl_add_u64 v[210:211], s[30:31], 0, v[190:191]
	s_addc_u32 s27, s31, 0
	s_add_i32 s65, s57, s43
	global_load_lds_dwordx4 v[210:211], off
	v_lshl_add_u64 v[212:213], s[26:27], 0, v[186:187]
	s_mov_b32 m0, s65
	v_lshl_add_u64 v[214:215], s[36:37], 0, v[188:189]
	global_load_lds_dwordx4 v[212:213], off
	s_add_i32 m0, s65, 0x2000
	v_lshl_add_u64 v[212:213], s[26:27], 0, v[190:191]
	global_load_lds_dwordx4 v[212:213], off
	s_mov_b32 m0, s44
	v_lshl_add_u64 v[212:213], s[36:37], 0, v[184:185]
	global_load_lds_dwordx4 v[212:213], off
	s_mov_b32 m0, s45
	s_nop 0
	global_load_lds_dwordx4 v[214:215], off
	s_cmp_eq_u32 s100, 0
	s_waitcnt lgkmcnt(0)
	s_cbranch_scc1 .Ldw_30
	s_waitcnt vmcnt(8)
.Ldw_30:
	s_barrier
	s_setprio 1
	v_mfma_f32_16x16x32_bf16 v[60:63], v[120:123], v[160:163], v[60:63]
	v_mfma_f32_16x16x32_bf16 v[56:59], v[136:139], v[160:163], v[56:59]
	v_mfma_f32_16x16x32_bf16 v[44:47], v[120:123], v[168:171], v[44:47]
	v_mfma_f32_16x16x32_bf16 v[40:43], v[136:139], v[168:171], v[40:43]
	v_mfma_f32_16x16x32_bf16 v[28:31], v[120:123], v[176:179], v[28:31]
	v_mfma_f32_16x16x32_bf16 v[24:27], v[136:139], v[176:179], v[24:27]
	v_mfma_f32_16x16x32_bf16 v[12:15], v[120:123], v[200:203], v[12:15]
	v_mfma_f32_16x16x32_bf16 v[8:11], v[136:139], v[200:203], v[8:11]
	v_mfma_f32_16x16x32_bf16 v[60:63], v[124:127], v[164:167], v[60:63]
	v_mfma_f32_16x16x32_bf16 v[56:59], v[140:143], v[164:167], v[56:59]
	v_mfma_f32_16x16x32_bf16 v[44:47], v[124:127], v[172:175], v[44:47]
	v_mfma_f32_16x16x32_bf16 v[40:43], v[140:143], v[172:175], v[40:43]
	v_mfma_f32_16x16x32_bf16 v[28:31], v[124:127], v[180:183], v[28:31]
	v_mfma_f32_16x16x32_bf16 v[24:27], v[140:143], v[180:183], v[24:27]
	v_mfma_f32_16x16x32_bf16 v[12:15], v[124:127], v[204:207], v[12:15]
	v_mfma_f32_16x16x32_bf16 v[8:11], v[140:143], v[204:207], v[8:11]
	s_setprio 0
	s_setprio 1
	v_mfma_f32_16x16x32_bf16 v[52:55], v[144:147], v[160:163], v[52:55]
	v_mfma_f32_16x16x32_bf16 v[48:51], v[152:155], v[160:163], v[48:51]
	v_mfma_f32_16x16x32_bf16 v[36:39], v[144:147], v[168:171], v[36:39]
	v_mfma_f32_16x16x32_bf16 v[32:35], v[152:155], v[168:171], v[32:35]
	v_mfma_f32_16x16x32_bf16 v[20:23], v[144:147], v[176:179], v[20:23]
	v_mfma_f32_16x16x32_bf16 v[16:19], v[152:155], v[176:179], v[16:19]
	v_mfma_f32_16x16x32_bf16 v[4:7], v[144:147], v[200:203], v[4:7]
	v_mfma_f32_16x16x32_bf16 v[0:3], v[152:155], v[200:203], v[0:3]
	v_mfma_f32_16x16x32_bf16 v[52:55], v[148:151], v[164:167], v[52:55]
	v_mfma_f32_16x16x32_bf16 v[48:51], v[156:159], v[164:167], v[48:51]
	v_mfma_f32_16x16x32_bf16 v[36:39], v[148:151], v[172:175], v[36:39]
	v_mfma_f32_16x16x32_bf16 v[32:35], v[156:159], v[172:175], v[32:35]
	s_waitcnt vmcnt(8)
	s_setprio 2
	s_barrier
	v_mfma_f32_16x16x32_bf16 v[20:23], v[148:151], v[180:183], v[20:23]
	v_mfma_f32_16x16x32_bf16 v[16:19], v[156:159], v[180:183], v[16:19]
	v_mfma_f32_16x16x32_bf16 v[4:7], v[148:151], v[204:207], v[4:7]
	v_mfma_f32_16x16x32_bf16 v[0:3], v[156:159], v[204:207], v[0:3]
	s_setprio 0
	s_add_i32 s65, 0, 0x18000
	s_add_i32 s66, 0, 0x1c000
	v_add_u32_e32 v140, s65, v232
	v_add_u32_e32 v156, s66, v232
	ds_read_b128 v[120:123], v140
	ds_read_b128 v[124:127], v140 offset:1024
	ds_read_b128 v[136:139], v140 offset:2048
	ds_read_b128 v[140:143], v140 offset:3072
	ds_read_b128 v[144:147], v156
	ds_read_b128 v[148:151], v156 offset:1024
	ds_read_b128 v[152:155], v156 offset:2048
	ds_read_b128 v[156:159], v156 offset:3072
	s_add_u32 s26, s36, 0xb0000
	s_addc_u32 s27, s37, 0
	s_mov_b32 m0, s46
	v_lshl_add_u64 v[216:217], s[26:27], 0, v[184:185]
	ds_read_b128 v[160:163], v235 offset:32768
	ds_read_b128 v[164:167], v235 offset:33792
	ds_read_b128 v[168:171], v235 offset:34816
	ds_read_b128 v[172:175], v235 offset:35840
	ds_read_b128 v[176:179], v235 offset:36864
	ds_read_b128 v[180:183], v235 offset:37888
	ds_read_b128 v[200:203], v235 offset:38912
	ds_read_b128 v[204:207], v235 offset:39936
	global_load_lds_dwordx4 v[216:217], off
	s_mov_b32 m0, s47
	v_lshl_add_u64 v[216:217], s[26:27], 0, v[188:189]
	global_load_lds_dwordx4 v[216:217], off
	s_cmp_eq_u32 s100, 0
	s_waitcnt lgkmcnt(0)
	s_cbranch_scc1 .Ldw_31
	s_waitcnt vmcnt(8)

.Ldw_32:
	s_barrier
	s_setprio 1
	v_mfma_f32_16x16x32_bf16 v[60:63], v[120:123], v[160:163], v[60:63]
	v_mfma_f32_16x16x32_bf16 v[56:59], v[136:139], v[160:163], v[56:59]
	v_mfma_f32_16x16x32_bf16 v[44:47], v[120:123], v[168:171], v[44:47]
	v_mfma_f32_16x16x32_bf16 v[40:43], v[136:139], v[168:171], v[40:43]
	v_mfma_f32_16x16x32_bf16 v[28:31], v[120:123], v[176:179], v[28:31]
	v_mfma_f32_16x16x32_bf16 v[24:27], v[136:139], v[176:179], v[24:27]
	v_mfma_f32_16x16x32_bf16 v[12:15], v[120:123], v[200:203], v[12:15]
	v_mfma_f32_16x16x32_bf16 v[8:11], v[136:139], v[200:203], v[8:11]
	v_mfma_f32_16x16x32_bf16 v[60:63], v[124:127], v[164:167], v[60:63]
	v_mfma_f32_16x16x32_bf16 v[56:59], v[140:143], v[164:167], v[56:59]
	v_mfma_f32_16x16x32_bf16 v[44:47], v[124:127], v[172:175], v[44:47]
	v_mfma_f32_16x16x32_bf16 v[40:43], v[140:143], v[172:175], v[40:43]
	v_mfma_f32_16x16x32_bf16 v[28:31], v[124:127], v[180:183], v[28:31]
	v_mfma_f32_16x16x32_bf16 v[24:27], v[140:143], v[180:183], v[24:27]
	v_mfma_f32_16x16x32_bf16 v[12:15], v[124:127], v[204:207], v[12:15]
	v_mfma_f32_16x16x32_bf16 v[8:11], v[140:143], v[204:207], v[8:11]
	s_setprio 0
	s_setprio 1
	v_mfma_f32_16x16x32_bf16 v[52:55], v[144:147], v[160:163], v[52:55]
	v_mfma_f32_16x16x32_bf16 v[48:51], v[152:155], v[160:163], v[48:51]
	v_mfma_f32_16x16x32_bf16 v[36:39], v[144:147], v[168:171], v[36:39]
	v_mfma_f32_16x16x32_bf16 v[32:35], v[152:155], v[168:171], v[32:35]
	v_mfma_f32_16x16x32_bf16 v[20:23], v[144:147], v[176:179], v[20:23]
	v_mfma_f32_16x16x32_bf16 v[16:19], v[152:155], v[176:179], v[16:19]
	v_mfma_f32_16x16x32_bf16 v[4:7], v[144:147], v[200:203], v[4:7]
	v_mfma_f32_16x16x32_bf16 v[0:3], v[152:155], v[200:203], v[0:3]
	v_mfma_f32_16x16x32_bf16 v[52:55], v[148:151], v[164:167], v[52:55]
	v_mfma_f32_16x16x32_bf16 v[48:51], v[156:159], v[164:167], v[48:51]
	v_mfma_f32_16x16x32_bf16 v[36:39], v[148:151], v[172:175], v[36:39]
	v_mfma_f32_16x16x32_bf16 v[32:35], v[156:159], v[172:175], v[32:35]
	s_waitcnt vmcnt(8)
	s_setprio 2
	s_barrier
	v_mfma_f32_16x16x32_bf16 v[20:23], v[148:151], v[180:183], v[20:23]
	v_mfma_f32_16x16x32_bf16 v[16:19], v[156:159], v[180:183], v[16:19]
	v_mfma_f32_16x16x32_bf16 v[4:7], v[148:151], v[204:207], v[4:7]
	v_mfma_f32_16x16x32_bf16 v[0:3], v[156:159], v[204:207], v[0:3]
	s_setprio 0
	s_add_i32 s64, s64, 2
	s_add_u32 s62, s62, 0x100
	s_addc_u32 s63, s63, 0
	s_cmp_gt_u32 s64, 41
	s_mov_b64 s[26:27], s[28:29]
	s_cbranch_scc0 .LBB0_866

.LBB0_951:
	s_ashr_i32 s27, s26, 31
	s_lshl_b64 s[30:31], s[26:27], 19
	s_add_u32 s30, s47, s30
	s_addc_u32 s31, s48, s31
	s_and_b64 s[36:37], s[4:5], exec
	s_cselect_b32 s27, s31, s7
	s_cselect_b32 s39, s30, s6
	s_ashr_i32 s29, s28, 31
	s_lshl_b64 s[36:37], s[28:29], 19
	s_add_u32 s36, s49, s36
	s_addc_u32 s37, s50, s37
	s_and_b64 s[44:45], s[4:5], exec
	s_cselect_b32 s29, s37, s41
	s_cselect_b32 s43, s36, s40
	s_add_u32 s6, s6, 0x40080
	s_addc_u32 s7, s7, 0
	s_add_u32 s71, s40, 0x100
	s_addc_u32 s72, s41, 0
	s_mov_b32 s73, -2
	ds_read_b128 v[144:147], v179
	ds_read_b128 v[148:151], v179 offset:1024
	ds_read_b128 v[152:155], v179 offset:2048
	ds_read_b128 v[156:159], v179 offset:3072
	ds_read_b128 v[160:163], v180
	ds_read_b128 v[164:167], v180 offset:1024
	ds_read_b128 v[168:171], v180 offset:2048
	ds_read_b128 v[172:175], v180 offset:3072
	s_add_u32 s40, s6, 0xfffc0080
	s_addc_u32 s41, s7, -1
	s_cmp_eq_u32 s73, 12
	s_cselect_b32 s45, s27, s41
	s_cselect_b32 s44, s39, s40
	s_cselect_b32 s41, s29, s72
	s_cselect_b32 s40, s43, s71
	v_lshl_add_u64 v[176:177], s[6:7], 0, v[136:137]
	s_add_i32 m0, s54, 0xc000
	ds_read_b128 v[184:187], v181
	ds_read_b128 v[188:191], v181 offset:1024
	ds_read_b128 v[192:195], v181 offset:2048
	ds_read_b128 v[196:199], v181 offset:3072
	ds_read_b128 v[200:203], v181 offset:4096
	ds_read_b128 v[204:207], v181 offset:5120
	ds_read_b128 v[208:211], v181 offset:6144
	ds_read_b128 v[212:215], v181 offset:7168
	global_load_lds_dwordx4 v[176:177], off
	s_add_i32 m0, s54, 0xe000
	v_lshl_add_u64 v[176:177], s[6:7], 0, v[138:139]
	global_load_lds_dwordx4 v[176:177], off
	s_cmp_eq_u32 s100, 0
	s_waitcnt lgkmcnt(0)
	s_cbranch_scc1 .Ldw_33
	s_waitcnt vmcnt(8)
.Ldw_33:
	s_barrier
	s_setprio 1
	v_mfma_f32_16x16x32_bf16 v[124:127], v[144:147], v[184:187], 0
	v_mfma_f32_16x16x32_bf16 v[120:123], v[152:155], v[184:187], 0
	v_mfma_f32_16x16x32_bf16 v[108:111], v[144:147], v[192:195], 0
	v_mfma_f32_16x16x32_bf16 v[104:107], v[152:155], v[192:195], 0
	v_mfma_f32_16x16x32_bf16 v[92:95], v[144:147], v[200:203], 0
	v_mfma_f32_16x16x32_bf16 v[88:91], v[152:155], v[200:203], 0
	v_mfma_f32_16x16x32_bf16 v[76:79], v[144:147], v[208:211], 0
	v_mfma_f32_16x16x32_bf16 v[72:75], v[152:155], v[208:211], 0
	v_mfma_f32_16x16x32_bf16 v[124:127], v[148:151], v[188:191], v[124:127]
	v_mfma_f32_16x16x32_bf16 v[120:123], v[156:159], v[188:191], v[120:123]
	v_mfma_f32_16x16x32_bf16 v[108:111], v[148:151], v[196:199], v[108:111]
	v_mfma_f32_16x16x32_bf16 v[104:107], v[156:159], v[196:199], v[104:107]
	v_mfma_f32_16x16x32_bf16 v[92:95], v[148:151], v[204:207], v[92:95]
	v_mfma_f32_16x16x32_bf16 v[88:91], v[156:159], v[204:207], v[88:91]
	v_mfma_f32_16x16x32_bf16 v[76:79], v[148:151], v[212:215], v[76:79]
	v_mfma_f32_16x16x32_bf16 v[72:75], v[156:159], v[212:215], v[72:75]
	s_setprio 0
	s_setprio 1
	v_mfma_f32_16x16x32_bf16 v[116:119], v[160:163], v[184:187], 0
	v_mfma_f32_16x16x32_bf16 v[112:115], v[168:171], v[184:187], 0
	v_mfma_f32_16x16x32_bf16 v[100:103], v[160:163], v[192:195], 0
	v_mfma_f32_16x16x32_bf16 v[96:99], v[168:171], v[192:195], 0
	v_mfma_f32_16x16x32_bf16 v[84:87], v[160:163], v[200:203], 0
	v_mfma_f32_16x16x32_bf16 v[80:83], v[168:171], v[200:203], 0
	v_mfma_f32_16x16x32_bf16 v[68:71], v[160:163], v[208:211], 0
	v_mfma_f32_16x16x32_bf16 v[64:67], v[168:171], v[208:211], 0
	v_mfma_f32_16x16x32_bf16 v[116:119], v[164:167], v[188:191], v[116:119]
	v_mfma_f32_16x16x32_bf16 v[112:115], v[172:175], v[188:191], v[112:115]
	v_mfma_f32_16x16x32_bf16 v[100:103], v[164:167], v[196:199], v[100:103]
	v_mfma_f32_16x16x32_bf16 v[96:99], v[172:175], v[196:199], v[96:99]
	s_waitcnt vmcnt(8)
	s_setprio 2
	s_barrier
	v_mfma_f32_16x16x32_bf16 v[84:87], v[164:167], v[204:207], v[84:87]
	v_mfma_f32_16x16x32_bf16 v[80:83], v[172:175], v[204:207], v[80:83]
	v_mfma_f32_16x16x32_bf16 v[68:71], v[164:167], v[212:215], v[68:71]
	v_mfma_f32_16x16x32_bf16 v[64:67], v[172:175], v[212:215], v[64:67]
	s_setprio 2
	s_add_i32 s74, s69, s51
	v_lshl_add_u64 v[176:177], s[40:41], 0, v[130:131]
	s_mov_b32 m0, s74
	ds_read_b128 v[184:187], v181 offset:16384
	ds_read_b128 v[188:191], v181 offset:17408
	ds_read_b128 v[192:195], v181 offset:18432
	ds_read_b128 v[196:199], v181 offset:19456
	ds_read_b128 v[200:203], v181 offset:20480
	ds_read_b128 v[204:207], v181 offset:21504
	ds_read_b128 v[208:211], v181 offset:22528
	ds_read_b128 v[212:215], v181 offset:23552
	global_load_lds_dwordx4 v[176:177], off
	s_add_i32 m0, s74, 0x2000
	s_add_u32 s74, s40, 0x40000
	v_lshl_add_u64 v[216:217], s[40:41], 0, v[134:135]
	s_addc_u32 s75, s41, 0
	s_add_i32 s76, s70, s51
	global_load_lds_dwordx4 v[216:217], off
	v_lshl_add_u64 v[218:219], s[74:75], 0, v[130:131]
	s_mov_b32 m0, s76
	v_lshl_add_u64 v[220:221], s[44:45], 0, v[132:133]
	global_load_lds_dwordx4 v[218:219], off
	s_add_i32 m0, s76, 0x2000
	v_lshl_add_u64 v[218:219], s[74:75], 0, v[134:135]
	global_load_lds_dwordx4 v[218:219], off
	s_mov_b32 m0, s54
	v_lshl_add_u64 v[218:219], s[44:45], 0, v[128:129]
	global_load_lds_dwordx4 v[218:219], off
	s_mov_b32 m0, s55
	s_nop 0
	global_load_lds_dwordx4 v[220:221], off
	s_cmp_eq_u32 s100, 0
	s_waitcnt lgkmcnt(0)
	s_cbranch_scc1 .Ldw_34
	s_waitcnt vmcnt(8)
.Ldw_34:
	s_barrier
	s_setprio 1
	v_mfma_f32_16x16x32_bf16 v[60:63], v[144:147], v[184:187], 0
	v_mfma_f32_16x16x32_bf16 v[56:59], v[152:155], v[184:187], 0
	v_mfma_f32_16x16x32_bf16 v[44:47], v[144:147], v[192:195], 0
	v_mfma_f32_16x16x32_bf16 v[40:43], v[152:155], v[192:195], 0
	v_mfma_f32_16x16x32_bf16 v[28:31], v[144:147], v[200:203], 0
	v_mfma_f32_16x16x32_bf16 v[24:27], v[152:155], v[200:203], 0
	v_mfma_f32_16x16x32_bf16 v[12:15], v[144:147], v[208:211], 0
	v_mfma_f32_16x16x32_bf16 v[8:11], v[152:155], v[208:211], 0
	v_mfma_f32_16x16x32_bf16 v[60:63], v[148:151], v[188:191], v[60:63]
	v_mfma_f32_16x16x32_bf16 v[56:59], v[156:159], v[188:191], v[56:59]
	v_mfma_f32_16x16x32_bf16 v[44:47], v[148:151], v[196:199], v[44:47]
	v_mfma_f32_16x16x32_bf16 v[40:43], v[156:159], v[196:199], v[40:43]
	v_mfma_f32_16x16x32_bf16 v[28:31], v[148:151], v[204:207], v[28:31]
	v_mfma_f32_16x16x32_bf16 v[24:27], v[156:159], v[204:207], v[24:27]
	v_mfma_f32_16x16x32_bf16 v[12:15], v[148:151], v[212:215], v[12:15]
	v_mfma_f32_16x16x32_bf16 v[8:11], v[156:159], v[212:215], v[8:11]
	s_setprio 0
	s_setprio 1
	v_mfma_f32_16x16x32_bf16 v[52:55], v[160:163], v[184:187], 0
	v_mfma_f32_16x16x32_bf16 v[48:51], v[168:171], v[184:187], 0
	v_mfma_f32_16x16x32_bf16 v[36:39], v[160:163], v[192:195], 0
	v_mfma_f32_16x16x32_bf16 v[32:35], v[168:171], v[192:195], 0
	v_mfma_f32_16x16x32_bf16 v[20:23], v[160:163], v[200:203], 0
	v_mfma_f32_16x16x32_bf16 v[16:19], v[168:171], v[200:203], 0
	v_mfma_f32_16x16x32_bf16 v[4:7], v[160:163], v[208:211], 0
	v_mfma_f32_16x16x32_bf16 v[0:3], v[168:171], v[208:211], 0
	v_mfma_f32_16x16x32_bf16 v[52:55], v[164:167], v[188:191], v[52:55]
	v_mfma_f32_16x16x32_bf16 v[48:51], v[172:175], v[188:191], v[48:51]
	v_mfma_f32_16x16x32_bf16 v[36:39], v[164:167], v[196:199], v[36:39]
	v_mfma_f32_16x16x32_bf16 v[32:35], v[172:175], v[196:199], v[32:35]
	s_waitcnt vmcnt(8)
	s_setprio 2
	s_barrier
	v_mfma_f32_16x16x32_bf16 v[20:23], v[164:167], v[204:207], v[20:23]
	v_mfma_f32_16x16x32_bf16 v[16:19], v[172:175], v[204:207], v[16:19]
	v_mfma_f32_16x16x32_bf16 v[4:7], v[164:167], v[212:215], v[4:7]
	v_mfma_f32_16x16x32_bf16 v[0:3], v[172:175], v[212:215], v[0:3]
	s_setprio 0
	s_add_i32 s74, 0, 0x18000
	s_add_i32 s75, 0, 0x1c000
	v_add_u32_e32 v156, s74, v178
	v_add_u32_e32 v172, s75, v178
	ds_read_b128 v[144:147], v156
	ds_read_b128 v[148:151], v156 offset:1024
	ds_read_b128 v[152:155], v156 offset:2048
	ds_read_b128 v[156:159], v156 offset:3072
	ds_read_b128 v[160:163], v172
	ds_read_b128 v[164:167], v172 offset:1024
	ds_read_b128 v[168:171], v172 offset:2048
	ds_read_b128 v[172:175], v172 offset:3072
	s_add_u32 s44, s44, 0x40000
	s_addc_u32 s45, s45, 0
	s_mov_b32 m0, s56
	v_lshl_add_u64 v[222:223], s[44:45], 0, v[128:129]
	ds_read_b128 v[184:187], v181 offset:32768
	ds_read_b128 v[188:191], v181 offset:33792
	ds_read_b128 v[192:195], v181 offset:34816
	ds_read_b128 v[196:199], v181 offset:35840
	ds_read_b128 v[200:203], v181 offset:36864
	ds_read_b128 v[204:207], v181 offset:37888
	ds_read_b128 v[208:211], v181 offset:38912
	ds_read_b128 v[212:215], v181 offset:39936
	global_load_lds_dwordx4 v[222:223], off
	s_mov_b32 m0, s57
	v_lshl_add_u64 v[222:223], s[44:45], 0, v[132:133]
	global_load_lds_dwordx4 v[222:223], off
	s_cmp_eq_u32 s100, 0
	s_waitcnt lgkmcnt(0)
	s_cbranch_scc1 .Ldw_35
	s_waitcnt vmcnt(8)
.Ldw_35:
	s_barrier
	s_setprio 1
	v_mfma_f32_16x16x32_bf16 v[124:127], v[144:147], v[184:187], v[124:127]
	v_mfma_f32_16x16x32_bf16 v[120:123], v[152:155], v[184:187], v[120:123]
	v_mfma_f32_16x16x32_bf16 v[108:111], v[144:147], v[192:195], v[108:111]
	v_mfma_f32_16x16x32_bf16 v[104:107], v[152:155], v[192:195], v[104:107]
	v_mfma_f32_16x16x32_bf16 v[92:95], v[144:147], v[200:203], v[92:95]
	v_mfma_f32_16x16x32_bf16 v[88:91], v[152:155], v[200:203], v[88:91]
	v_mfma_f32_16x16x32_bf16 v[76:79], v[144:147], v[208:211], v[76:79]
	v_mfma_f32_16x16x32_bf16 v[72:75], v[152:155], v[208:211], v[72:75]
	v_mfma_f32_16x16x32_bf16 v[124:127], v[148:151], v[188:191], v[124:127]
	v_mfma_f32_16x16x32_bf16 v[120:123], v[156:159], v[188:191], v[120:123]
	v_mfma_f32_16x16x32_bf16 v[108:111], v[148:151], v[196:199], v[108:111]
	v_mfma_f32_16x16x32_bf16 v[104:107], v[156:159], v[196:199], v[104:107]
	v_mfma_f32_16x16x32_bf16 v[92:95], v[148:151], v[204:207], v[92:95]
	v_mfma_f32_16x16x32_bf16 v[88:91], v[156:159], v[204:207], v[88:91]
	v_mfma_f32_16x16x32_bf16 v[76:79], v[148:151], v[212:215], v[76:79]
	v_mfma_f32_16x16x32_bf16 v[72:75], v[156:159], v[212:215], v[72:75]
	s_setprio 0
	s_setprio 1
	v_mfma_f32_16x16x32_bf16 v[116:119], v[160:163], v[184:187], v[116:119]
	v_mfma_f32_16x16x32_bf16 v[112:115], v[168:171], v[184:187], v[112:115]
	v_mfma_f32_16x16x32_bf16 v[100:103], v[160:163], v[192:195], v[100:103]
	v_mfma_f32_16x16x32_bf16 v[96:99], v[168:171], v[192:195], v[96:99]
	v_mfma_f32_16x16x32_bf16 v[84:87], v[160:163], v[200:203], v[84:87]
	v_mfma_f32_16x16x32_bf16 v[80:83], v[168:171], v[200:203], v[80:83]
	v_mfma_f32_16x16x32_bf16 v[68:71], v[160:163], v[208:211], v[68:71]
	v_mfma_f32_16x16x32_bf16 v[64:67], v[168:171], v[208:211], v[64:67]
	v_mfma_f32_16x16x32_bf16 v[116:119], v[164:167], v[188:191], v[116:119]
	v_mfma_f32_16x16x32_bf16 v[112:115], v[172:175], v[188:191], v[112:115]
	v_mfma_f32_16x16x32_bf16 v[100:103], v[164:167], v[196:199], v[100:103]
	v_mfma_f32_16x16x32_bf16 v[96:99], v[172:175], v[196:199], v[96:99]
	s_waitcnt vmcnt(8)
	s_setprio 2
	s_barrier
	v_mfma_f32_16x16x32_bf16 v[84:87], v[164:167], v[204:207], v[84:87]
	v_mfma_f32_16x16x32_bf16 v[80:83], v[172:175], v[204:207], v[80:83]
	v_mfma_f32_16x16x32_bf16 v[68:71], v[164:167], v[212:215], v[68:71]
	v_mfma_f32_16x16x32_bf16 v[64:67], v[172:175], v[212:215], v[64:67]
	s_setprio 2
	s_add_i32 s44, s74, s51
	v_lshl_add_u64 v[176:177], v[176:177], 0, s[22:23]
	s_mov_b32 m0, s44
	ds_read_b128 v[184:187], v181 offset:49152
	ds_read_b128 v[188:191], v181 offset:50176
	ds_read_b128 v[192:195], v181 offset:51200
	ds_read_b128 v[196:199], v181 offset:52224
	ds_read_b128 v[200:203], v181 offset:53248
	ds_read_b128 v[204:207], v181 offset:54272
	ds_read_b128 v[208:211], v181 offset:55296
	ds_read_b128 v[212:215], v181 offset:56320
	global_load_lds_dwordx4 v[176:177], off
	s_add_i32 m0, s44, 0x2000
	s_add_u32 s40, s40, 0x40080
	v_lshl_add_u64 v[176:177], v[216:217], 0, s[22:23]
	s_addc_u32 s41, s41, 0
	s_add_i32 s44, s75, s51
	global_load_lds_dwordx4 v[176:177], off
	s_mov_b32 m0, s44
	v_lshl_add_u64 v[176:177], s[40:41], 0, v[130:131]
	global_load_lds_dwordx4 v[176:177], off
	s_add_i32 m0, s44, 0x2000
	v_lshl_add_u64 v[176:177], s[40:41], 0, v[134:135]
	global_load_lds_dwordx4 v[176:177], off
	s_mov_b32 m0, s64
	v_lshl_add_u64 v[176:177], v[218:219], 0, s[22:23]
	global_load_lds_dwordx4 v[176:177], off
	s_mov_b32 m0, s65
	v_lshl_add_u64 v[176:177], v[220:221], 0, s[22:23]
	global_load_lds_dwordx4 v[176:177], off
	s_cmp_eq_u32 s100, 0
	s_waitcnt lgkmcnt(0)
	s_cbranch_scc1 .Ldw_36
	s_waitcnt vmcnt(8)
.Ldw_36:
	s_barrier
	s_setprio 1
	v_mfma_f32_16x16x32_bf16 v[60:63], v[144:147], v[184:187], v[60:63]
	v_mfma_f32_16x16x32_bf16 v[56:59], v[152:155], v[184:187], v[56:59]
	v_mfma_f32_16x16x32_bf16 v[44:47], v[144:147], v[192:195], v[44:47]
	v_mfma_f32_16x16x32_bf16 v[40:43], v[152:155], v[192:195], v[40:43]
	v_mfma_f32_16x16x32_bf16 v[28:31], v[144:147], v[200:203], v[28:31]
	v_mfma_f32_16x16x32_bf16 v[24:27], v[152:155], v[200:203], v[24:27]
	v_mfma_f32_16x16x32_bf16 v[12:15], v[144:147], v[208:211], v[12:15]
	v_mfma_f32_16x16x32_bf16 v[8:11], v[152:155], v[208:211], v[8:11]
	v_mfma_f32_16x16x32_bf16 v[60:63], v[148:151], v[188:191], v[60:63]
	v_mfma_f32_16x16x32_bf16 v[56:59], v[156:159], v[188:191], v[56:59]
	v_mfma_f32_16x16x32_bf16 v[44:47], v[148:151], v[196:199], v[44:47]
	v_mfma_f32_16x16x32_bf16 v[40:43], v[156:159], v[196:199], v[40:43]
	v_mfma_f32_16x16x32_bf16 v[28:31], v[148:151], v[204:207], v[28:31]
	v_mfma_f32_16x16x32_bf16 v[24:27], v[156:159], v[204:207], v[24:27]
	v_mfma_f32_16x16x32_bf16 v[12:15], v[148:151], v[212:215], v[12:15]
	v_mfma_f32_16x16x32_bf16 v[8:11], v[156:159], v[212:215], v[8:11]
	s_setprio 0
	s_setprio 1
	v_mfma_f32_16x16x32_bf16 v[52:55], v[160:163], v[184:187], v[52:55]
	v_mfma_f32_16x16x32_bf16 v[48:51], v[168:171], v[184:187], v[48:51]
	v_mfma_f32_16x16x32_bf16 v[36:39], v[160:163], v[192:195], v[36:39]
	v_mfma_f32_16x16x32_bf16 v[32:35], v[168:171], v[192:195], v[32:35]
	v_mfma_f32_16x16x32_bf16 v[20:23], v[160:163], v[200:203], v[20:23]
	v_mfma_f32_16x16x32_bf16 v[16:19], v[168:171], v[200:203], v[16:19]
	v_mfma_f32_16x16x32_bf16 v[4:7], v[160:163], v[208:211], v[4:7]
	v_mfma_f32_16x16x32_bf16 v[0:3], v[168:171], v[208:211], v[0:3]
	v_mfma_f32_16x16x32_bf16 v[52:55], v[164:167], v[188:191], v[52:55]
	v_mfma_f32_16x16x32_bf16 v[48:51], v[172:175], v[188:191], v[48:51]
	v_mfma_f32_16x16x32_bf16 v[36:39], v[164:167], v[196:199], v[36:39]
	v_mfma_f32_16x16x32_bf16 v[32:35], v[172:175], v[196:199], v[32:35]
	s_waitcnt vmcnt(8)
	s_setprio 2
	s_barrier
	v_mfma_f32_16x16x32_bf16 v[20:23], v[164:167], v[204:207], v[20:23]
	v_mfma_f32_16x16x32_bf16 v[16:19], v[172:175], v[204:207], v[16:19]
	v_mfma_f32_16x16x32_bf16 v[4:7], v[164:167], v[212:215], v[4:7]
	v_mfma_f32_16x16x32_bf16 v[0:3], v[172:175], v[212:215], v[0:3]
	s_setprio 0
	s_add_i32 s73, s73, 2
	s_add_u32 s6, s6, 0x100
	s_addc_u32 s7, s7, 0
	s_add_u32 s71, s71, 0x100
	s_addc_u32 s72, s72, 0
	s_cmp_gt_u32 s73, 13
.LBB0_952:
	ds_read_b128 v[144:147], v179
	ds_read_b128 v[148:151], v179 offset:1024
	ds_read_b128 v[152:155], v179 offset:2048
	ds_read_b128 v[156:159], v179 offset:3072
	ds_read_b128 v[160:163], v180
	ds_read_b128 v[164:167], v180 offset:1024
	ds_read_b128 v[168:171], v180 offset:2048
	ds_read_b128 v[172:175], v180 offset:3072
	s_add_u32 s40, s6, 0xfffc0080
	s_addc_u32 s41, s7, -1
	s_cmp_eq_u32 s73, 12
	s_cselect_b32 s45, s27, s41
	s_cselect_b32 s44, s39, s40
	s_cselect_b32 s41, s29, s72
	s_cselect_b32 s40, s43, s71
	v_lshl_add_u64 v[176:177], s[6:7], 0, v[136:137]
	s_add_i32 m0, s54, 0xc000
	ds_read_b128 v[184:187], v181
	ds_read_b128 v[188:191], v181 offset:1024
	ds_read_b128 v[192:195], v181 offset:2048
	ds_read_b128 v[196:199], v181 offset:3072
	ds_read_b128 v[200:203], v181 offset:4096
	ds_read_b128 v[204:207], v181 offset:5120
	ds_read_b128 v[208:211], v181 offset:6144
	ds_read_b128 v[212:215], v181 offset:7168
	global_load_lds_dwordx4 v[176:177], off
	s_add_i32 m0, s54, 0xe000
	v_lshl_add_u64 v[176:177], s[6:7], 0, v[138:139]
	global_load_lds_dwordx4 v[176:177], off
	s_cmp_eq_u32 s100, 0
	s_waitcnt lgkmcnt(0)
	s_cbranch_scc1 .Ldw_37
	s_waitcnt vmcnt(8)
.Ldw_37:
	s_barrier
	s_setprio 1
	v_mfma_f32_16x16x32_bf16 v[124:127], v[144:147], v[184:187], v[124:127]
	v_mfma_f32_16x16x32_bf16 v[120:123], v[152:155], v[184:187], v[120:123]
	v_mfma_f32_16x16x32_bf16 v[108:111], v[144:147], v[192:195], v[108:111]
	v_mfma_f32_16x16x32_bf16 v[104:107], v[152:155], v[192:195], v[104:107]
	v_mfma_f32_16x16x32_bf16 v[92:95], v[144:147], v[200:203], v[92:95]
	v_mfma_f32_16x16x32_bf16 v[88:91], v[152:155], v[200:203], v[88:91]
	v_mfma_f32_16x16x32_bf16 v[76:79], v[144:147], v[208:211], v[76:79]
	v_mfma_f32_16x16x32_bf16 v[72:75], v[152:155], v[208:211], v[72:75]
	v_mfma_f32_16x16x32_bf16 v[124:127], v[148:151], v[188:191], v[124:127]
	v_mfma_f32_16x16x32_bf16 v[120:123], v[156:159], v[188:191], v[120:123]
	v_mfma_f32_16x16x32_bf16 v[108:111], v[148:151], v[196:199], v[108:111]
	v_mfma_f32_16x16x32_bf16 v[104:107], v[156:159], v[196:199], v[104:107]
	v_mfma_f32_16x16x32_bf16 v[92:95], v[148:151], v[204:207], v[92:95]
	v_mfma_f32_16x16x32_bf16 v[88:91], v[156:159], v[204:207], v[88:91]
	v_mfma_f32_16x16x32_bf16 v[76:79], v[148:151], v[212:215], v[76:79]
	v_mfma_f32_16x16x32_bf16 v[72:75], v[156:159], v[212:215], v[72:75]
	s_setprio 0
	s_setprio 1
	v_mfma_f32_16x16x32_bf16 v[116:119], v[160:163], v[184:187], v[116:119]
	v_mfma_f32_16x16x32_bf16 v[112:115], v[168:171], v[184:187], v[112:115]
	v_mfma_f32_16x16x32_bf16 v[100:103], v[160:163], v[192:195], v[100:103]
	v_mfma_f32_16x16x32_bf16 v[96:99], v[168:171], v[192:195], v[96:99]
	v_mfma_f32_16x16x32_bf16 v[84:87], v[160:163], v[200:203], v[84:87]
	v_mfma_f32_16x16x32_bf16 v[80:83], v[168:171], v[200:203], v[80:83]
	v_mfma_f32_16x16x32_bf16 v[68:71], v[160:163], v[208:211], v[68:71]
	v_mfma_f32_16x16x32_bf16 v[64:67], v[168:171], v[208:211], v[64:67]
	v_mfma_f32_16x16x32_bf16 v[116:119], v[164:167], v[188:191], v[116:119]
	v_mfma_f32_16x16x32_bf16 v[112:115], v[172:175], v[188:191], v[112:115]
	v_mfma_f32_16x16x32_bf16 v[100:103], v[164:167], v[196:199], v[100:103]
	v_mfma_f32_16x16x32_bf16 v[96:99], v[172:175], v[196:199], v[96:99]
	s_waitcnt vmcnt(8)
	s_setprio 2
	s_barrier
	v_mfma_f32_16x16x32_bf16 v[84:87], v[164:167], v[204:207], v[84:87]
	v_mfma_f32_16x16x32_bf16 v[80:83], v[172:175], v[204:207], v[80:83]
	v_mfma_f32_16x16x32_bf16 v[68:71], v[164:167], v[212:215], v[68:71]
	v_mfma_f32_16x16x32_bf16 v[64:67], v[172:175], v[212:215], v[64:67]
	s_setprio 2
	s_add_i32 s74, s69, s51
	v_lshl_add_u64 v[176:177], s[40:41], 0, v[130:131]
	s_mov_b32 m0, s74
	ds_read_b128 v[184:187], v181 offset:16384
	ds_read_b128 v[188:191], v181 offset:17408
	ds_read_b128 v[192:195], v181 offset:18432
	ds_read_b128 v[196:199], v181 offset:19456
	ds_read_b128 v[200:203], v181 offset:20480
	ds_read_b128 v[204:207], v181 offset:21504
	ds_read_b128 v[208:211], v181 offset:22528
	ds_read_b128 v[212:215], v181 offset:23552
	global_load_lds_dwordx4 v[176:177], off
	s_add_i32 m0, s74, 0x2000
	s_add_u32 s74, s40, 0x40000
	v_lshl_add_u64 v[216:217], s[40:41], 0, v[134:135]
	s_addc_u32 s75, s41, 0
	s_add_i32 s76, s70, s51
	global_load_lds_dwordx4 v[216:217], off
	v_lshl_add_u64 v[218:219], s[74:75], 0, v[130:131]
	s_mov_b32 m0, s76
	v_lshl_add_u64 v[220:221], s[44:45], 0, v[132:133]
	global_load_lds_dwordx4 v[218:219], off
	s_add_i32 m0, s76, 0x2000
	v_lshl_add_u64 v[218:219], s[74:75], 0, v[134:135]
	global_load_lds_dwordx4 v[218:219], off
	s_mov_b32 m0, s54
	v_lshl_add_u64 v[218:219], s[44:45], 0, v[128:129]
	global_load_lds_dwordx4 v[218:219], off
	s_mov_b32 m0, s55
	s_nop 0
	global_load_lds_dwordx4 v[220:221], off
	s_cmp_eq_u32 s100, 0
	s_waitcnt lgkmcnt(0)
	s_cbranch_scc1 .Ldw_38
	s_waitcnt vmcnt(8)
.Ldw_38:
	s_barrier
	s_setprio 1
	v_mfma_f32_16x16x32_bf16 v[60:63], v[144:147], v[184:187], v[60:63]
	v_mfma_f32_16x16x32_bf16 v[56:59], v[152:155], v[184:187], v[56:59]
	v_mfma_f32_16x16x32_bf16 v[44:47], v[144:147], v[192:195], v[44:47]
	v_mfma_f32_16x16x32_bf16 v[40:43], v[152:155], v[192:195], v[40:43]
	v_mfma_f32_16x16x32_bf16 v[28:31], v[144:147], v[200:203], v[28:31]
	v_mfma_f32_16x16x32_bf16 v[24:27], v[152:155], v[200:203], v[24:27]
	v_mfma_f32_16x16x32_bf16 v[12:15], v[144:147], v[208:211], v[12:15]
	v_mfma_f32_16x16x32_bf16 v[8:11], v[152:155], v[208:211], v[8:11]
	v_mfma_f32_16x16x32_bf16 v[60:63], v[148:151], v[188:191], v[60:63]
	v_mfma_f32_16x16x32_bf16 v[56:59], v[156:159], v[188:191], v[56:59]
	v_mfma_f32_16x16x32_bf16 v[44:47], v[148:151], v[196:199], v[44:47]
	v_mfma_f32_16x16x32_bf16 v[40:43], v[156:159], v[196:199], v[40:43]
	v_mfma_f32_16x16x32_bf16 v[28:31], v[148:151], v[204:207], v[28:31]
	v_mfma_f32_16x16x32_bf16 v[24:27], v[156:159], v[204:207], v[24:27]
	v_mfma_f32_16x16x32_bf16 v[12:15], v[148:151], v[212:215], v[12:15]
	v_mfma_f32_16x16x32_bf16 v[8:11], v[156:159], v[212:215], v[8:11]
	s_setprio 0
	s_setprio 1
	v_mfma_f32_16x16x32_bf16 v[52:55], v[160:163], v[184:187], v[52:55]
	v_mfma_f32_16x16x32_bf16 v[48:51], v[168:171], v[184:187], v[48:51]
	v_mfma_f32_16x16x32_bf16 v[36:39], v[160:163], v[192:195], v[36:39]
	v_mfma_f32_16x16x32_bf16 v[32:35], v[168:171], v[192:195], v[32:35]
	v_mfma_f32_16x16x32_bf16 v[20:23], v[160:163], v[200:203], v[20:23]
	v_mfma_f32_16x16x32_bf16 v[16:19], v[168:171], v[200:203], v[16:19]
	v_mfma_f32_16x16x32_bf16 v[4:7], v[160:163], v[208:211], v[4:7]
	v_mfma_f32_16x16x32_bf16 v[0:3], v[168:171], v[208:211], v[0:3]
	v_mfma_f32_16x16x32_bf16 v[52:55], v[164:167], v[188:191], v[52:55]
	v_mfma_f32_16x16x32_bf16 v[48:51], v[172:175], v[188:191], v[48:51]
	v_mfma_f32_16x16x32_bf16 v[36:39], v[164:167], v[196:199], v[36:39]
	v_mfma_f32_16x16x32_bf16 v[32:35], v[172:175], v[196:199], v[32:35]
	s_waitcnt vmcnt(8)
	s_setprio 2
	s_barrier
	v_mfma_f32_16x16x32_bf16 v[20:23], v[164:167], v[204:207], v[20:23]
	v_mfma_f32_16x16x32_bf16 v[16:19], v[172:175], v[204:207], v[16:19]
	v_mfma_f32_16x16x32_bf16 v[4:7], v[164:167], v[212:215], v[4:7]
	v_mfma_f32_16x16x32_bf16 v[0:3], v[172:175], v[212:215], v[0:3]
	s_setprio 0
	s_add_i32 s74, 0, 0x18000
	s_add_i32 s75, 0, 0x1c000
	v_add_u32_e32 v156, s74, v178
	v_add_u32_e32 v172, s75, v178
	ds_read_b128 v[144:147], v156
	ds_read_b128 v[148:151], v156 offset:1024
	ds_read_b128 v[152:155], v156 offset:2048
	ds_read_b128 v[156:159], v156 offset:3072
	ds_read_b128 v[160:163], v172
	ds_read_b128 v[164:167], v172 offset:1024
	ds_read_b128 v[168:171], v172 offset:2048
	ds_read_b128 v[172:175], v172 offset:3072
	s_add_u32 s44, s44, 0x40000
	s_addc_u32 s45, s45, 0
	s_mov_b32 m0, s56
	v_lshl_add_u64 v[222:223], s[44:45], 0, v[128:129]
	ds_read_b128 v[184:187], v181 offset:32768
	ds_read_b128 v[188:191], v181 offset:33792
	ds_read_b128 v[192:195], v181 offset:34816
	ds_read_b128 v[196:199], v181 offset:35840
	ds_read_b128 v[200:203], v181 offset:36864
	ds_read_b128 v[204:207], v181 offset:37888
	ds_read_b128 v[208:211], v181 offset:38912
	ds_read_b128 v[212:215], v181 offset:39936
	global_load_lds_dwordx4 v[222:223], off
	s_mov_b32 m0, s57
	v_lshl_add_u64 v[222:223], s[44:45], 0, v[132:133]
	global_load_lds_dwordx4 v[222:223], off
	s_cmp_eq_u32 s100, 0
	s_waitcnt lgkmcnt(0)
	s_cbranch_scc1 .Ldw_39
	s_waitcnt vmcnt(8)

.Ldw_40:
	s_barrier
	s_setprio 1
	v_mfma_f32_16x16x32_bf16 v[60:63], v[144:147], v[184:187], v[60:63]
	v_mfma_f32_16x16x32_bf16 v[56:59], v[152:155], v[184:187], v[56:59]
	v_mfma_f32_16x16x32_bf16 v[44:47], v[144:147], v[192:195], v[44:47]
	v_mfma_f32_16x16x32_bf16 v[40:43], v[152:155], v[192:195], v[40:43]
	v_mfma_f32_16x16x32_bf16 v[28:31], v[144:147], v[200:203], v[28:31]
	v_mfma_f32_16x16x32_bf16 v[24:27], v[152:155], v[200:203], v[24:27]
	v_mfma_f32_16x16x32_bf16 v[12:15], v[144:147], v[208:211], v[12:15]
	v_mfma_f32_16x16x32_bf16 v[8:11], v[152:155], v[208:211], v[8:11]
	v_mfma_f32_16x16x32_bf16 v[60:63], v[148:151], v[188:191], v[60:63]
	v_mfma_f32_16x16x32_bf16 v[56:59], v[156:159], v[188:191], v[56:59]
	v_mfma_f32_16x16x32_bf16 v[44:47], v[148:151], v[196:199], v[44:47]
	v_mfma_f32_16x16x32_bf16 v[40:43], v[156:159], v[196:199], v[40:43]
	v_mfma_f32_16x16x32_bf16 v[28:31], v[148:151], v[204:207], v[28:31]
	v_mfma_f32_16x16x32_bf16 v[24:27], v[156:159], v[204:207], v[24:27]
	v_mfma_f32_16x16x32_bf16 v[12:15], v[148:151], v[212:215], v[12:15]
	v_mfma_f32_16x16x32_bf16 v[8:11], v[156:159], v[212:215], v[8:11]
	s_setprio 0
	s_setprio 1
	v_mfma_f32_16x16x32_bf16 v[52:55], v[160:163], v[184:187], v[52:55]
	v_mfma_f32_16x16x32_bf16 v[48:51], v[168:171], v[184:187], v[48:51]
	v_mfma_f32_16x16x32_bf16 v[36:39], v[160:163], v[192:195], v[36:39]
	v_mfma_f32_16x16x32_bf16 v[32:35], v[168:171], v[192:195], v[32:35]
	v_mfma_f32_16x16x32_bf16 v[20:23], v[160:163], v[200:203], v[20:23]
	v_mfma_f32_16x16x32_bf16 v[16:19], v[168:171], v[200:203], v[16:19]
	v_mfma_f32_16x16x32_bf16 v[4:7], v[160:163], v[208:211], v[4:7]
	v_mfma_f32_16x16x32_bf16 v[0:3], v[168:171], v[208:211], v[0:3]
	v_mfma_f32_16x16x32_bf16 v[52:55], v[164:167], v[188:191], v[52:55]
	v_mfma_f32_16x16x32_bf16 v[48:51], v[172:175], v[188:191], v[48:51]
	v_mfma_f32_16x16x32_bf16 v[36:39], v[164:167], v[196:199], v[36:39]
	v_mfma_f32_16x16x32_bf16 v[32:35], v[172:175], v[196:199], v[32:35]
	s_waitcnt vmcnt(8)
	s_setprio 2
	s_barrier
	v_mfma_f32_16x16x32_bf16 v[20:23], v[164:167], v[204:207], v[20:23]
	v_mfma_f32_16x16x32_bf16 v[16:19], v[172:175], v[204:207], v[16:19]
	v_mfma_f32_16x16x32_bf16 v[4:7], v[164:167], v[212:215], v[4:7]
	v_mfma_f32_16x16x32_bf16 v[0:3], v[172:175], v[212:215], v[0:3]
	s_setprio 0
	s_add_i32 s73, s73, 2
	s_add_u32 s6, s6, 0x100
	s_addc_u32 s7, s7, 0
	s_add_u32 s71, s71, 0x100
	s_addc_u32 s72, s72, 0
	s_cmp_gt_u32 s73, 13
	s_cbranch_scc0 .LBB0_952

.LBB0_1145:
	s_ashr_i32 s23, s22, 31
	s_lshl_b64 s[26:27], s[22:23], 19
	s_add_u32 s26, s45, s26
	s_addc_u32 s27, s46, s27
	s_and_b64 s[28:29], s[4:5], exec
	s_cselect_b32 s23, s27, s39
	s_cselect_b32 s31, s26, s38
	s_ashr_i32 s25, s24, 31
	s_lshl_b64 s[28:29], s[24:25], 19
	s_add_u32 s28, s47, s28
	s_addc_u32 s29, s48, s29
	s_and_b64 s[42:43], s[4:5], exec
	s_cselect_b32 s25, s29, s41
	s_cselect_b32 s37, s28, s40
	s_add_u32 s38, s38, 0x40080
	s_addc_u32 s39, s39, 0
	s_add_u32 s64, s40, 0x100
	s_addc_u32 s65, s41, 0
	s_mov_b32 s66, -2
	ds_read_b128 v[120:123], v233
	ds_read_b128 v[132:135], v233 offset:1024
	ds_read_b128 v[136:139], v233 offset:2048
	ds_read_b128 v[140:143], v233 offset:3072
	ds_read_b128 v[144:147], v234
	ds_read_b128 v[148:151], v234 offset:1024
	ds_read_b128 v[152:155], v234 offset:2048
	ds_read_b128 v[156:159], v234 offset:3072
	s_add_u32 s40, s38, 0xfffc0080
	s_addc_u32 s41, s39, -1
	s_cmp_eq_u32 s66, 12
	s_cselect_b32 s43, s23, s41
	s_cselect_b32 s42, s31, s40
	s_cselect_b32 s41, s25, s65
	s_cselect_b32 s40, s37, s64
	v_lshl_add_u64 v[208:209], s[38:39], 0, v[192:193]
	s_add_i32 m0, s50, 0xc000
	ds_read_b128 v[160:163], v235
	ds_read_b128 v[164:167], v235 offset:1024
	ds_read_b128 v[168:171], v235 offset:2048
	ds_read_b128 v[172:175], v235 offset:3072
	ds_read_b128 v[176:179], v235 offset:4096
	ds_read_b128 v[180:183], v235 offset:5120
	ds_read_b128 v[200:203], v235 offset:6144
	ds_read_b128 v[204:207], v235 offset:7168
	global_load_lds_dwordx4 v[208:209], off
	s_add_i32 m0, s50, 0xe000
	v_lshl_add_u64 v[208:209], s[38:39], 0, v[194:195]
	global_load_lds_dwordx4 v[208:209], off
	s_cmp_eq_u32 s100, 0
	s_waitcnt lgkmcnt(0)
	s_cbranch_scc1 .Ldw_41
	s_waitcnt vmcnt(8)
.Ldw_41:
	s_barrier
	s_setprio 1
	v_mfma_f32_16x16x32_bf16 v[128:131], v[120:123], v[160:163], 0
	v_mfma_f32_16x16x32_bf16 v[124:127], v[136:139], v[160:163], 0
	v_mfma_f32_16x16x32_bf16 v[108:111], v[120:123], v[168:171], 0
	v_mfma_f32_16x16x32_bf16 v[104:107], v[136:139], v[168:171], 0
	v_mfma_f32_16x16x32_bf16 v[92:95], v[120:123], v[176:179], 0
	v_mfma_f32_16x16x32_bf16 v[88:91], v[136:139], v[176:179], 0
	v_mfma_f32_16x16x32_bf16 v[76:79], v[120:123], v[200:203], 0
	v_mfma_f32_16x16x32_bf16 v[72:75], v[136:139], v[200:203], 0
	v_mfma_f32_16x16x32_bf16 v[128:131], v[132:135], v[164:167], v[128:131]
	v_mfma_f32_16x16x32_bf16 v[124:127], v[140:143], v[164:167], v[124:127]
	v_mfma_f32_16x16x32_bf16 v[108:111], v[132:135], v[172:175], v[108:111]
	v_mfma_f32_16x16x32_bf16 v[104:107], v[140:143], v[172:175], v[104:107]
	v_mfma_f32_16x16x32_bf16 v[92:95], v[132:135], v[180:183], v[92:95]
	v_mfma_f32_16x16x32_bf16 v[88:91], v[140:143], v[180:183], v[88:91]
	v_mfma_f32_16x16x32_bf16 v[76:79], v[132:135], v[204:207], v[76:79]
	v_mfma_f32_16x16x32_bf16 v[72:75], v[140:143], v[204:207], v[72:75]
	s_setprio 0
	s_setprio 1
	v_mfma_f32_16x16x32_bf16 v[116:119], v[144:147], v[160:163], 0
	v_mfma_f32_16x16x32_bf16 v[112:115], v[152:155], v[160:163], 0
	v_mfma_f32_16x16x32_bf16 v[100:103], v[144:147], v[168:171], 0
	v_mfma_f32_16x16x32_bf16 v[96:99], v[152:155], v[168:171], 0
	v_mfma_f32_16x16x32_bf16 v[84:87], v[144:147], v[176:179], 0
	v_mfma_f32_16x16x32_bf16 v[80:83], v[152:155], v[176:179], 0
	v_mfma_f32_16x16x32_bf16 v[68:71], v[144:147], v[200:203], 0
	v_mfma_f32_16x16x32_bf16 v[64:67], v[152:155], v[200:203], 0
	v_mfma_f32_16x16x32_bf16 v[116:119], v[148:151], v[164:167], v[116:119]
	v_mfma_f32_16x16x32_bf16 v[112:115], v[156:159], v[164:167], v[112:115]
	v_mfma_f32_16x16x32_bf16 v[100:103], v[148:151], v[172:175], v[100:103]
	v_mfma_f32_16x16x32_bf16 v[96:99], v[156:159], v[172:175], v[96:99]
	s_waitcnt vmcnt(8)
	s_setprio 2
	s_barrier
	v_mfma_f32_16x16x32_bf16 v[84:87], v[148:151], v[180:183], v[84:87]
	v_mfma_f32_16x16x32_bf16 v[80:83], v[156:159], v[180:183], v[80:83]
	v_mfma_f32_16x16x32_bf16 v[68:71], v[148:151], v[204:207], v[68:71]
	v_mfma_f32_16x16x32_bf16 v[64:67], v[156:159], v[204:207], v[64:67]
	s_setprio 2
	s_add_i32 s67, s62, s49
	v_lshl_add_u64 v[208:209], s[40:41], 0, v[186:187]
	s_mov_b32 m0, s67
	ds_read_b128 v[160:163], v235 offset:16384
	ds_read_b128 v[164:167], v235 offset:17408
	ds_read_b128 v[168:171], v235 offset:18432
	ds_read_b128 v[172:175], v235 offset:19456
	ds_read_b128 v[176:179], v235 offset:20480
	ds_read_b128 v[180:183], v235 offset:21504
	ds_read_b128 v[200:203], v235 offset:22528
	ds_read_b128 v[204:207], v235 offset:23552
	global_load_lds_dwordx4 v[208:209], off
	s_add_i32 m0, s67, 0x2000
	s_add_u32 s68, s40, 0x40000
	v_lshl_add_u64 v[210:211], s[40:41], 0, v[190:191]
	s_addc_u32 s69, s41, 0
	s_add_i32 s67, s63, s49
	global_load_lds_dwordx4 v[210:211], off
	v_lshl_add_u64 v[212:213], s[68:69], 0, v[186:187]
	s_mov_b32 m0, s67
	v_lshl_add_u64 v[214:215], s[42:43], 0, v[188:189]
	global_load_lds_dwordx4 v[212:213], off
	s_add_i32 m0, s67, 0x2000
	v_lshl_add_u64 v[212:213], s[68:69], 0, v[190:191]
	global_load_lds_dwordx4 v[212:213], off
	s_mov_b32 m0, s50
	v_lshl_add_u64 v[212:213], s[42:43], 0, v[184:185]
	global_load_lds_dwordx4 v[212:213], off
	s_mov_b32 m0, s51
	s_nop 0
	global_load_lds_dwordx4 v[214:215], off
	s_cmp_eq_u32 s100, 0
	s_waitcnt lgkmcnt(0)
	s_cbranch_scc1 .Ldw_42
	s_waitcnt vmcnt(8)
.Ldw_42:
	s_barrier
	s_setprio 1
	v_mfma_f32_16x16x32_bf16 v[60:63], v[120:123], v[160:163], 0
	v_mfma_f32_16x16x32_bf16 v[56:59], v[136:139], v[160:163], 0
	v_mfma_f32_16x16x32_bf16 v[44:47], v[120:123], v[168:171], 0
	v_mfma_f32_16x16x32_bf16 v[40:43], v[136:139], v[168:171], 0
	v_mfma_f32_16x16x32_bf16 v[28:31], v[120:123], v[176:179], 0
	v_mfma_f32_16x16x32_bf16 v[24:27], v[136:139], v[176:179], 0
	v_mfma_f32_16x16x32_bf16 v[12:15], v[120:123], v[200:203], 0
	v_mfma_f32_16x16x32_bf16 v[8:11], v[136:139], v[200:203], 0
	v_mfma_f32_16x16x32_bf16 v[60:63], v[132:135], v[164:167], v[60:63]
	v_mfma_f32_16x16x32_bf16 v[56:59], v[140:143], v[164:167], v[56:59]
	v_mfma_f32_16x16x32_bf16 v[44:47], v[132:135], v[172:175], v[44:47]
	v_mfma_f32_16x16x32_bf16 v[40:43], v[140:143], v[172:175], v[40:43]
	v_mfma_f32_16x16x32_bf16 v[28:31], v[132:135], v[180:183], v[28:31]
	v_mfma_f32_16x16x32_bf16 v[24:27], v[140:143], v[180:183], v[24:27]
	v_mfma_f32_16x16x32_bf16 v[12:15], v[132:135], v[204:207], v[12:15]
	v_mfma_f32_16x16x32_bf16 v[8:11], v[140:143], v[204:207], v[8:11]
	s_setprio 0
	s_setprio 1
	v_mfma_f32_16x16x32_bf16 v[52:55], v[144:147], v[160:163], 0
	v_mfma_f32_16x16x32_bf16 v[48:51], v[152:155], v[160:163], 0
	v_mfma_f32_16x16x32_bf16 v[36:39], v[144:147], v[168:171], 0
	v_mfma_f32_16x16x32_bf16 v[32:35], v[152:155], v[168:171], 0
	v_mfma_f32_16x16x32_bf16 v[20:23], v[144:147], v[176:179], 0
	v_mfma_f32_16x16x32_bf16 v[16:19], v[152:155], v[176:179], 0
	v_mfma_f32_16x16x32_bf16 v[4:7], v[144:147], v[200:203], 0
	v_mfma_f32_16x16x32_bf16 v[0:3], v[152:155], v[200:203], 0
	v_mfma_f32_16x16x32_bf16 v[52:55], v[148:151], v[164:167], v[52:55]
	v_mfma_f32_16x16x32_bf16 v[48:51], v[156:159], v[164:167], v[48:51]
	v_mfma_f32_16x16x32_bf16 v[36:39], v[148:151], v[172:175], v[36:39]
	v_mfma_f32_16x16x32_bf16 v[32:35], v[156:159], v[172:175], v[32:35]
	s_waitcnt vmcnt(8)
	s_setprio 2
	s_barrier
	v_mfma_f32_16x16x32_bf16 v[20:23], v[148:151], v[180:183], v[20:23]
	v_mfma_f32_16x16x32_bf16 v[16:19], v[156:159], v[180:183], v[16:19]
	v_mfma_f32_16x16x32_bf16 v[4:7], v[148:151], v[204:207], v[4:7]
	v_mfma_f32_16x16x32_bf16 v[0:3], v[156:159], v[204:207], v[0:3]
	s_setprio 0
	s_add_i32 s67, 0, 0x18000
	s_add_i32 s68, 0, 0x1c000
	v_add_u32_e32 v140, s67, v232
	v_add_u32_e32 v156, s68, v232
	ds_read_b128 v[120:123], v140
	ds_read_b128 v[132:135], v140 offset:1024
	ds_read_b128 v[136:139], v140 offset:2048
	ds_read_b128 v[140:143], v140 offset:3072
	ds_read_b128 v[144:147], v156
	ds_read_b128 v[148:151], v156 offset:1024
	ds_read_b128 v[152:155], v156 offset:2048
	ds_read_b128 v[156:159], v156 offset:3072
	s_add_u32 s42, s42, 0x40000
	s_addc_u32 s43, s43, 0
	s_mov_b32 m0, s54
	v_lshl_add_u64 v[216:217], s[42:43], 0, v[184:185]
	ds_read_b128 v[160:163], v235 offset:32768
	ds_read_b128 v[164:167], v235 offset:33792
	ds_read_b128 v[168:171], v235 offset:34816
	ds_read_b128 v[172:175], v235 offset:35840
	ds_read_b128 v[176:179], v235 offset:36864
	ds_read_b128 v[180:183], v235 offset:37888
	ds_read_b128 v[200:203], v235 offset:38912
	ds_read_b128 v[204:207], v235 offset:39936
	global_load_lds_dwordx4 v[216:217], off
	s_mov_b32 m0, s55
	v_lshl_add_u64 v[216:217], s[42:43], 0, v[188:189]
	global_load_lds_dwordx4 v[216:217], off
	s_cmp_eq_u32 s100, 0
	s_waitcnt lgkmcnt(0)
	s_cbranch_scc1 .Ldw_43
	s_waitcnt vmcnt(8)
.Ldw_43:
	s_barrier
	s_setprio 1
	v_mfma_f32_16x16x32_bf16 v[128:131], v[120:123], v[160:163], v[128:131]
	v_mfma_f32_16x16x32_bf16 v[124:127], v[136:139], v[160:163], v[124:127]
	v_mfma_f32_16x16x32_bf16 v[108:111], v[120:123], v[168:171], v[108:111]
	v_mfma_f32_16x16x32_bf16 v[104:107], v[136:139], v[168:171], v[104:107]
	v_mfma_f32_16x16x32_bf16 v[92:95], v[120:123], v[176:179], v[92:95]
	v_mfma_f32_16x16x32_bf16 v[88:91], v[136:139], v[176:179], v[88:91]
	v_mfma_f32_16x16x32_bf16 v[76:79], v[120:123], v[200:203], v[76:79]
	v_mfma_f32_16x16x32_bf16 v[72:75], v[136:139], v[200:203], v[72:75]
	v_mfma_f32_16x16x32_bf16 v[128:131], v[132:135], v[164:167], v[128:131]
	v_mfma_f32_16x16x32_bf16 v[124:127], v[140:143], v[164:167], v[124:127]
	v_mfma_f32_16x16x32_bf16 v[108:111], v[132:135], v[172:175], v[108:111]
	v_mfma_f32_16x16x32_bf16 v[104:107], v[140:143], v[172:175], v[104:107]
	v_mfma_f32_16x16x32_bf16 v[92:95], v[132:135], v[180:183], v[92:95]
	v_mfma_f32_16x16x32_bf16 v[88:91], v[140:143], v[180:183], v[88:91]
	v_mfma_f32_16x16x32_bf16 v[76:79], v[132:135], v[204:207], v[76:79]
	v_mfma_f32_16x16x32_bf16 v[72:75], v[140:143], v[204:207], v[72:75]
	s_setprio 0
	s_setprio 1
	v_mfma_f32_16x16x32_bf16 v[116:119], v[144:147], v[160:163], v[116:119]
	v_mfma_f32_16x16x32_bf16 v[112:115], v[152:155], v[160:163], v[112:115]
	v_mfma_f32_16x16x32_bf16 v[100:103], v[144:147], v[168:171], v[100:103]
	v_mfma_f32_16x16x32_bf16 v[96:99], v[152:155], v[168:171], v[96:99]
	v_mfma_f32_16x16x32_bf16 v[84:87], v[144:147], v[176:179], v[84:87]
	v_mfma_f32_16x16x32_bf16 v[80:83], v[152:155], v[176:179], v[80:83]
	v_mfma_f32_16x16x32_bf16 v[68:71], v[144:147], v[200:203], v[68:71]
	v_mfma_f32_16x16x32_bf16 v[64:67], v[152:155], v[200:203], v[64:67]
	v_mfma_f32_16x16x32_bf16 v[116:119], v[148:151], v[164:167], v[116:119]
	v_mfma_f32_16x16x32_bf16 v[112:115], v[156:159], v[164:167], v[112:115]
	v_mfma_f32_16x16x32_bf16 v[100:103], v[148:151], v[172:175], v[100:103]
	v_mfma_f32_16x16x32_bf16 v[96:99], v[156:159], v[172:175], v[96:99]
	s_waitcnt vmcnt(8)
	s_setprio 2
	s_barrier
	v_mfma_f32_16x16x32_bf16 v[84:87], v[148:151], v[180:183], v[84:87]
	v_mfma_f32_16x16x32_bf16 v[80:83], v[156:159], v[180:183], v[80:83]
	v_mfma_f32_16x16x32_bf16 v[68:71], v[148:151], v[204:207], v[68:71]
	v_mfma_f32_16x16x32_bf16 v[64:67], v[156:159], v[204:207], v[64:67]
	s_setprio 2
	s_add_i32 s42, s67, s49
	v_lshl_add_u64 v[208:209], v[208:209], 0, s[18:19]
	s_mov_b32 m0, s42
	ds_read_b128 v[160:163], v235 offset:49152
	ds_read_b128 v[164:167], v235 offset:50176
	ds_read_b128 v[168:171], v235 offset:51200
	ds_read_b128 v[172:175], v235 offset:52224
	ds_read_b128 v[176:179], v235 offset:53248
	ds_read_b128 v[180:183], v235 offset:54272
	ds_read_b128 v[200:203], v235 offset:55296
	ds_read_b128 v[204:207], v235 offset:56320
	global_load_lds_dwordx4 v[208:209], off
	s_add_i32 m0, s42, 0x2000
	s_add_u32 s40, s40, 0x40080
	v_lshl_add_u64 v[208:209], v[210:211], 0, s[18:19]
	s_addc_u32 s41, s41, 0
	s_add_i32 s42, s68, s49
	global_load_lds_dwordx4 v[208:209], off
	s_mov_b32 m0, s42
	v_lshl_add_u64 v[208:209], s[40:41], 0, v[186:187]
	global_load_lds_dwordx4 v[208:209], off
	s_add_i32 m0, s42, 0x2000
	v_lshl_add_u64 v[208:209], s[40:41], 0, v[190:191]
	global_load_lds_dwordx4 v[208:209], off
	s_mov_b32 m0, s57
	v_lshl_add_u64 v[208:209], v[212:213], 0, s[18:19]
	global_load_lds_dwordx4 v[208:209], off
	s_mov_b32 m0, s58
	v_lshl_add_u64 v[208:209], v[214:215], 0, s[18:19]
	global_load_lds_dwordx4 v[208:209], off
	s_cmp_eq_u32 s100, 0
	s_waitcnt lgkmcnt(0)
	s_cbranch_scc1 .Ldw_44
	s_waitcnt vmcnt(8)
.Ldw_44:
	s_barrier
	s_setprio 1
	v_mfma_f32_16x16x32_bf16 v[60:63], v[120:123], v[160:163], v[60:63]
	v_mfma_f32_16x16x32_bf16 v[56:59], v[136:139], v[160:163], v[56:59]
	v_mfma_f32_16x16x32_bf16 v[44:47], v[120:123], v[168:171], v[44:47]
	v_mfma_f32_16x16x32_bf16 v[40:43], v[136:139], v[168:171], v[40:43]
	v_mfma_f32_16x16x32_bf16 v[28:31], v[120:123], v[176:179], v[28:31]
	v_mfma_f32_16x16x32_bf16 v[24:27], v[136:139], v[176:179], v[24:27]
	v_mfma_f32_16x16x32_bf16 v[12:15], v[120:123], v[200:203], v[12:15]
	v_mfma_f32_16x16x32_bf16 v[8:11], v[136:139], v[200:203], v[8:11]
	v_mfma_f32_16x16x32_bf16 v[60:63], v[132:135], v[164:167], v[60:63]
	v_mfma_f32_16x16x32_bf16 v[56:59], v[140:143], v[164:167], v[56:59]
	v_mfma_f32_16x16x32_bf16 v[44:47], v[132:135], v[172:175], v[44:47]
	v_mfma_f32_16x16x32_bf16 v[40:43], v[140:143], v[172:175], v[40:43]
	v_mfma_f32_16x16x32_bf16 v[28:31], v[132:135], v[180:183], v[28:31]
	v_mfma_f32_16x16x32_bf16 v[24:27], v[140:143], v[180:183], v[24:27]
	v_mfma_f32_16x16x32_bf16 v[12:15], v[132:135], v[204:207], v[12:15]
	v_mfma_f32_16x16x32_bf16 v[8:11], v[140:143], v[204:207], v[8:11]
	s_setprio 0
	s_setprio 1
	v_mfma_f32_16x16x32_bf16 v[52:55], v[144:147], v[160:163], v[52:55]
	v_mfma_f32_16x16x32_bf16 v[48:51], v[152:155], v[160:163], v[48:51]
	v_mfma_f32_16x16x32_bf16 v[36:39], v[144:147], v[168:171], v[36:39]
	v_mfma_f32_16x16x32_bf16 v[32:35], v[152:155], v[168:171], v[32:35]
	v_mfma_f32_16x16x32_bf16 v[20:23], v[144:147], v[176:179], v[20:23]
	v_mfma_f32_16x16x32_bf16 v[16:19], v[152:155], v[176:179], v[16:19]
	v_mfma_f32_16x16x32_bf16 v[4:7], v[144:147], v[200:203], v[4:7]
	v_mfma_f32_16x16x32_bf16 v[0:3], v[152:155], v[200:203], v[0:3]
	v_mfma_f32_16x16x32_bf16 v[52:55], v[148:151], v[164:167], v[52:55]
	v_mfma_f32_16x16x32_bf16 v[48:51], v[156:159], v[164:167], v[48:51]
	v_mfma_f32_16x16x32_bf16 v[36:39], v[148:151], v[172:175], v[36:39]
	v_mfma_f32_16x16x32_bf16 v[32:35], v[156:159], v[172:175], v[32:35]
	s_waitcnt vmcnt(8)
	s_setprio 2
	s_barrier
	v_mfma_f32_16x16x32_bf16 v[20:23], v[148:151], v[180:183], v[20:23]
	v_mfma_f32_16x16x32_bf16 v[16:19], v[156:159], v[180:183], v[16:19]
	v_mfma_f32_16x16x32_bf16 v[4:7], v[148:151], v[204:207], v[4:7]
	v_mfma_f32_16x16x32_bf16 v[0:3], v[156:159], v[204:207], v[0:3]
	s_setprio 0
	s_add_i32 s66, s66, 2
	s_add_u32 s38, s38, 0x100
	s_addc_u32 s39, s39, 0
	s_add_u32 s64, s64, 0x100
	s_addc_u32 s65, s65, 0
	s_cmp_gt_u32 s66, 13
.LBB0_1146:
	ds_read_b128 v[120:123], v233
	ds_read_b128 v[132:135], v233 offset:1024
	ds_read_b128 v[136:139], v233 offset:2048
	ds_read_b128 v[140:143], v233 offset:3072
	ds_read_b128 v[144:147], v234
	ds_read_b128 v[148:151], v234 offset:1024
	ds_read_b128 v[152:155], v234 offset:2048
	ds_read_b128 v[156:159], v234 offset:3072
	s_add_u32 s40, s38, 0xfffc0080
	s_addc_u32 s41, s39, -1
	s_cmp_eq_u32 s66, 12
	s_cselect_b32 s43, s23, s41
	s_cselect_b32 s42, s31, s40
	s_cselect_b32 s41, s25, s65
	s_cselect_b32 s40, s37, s64
	v_lshl_add_u64 v[208:209], s[38:39], 0, v[192:193]
	s_add_i32 m0, s50, 0xc000
	ds_read_b128 v[160:163], v235
	ds_read_b128 v[164:167], v235 offset:1024
	ds_read_b128 v[168:171], v235 offset:2048
	ds_read_b128 v[172:175], v235 offset:3072
	ds_read_b128 v[176:179], v235 offset:4096
	ds_read_b128 v[180:183], v235 offset:5120
	ds_read_b128 v[200:203], v235 offset:6144
	ds_read_b128 v[204:207], v235 offset:7168
	global_load_lds_dwordx4 v[208:209], off
	s_add_i32 m0, s50, 0xe000
	v_lshl_add_u64 v[208:209], s[38:39], 0, v[194:195]
	global_load_lds_dwordx4 v[208:209], off
	s_cmp_eq_u32 s100, 0
	s_waitcnt lgkmcnt(0)
	s_cbranch_scc1 .Ldw_45
	s_waitcnt vmcnt(8)
.Ldw_45:
	s_barrier
	s_setprio 1
	v_mfma_f32_16x16x32_bf16 v[128:131], v[120:123], v[160:163], v[128:131]
	v_mfma_f32_16x16x32_bf16 v[124:127], v[136:139], v[160:163], v[124:127]
	v_mfma_f32_16x16x32_bf16 v[108:111], v[120:123], v[168:171], v[108:111]
	v_mfma_f32_16x16x32_bf16 v[104:107], v[136:139], v[168:171], v[104:107]
	v_mfma_f32_16x16x32_bf16 v[92:95], v[120:123], v[176:179], v[92:95]
	v_mfma_f32_16x16x32_bf16 v[88:91], v[136:139], v[176:179], v[88:91]
	v_mfma_f32_16x16x32_bf16 v[76:79], v[120:123], v[200:203], v[76:79]
	v_mfma_f32_16x16x32_bf16 v[72:75], v[136:139], v[200:203], v[72:75]
	v_mfma_f32_16x16x32_bf16 v[128:131], v[132:135], v[164:167], v[128:131]
	v_mfma_f32_16x16x32_bf16 v[124:127], v[140:143], v[164:167], v[124:127]
	v_mfma_f32_16x16x32_bf16 v[108:111], v[132:135], v[172:175], v[108:111]
	v_mfma_f32_16x16x32_bf16 v[104:107], v[140:143], v[172:175], v[104:107]
	v_mfma_f32_16x16x32_bf16 v[92:95], v[132:135], v[180:183], v[92:95]
	v_mfma_f32_16x16x32_bf16 v[88:91], v[140:143], v[180:183], v[88:91]
	v_mfma_f32_16x16x32_bf16 v[76:79], v[132:135], v[204:207], v[76:79]
	v_mfma_f32_16x16x32_bf16 v[72:75], v[140:143], v[204:207], v[72:75]
	s_setprio 0
	s_setprio 1
	v_mfma_f32_16x16x32_bf16 v[116:119], v[144:147], v[160:163], v[116:119]
	v_mfma_f32_16x16x32_bf16 v[112:115], v[152:155], v[160:163], v[112:115]
	v_mfma_f32_16x16x32_bf16 v[100:103], v[144:147], v[168:171], v[100:103]
	v_mfma_f32_16x16x32_bf16 v[96:99], v[152:155], v[168:171], v[96:99]
	v_mfma_f32_16x16x32_bf16 v[84:87], v[144:147], v[176:179], v[84:87]
	v_mfma_f32_16x16x32_bf16 v[80:83], v[152:155], v[176:179], v[80:83]
	v_mfma_f32_16x16x32_bf16 v[68:71], v[144:147], v[200:203], v[68:71]
	v_mfma_f32_16x16x32_bf16 v[64:67], v[152:155], v[200:203], v[64:67]
	v_mfma_f32_16x16x32_bf16 v[116:119], v[148:151], v[164:167], v[116:119]
	v_mfma_f32_16x16x32_bf16 v[112:115], v[156:159], v[164:167], v[112:115]
	v_mfma_f32_16x16x32_bf16 v[100:103], v[148:151], v[172:175], v[100:103]
	v_mfma_f32_16x16x32_bf16 v[96:99], v[156:159], v[172:175], v[96:99]
	s_waitcnt vmcnt(8)
	s_setprio 2
	s_barrier
	v_mfma_f32_16x16x32_bf16 v[84:87], v[148:151], v[180:183], v[84:87]
	v_mfma_f32_16x16x32_bf16 v[80:83], v[156:159], v[180:183], v[80:83]
	v_mfma_f32_16x16x32_bf16 v[68:71], v[148:151], v[204:207], v[68:71]
	v_mfma_f32_16x16x32_bf16 v[64:67], v[156:159], v[204:207], v[64:67]
	s_setprio 2
	s_add_i32 s67, s62, s49
	v_lshl_add_u64 v[208:209], s[40:41], 0, v[186:187]
	s_mov_b32 m0, s67
	ds_read_b128 v[160:163], v235 offset:16384
	ds_read_b128 v[164:167], v235 offset:17408
	ds_read_b128 v[168:171], v235 offset:18432
	ds_read_b128 v[172:175], v235 offset:19456
	ds_read_b128 v[176:179], v235 offset:20480
	ds_read_b128 v[180:183], v235 offset:21504
	ds_read_b128 v[200:203], v235 offset:22528
	ds_read_b128 v[204:207], v235 offset:23552
	global_load_lds_dwordx4 v[208:209], off
	s_add_i32 m0, s67, 0x2000
	s_add_u32 s68, s40, 0x40000
	v_lshl_add_u64 v[210:211], s[40:41], 0, v[190:191]
	s_addc_u32 s69, s41, 0
	s_add_i32 s67, s63, s49
	global_load_lds_dwordx4 v[210:211], off
	v_lshl_add_u64 v[212:213], s[68:69], 0, v[186:187]
	s_mov_b32 m0, s67
	v_lshl_add_u64 v[214:215], s[42:43], 0, v[188:189]
	global_load_lds_dwordx4 v[212:213], off
	s_add_i32 m0, s67, 0x2000
	v_lshl_add_u64 v[212:213], s[68:69], 0, v[190:191]
	global_load_lds_dwordx4 v[212:213], off
	s_mov_b32 m0, s50
	v_lshl_add_u64 v[212:213], s[42:43], 0, v[184:185]
	global_load_lds_dwordx4 v[212:213], off
	s_mov_b32 m0, s51
	s_nop 0
	global_load_lds_dwordx4 v[214:215], off
	s_cmp_eq_u32 s100, 0
	s_waitcnt lgkmcnt(0)
	s_cbranch_scc1 .Ldw_46
	s_waitcnt vmcnt(8)
.Ldw_46:
	s_barrier
	s_setprio 1
	v_mfma_f32_16x16x32_bf16 v[60:63], v[120:123], v[160:163], v[60:63]
	v_mfma_f32_16x16x32_bf16 v[56:59], v[136:139], v[160:163], v[56:59]
	v_mfma_f32_16x16x32_bf16 v[44:47], v[120:123], v[168:171], v[44:47]
	v_mfma_f32_16x16x32_bf16 v[40:43], v[136:139], v[168:171], v[40:43]
	v_mfma_f32_16x16x32_bf16 v[28:31], v[120:123], v[176:179], v[28:31]
	v_mfma_f32_16x16x32_bf16 v[24:27], v[136:139], v[176:179], v[24:27]
	v_mfma_f32_16x16x32_bf16 v[12:15], v[120:123], v[200:203], v[12:15]
	v_mfma_f32_16x16x32_bf16 v[8:11], v[136:139], v[200:203], v[8:11]
	v_mfma_f32_16x16x32_bf16 v[60:63], v[132:135], v[164:167], v[60:63]
	v_mfma_f32_16x16x32_bf16 v[56:59], v[140:143], v[164:167], v[56:59]
	v_mfma_f32_16x16x32_bf16 v[44:47], v[132:135], v[172:175], v[44:47]
	v_mfma_f32_16x16x32_bf16 v[40:43], v[140:143], v[172:175], v[40:43]
	v_mfma_f32_16x16x32_bf16 v[28:31], v[132:135], v[180:183], v[28:31]
	v_mfma_f32_16x16x32_bf16 v[24:27], v[140:143], v[180:183], v[24:27]
	v_mfma_f32_16x16x32_bf16 v[12:15], v[132:135], v[204:207], v[12:15]
	v_mfma_f32_16x16x32_bf16 v[8:11], v[140:143], v[204:207], v[8:11]
	s_setprio 0
	s_setprio 1
	v_mfma_f32_16x16x32_bf16 v[52:55], v[144:147], v[160:163], v[52:55]
	v_mfma_f32_16x16x32_bf16 v[48:51], v[152:155], v[160:163], v[48:51]
	v_mfma_f32_16x16x32_bf16 v[36:39], v[144:147], v[168:171], v[36:39]
	v_mfma_f32_16x16x32_bf16 v[32:35], v[152:155], v[168:171], v[32:35]
	v_mfma_f32_16x16x32_bf16 v[20:23], v[144:147], v[176:179], v[20:23]
	v_mfma_f32_16x16x32_bf16 v[16:19], v[152:155], v[176:179], v[16:19]
	v_mfma_f32_16x16x32_bf16 v[4:7], v[144:147], v[200:203], v[4:7]
	v_mfma_f32_16x16x32_bf16 v[0:3], v[152:155], v[200:203], v[0:3]
	v_mfma_f32_16x16x32_bf16 v[52:55], v[148:151], v[164:167], v[52:55]
	v_mfma_f32_16x16x32_bf16 v[48:51], v[156:159], v[164:167], v[48:51]
	v_mfma_f32_16x16x32_bf16 v[36:39], v[148:151], v[172:175], v[36:39]
	v_mfma_f32_16x16x32_bf16 v[32:35], v[156:159], v[172:175], v[32:35]
	s_waitcnt vmcnt(8)
	s_setprio 2
	s_barrier
	v_mfma_f32_16x16x32_bf16 v[20:23], v[148:151], v[180:183], v[20:23]
	v_mfma_f32_16x16x32_bf16 v[16:19], v[156:159], v[180:183], v[16:19]
	v_mfma_f32_16x16x32_bf16 v[4:7], v[148:151], v[204:207], v[4:7]
	v_mfma_f32_16x16x32_bf16 v[0:3], v[156:159], v[204:207], v[0:3]
	s_setprio 0
	s_add_i32 s67, 0, 0x18000
	s_add_i32 s68, 0, 0x1c000
	v_add_u32_e32 v140, s67, v232
	v_add_u32_e32 v156, s68, v232
	ds_read_b128 v[120:123], v140
	ds_read_b128 v[132:135], v140 offset:1024
	ds_read_b128 v[136:139], v140 offset:2048
	ds_read_b128 v[140:143], v140 offset:3072
	ds_read_b128 v[144:147], v156
	ds_read_b128 v[148:151], v156 offset:1024
	ds_read_b128 v[152:155], v156 offset:2048
	ds_read_b128 v[156:159], v156 offset:3072
	s_add_u32 s42, s42, 0x40000
	s_addc_u32 s43, s43, 0
	s_mov_b32 m0, s54
	v_lshl_add_u64 v[216:217], s[42:43], 0, v[184:185]
	ds_read_b128 v[160:163], v235 offset:32768
	ds_read_b128 v[164:167], v235 offset:33792
	ds_read_b128 v[168:171], v235 offset:34816
	ds_read_b128 v[172:175], v235 offset:35840
	ds_read_b128 v[176:179], v235 offset:36864
	ds_read_b128 v[180:183], v235 offset:37888
	ds_read_b128 v[200:203], v235 offset:38912
	ds_read_b128 v[204:207], v235 offset:39936
	global_load_lds_dwordx4 v[216:217], off
	s_mov_b32 m0, s55
	v_lshl_add_u64 v[216:217], s[42:43], 0, v[188:189]
	global_load_lds_dwordx4 v[216:217], off
	s_cmp_eq_u32 s100, 0
	s_waitcnt lgkmcnt(0)
	s_cbranch_scc1 .Ldw_47
	s_waitcnt vmcnt(8)

.Ldw_48:
	s_barrier
	s_setprio 1
	v_mfma_f32_16x16x32_bf16 v[60:63], v[120:123], v[160:163], v[60:63]
	v_mfma_f32_16x16x32_bf16 v[56:59], v[136:139], v[160:163], v[56:59]
	v_mfma_f32_16x16x32_bf16 v[44:47], v[120:123], v[168:171], v[44:47]
	v_mfma_f32_16x16x32_bf16 v[40:43], v[136:139], v[168:171], v[40:43]
	v_mfma_f32_16x16x32_bf16 v[28:31], v[120:123], v[176:179], v[28:31]
	v_mfma_f32_16x16x32_bf16 v[24:27], v[136:139], v[176:179], v[24:27]
	v_mfma_f32_16x16x32_bf16 v[12:15], v[120:123], v[200:203], v[12:15]
	v_mfma_f32_16x16x32_bf16 v[8:11], v[136:139], v[200:203], v[8:11]
	v_mfma_f32_16x16x32_bf16 v[60:63], v[132:135], v[164:167], v[60:63]
	v_mfma_f32_16x16x32_bf16 v[56:59], v[140:143], v[164:167], v[56:59]
	v_mfma_f32_16x16x32_bf16 v[44:47], v[132:135], v[172:175], v[44:47]
	v_mfma_f32_16x16x32_bf16 v[40:43], v[140:143], v[172:175], v[40:43]
	v_mfma_f32_16x16x32_bf16 v[28:31], v[132:135], v[180:183], v[28:31]
	v_mfma_f32_16x16x32_bf16 v[24:27], v[140:143], v[180:183], v[24:27]
	v_mfma_f32_16x16x32_bf16 v[12:15], v[132:135], v[204:207], v[12:15]
	v_mfma_f32_16x16x32_bf16 v[8:11], v[140:143], v[204:207], v[8:11]
	s_setprio 0
	s_setprio 1
	v_mfma_f32_16x16x32_bf16 v[52:55], v[144:147], v[160:163], v[52:55]
	v_mfma_f32_16x16x32_bf16 v[48:51], v[152:155], v[160:163], v[48:51]
	v_mfma_f32_16x16x32_bf16 v[36:39], v[144:147], v[168:171], v[36:39]
	v_mfma_f32_16x16x32_bf16 v[32:35], v[152:155], v[168:171], v[32:35]
	v_mfma_f32_16x16x32_bf16 v[20:23], v[144:147], v[176:179], v[20:23]
	v_mfma_f32_16x16x32_bf16 v[16:19], v[152:155], v[176:179], v[16:19]
	v_mfma_f32_16x16x32_bf16 v[4:7], v[144:147], v[200:203], v[4:7]
	v_mfma_f32_16x16x32_bf16 v[0:3], v[152:155], v[200:203], v[0:3]
	v_mfma_f32_16x16x32_bf16 v[52:55], v[148:151], v[164:167], v[52:55]
	v_mfma_f32_16x16x32_bf16 v[48:51], v[156:159], v[164:167], v[48:51]
	v_mfma_f32_16x16x32_bf16 v[36:39], v[148:151], v[172:175], v[36:39]
	v_mfma_f32_16x16x32_bf16 v[32:35], v[156:159], v[172:175], v[32:35]
	s_waitcnt vmcnt(8)
	s_setprio 2
	s_barrier
	v_mfma_f32_16x16x32_bf16 v[20:23], v[148:151], v[180:183], v[20:23]
	v_mfma_f32_16x16x32_bf16 v[16:19], v[156:159], v[180:183], v[16:19]
	v_mfma_f32_16x16x32_bf16 v[4:7], v[148:151], v[204:207], v[4:7]
	v_mfma_f32_16x16x32_bf16 v[0:3], v[156:159], v[204:207], v[0:3]
	s_setprio 0
	s_add_i32 s66, s66, 2
	s_add_u32 s38, s38, 0x100
	s_addc_u32 s39, s39, 0
	s_add_u32 s64, s64, 0x100
	s_addc_u32 s65, s65, 0
	s_cmp_gt_u32 s66, 13
	s_cbranch_scc0 .LBB0_1146

.LBB0_1309:
	s_add_u32 s51, s26, 0x100
	s_addc_u32 s52, s27, 0
	s_mov_b32 s53, -2
	ds_read_b128 v[128:131], v197
	ds_read_b128 v[132:135], v197 offset:1024
	ds_read_b128 v[136:139], v197 offset:2048
	ds_read_b128 v[140:143], v197 offset:3072
	ds_read_b128 v[144:147], v198
	ds_read_b128 v[148:151], v198 offset:1024
	ds_read_b128 v[152:155], v198 offset:2048
	ds_read_b128 v[156:159], v198 offset:3072
	s_add_u32 s4, s24, 0x100
	s_addc_u32 s5, s25, 0
	s_cmp_eq_u32 s53, 40
	s_cselect_b32 s29, s21, s5
	s_cselect_b32 s28, s20, s4
	s_cselect_b32 s27, s23, s52
	s_cselect_b32 s26, s22, s51
	v_lshl_add_u64 v[212:213], s[24:25], 0, v[172:173]
	s_add_i32 m0, s36, 0xc000
	ds_read_b128 v[160:163], v199
	ds_read_b128 v[180:183], v199 offset:1024
	ds_read_b128 v[184:187], v199 offset:2048
	ds_read_b128 v[188:191], v199 offset:3072
	ds_read_b128 v[192:195], v199 offset:4096
	ds_read_b128 v[200:203], v199 offset:5120
	ds_read_b128 v[204:207], v199 offset:6144
	ds_read_b128 v[208:211], v199 offset:7168
	global_load_lds_dwordx4 v[212:213], off
	s_add_i32 m0, s36, 0xe000
	v_lshl_add_u64 v[212:213], s[24:25], 0, v[174:175]
	global_load_lds_dwordx4 v[212:213], off
	s_cmp_eq_u32 s100, 0
	s_waitcnt lgkmcnt(0)
	s_cbranch_scc1 .Ldw_57
	s_waitcnt vmcnt(8)
.Ldw_57:
	s_barrier
	s_setprio 1
	v_mfma_f32_16x16x32_bf16 v[124:127], v[128:131], v[160:163], 0
	v_mfma_f32_16x16x32_bf16 v[120:123], v[136:139], v[160:163], 0
	v_mfma_f32_16x16x32_bf16 v[116:119], v[128:131], v[184:187], 0
	v_mfma_f32_16x16x32_bf16 v[108:111], v[136:139], v[184:187], 0
	v_mfma_f32_16x16x32_bf16 v[88:91], v[128:131], v[192:195], 0
	v_mfma_f32_16x16x32_bf16 v[100:103], v[136:139], v[192:195], 0
	v_mfma_f32_16x16x32_bf16 v[72:75], v[128:131], v[204:207], 0
	v_mfma_f32_16x16x32_bf16 v[76:79], v[136:139], v[204:207], 0
	v_mfma_f32_16x16x32_bf16 v[124:127], v[132:135], v[180:183], v[124:127]
	v_mfma_f32_16x16x32_bf16 v[120:123], v[140:143], v[180:183], v[120:123]
	v_mfma_f32_16x16x32_bf16 v[116:119], v[132:135], v[188:191], v[116:119]
	v_mfma_f32_16x16x32_bf16 v[108:111], v[140:143], v[188:191], v[108:111]
	v_mfma_f32_16x16x32_bf16 v[88:91], v[132:135], v[200:203], v[88:91]
	v_mfma_f32_16x16x32_bf16 v[100:103], v[140:143], v[200:203], v[100:103]
	v_mfma_f32_16x16x32_bf16 v[72:75], v[132:135], v[208:211], v[72:75]
	v_mfma_f32_16x16x32_bf16 v[76:79], v[140:143], v[208:211], v[76:79]
	s_setprio 0
	s_setprio 1
	v_mfma_f32_16x16x32_bf16 v[112:115], v[144:147], v[160:163], 0
	v_mfma_f32_16x16x32_bf16 v[104:107], v[152:155], v[160:163], 0
	v_mfma_f32_16x16x32_bf16 v[96:99], v[144:147], v[184:187], 0
	v_mfma_f32_16x16x32_bf16 v[92:95], v[152:155], v[184:187], 0
	v_mfma_f32_16x16x32_bf16 v[80:83], v[144:147], v[192:195], 0
	v_mfma_f32_16x16x32_bf16 v[84:87], v[152:155], v[192:195], 0
	v_mfma_f32_16x16x32_bf16 v[64:67], v[144:147], v[204:207], 0
	v_mfma_f32_16x16x32_bf16 v[68:71], v[152:155], v[204:207], 0
	v_mfma_f32_16x16x32_bf16 v[112:115], v[148:151], v[180:183], v[112:115]
	v_mfma_f32_16x16x32_bf16 v[104:107], v[156:159], v[180:183], v[104:107]
	v_mfma_f32_16x16x32_bf16 v[96:99], v[148:151], v[188:191], v[96:99]
	v_mfma_f32_16x16x32_bf16 v[92:95], v[156:159], v[188:191], v[92:95]
	s_waitcnt vmcnt(8)
	s_setprio 2
	s_barrier
	v_mfma_f32_16x16x32_bf16 v[80:83], v[148:151], v[200:203], v[80:83]
	v_mfma_f32_16x16x32_bf16 v[84:87], v[156:159], v[200:203], v[84:87]
	v_mfma_f32_16x16x32_bf16 v[64:67], v[148:151], v[208:211], v[64:67]
	v_mfma_f32_16x16x32_bf16 v[68:71], v[156:159], v[208:211], v[68:71]
	s_setprio 2
	s_add_i32 s24, s45, s35
	v_lshl_add_u64 v[212:213], s[26:27], 0, v[166:167]
	s_mov_b32 m0, s24
	ds_read_b128 v[160:163], v199 offset:16384
	ds_read_b128 v[180:183], v199 offset:17408
	ds_read_b128 v[184:187], v199 offset:18432
	ds_read_b128 v[188:191], v199 offset:19456
	ds_read_b128 v[192:195], v199 offset:20480
	ds_read_b128 v[200:203], v199 offset:21504
	ds_read_b128 v[204:207], v199 offset:22528
	ds_read_b128 v[208:211], v199 offset:23552
	global_load_lds_dwordx4 v[212:213], off
	s_add_i32 m0, s24, 0x2000
	s_add_u32 s24, s26, 0xb0000
	v_lshl_add_u64 v[214:215], s[26:27], 0, v[170:171]
	s_addc_u32 s25, s27, 0
	s_add_i32 s54, s46, s35
	global_load_lds_dwordx4 v[214:215], off
	v_lshl_add_u64 v[216:217], s[24:25], 0, v[166:167]
	s_mov_b32 m0, s54
	v_lshl_add_u64 v[218:219], s[28:29], 0, v[168:169]
	global_load_lds_dwordx4 v[216:217], off
	s_add_i32 m0, s54, 0x2000
	v_lshl_add_u64 v[216:217], s[24:25], 0, v[170:171]
	global_load_lds_dwordx4 v[216:217], off
	s_mov_b32 m0, s36
	v_lshl_add_u64 v[216:217], s[28:29], 0, v[164:165]
	global_load_lds_dwordx4 v[216:217], off
	s_mov_b32 m0, s37
	s_nop 0
	global_load_lds_dwordx4 v[218:219], off
	s_cmp_eq_u32 s100, 0
	s_waitcnt lgkmcnt(0)
	s_cbranch_scc1 .Ldw_58
	s_waitcnt vmcnt(8)
.Ldw_58:
	s_barrier
	s_setprio 1
	v_mfma_f32_16x16x32_bf16 v[56:59], v[128:131], v[160:163], 0
	v_mfma_f32_16x16x32_bf16 v[60:63], v[136:139], v[160:163], 0
	v_mfma_f32_16x16x32_bf16 v[40:43], v[128:131], v[184:187], 0
	v_mfma_f32_16x16x32_bf16 v[44:47], v[136:139], v[184:187], 0
	v_mfma_f32_16x16x32_bf16 v[24:27], v[128:131], v[192:195], 0
	v_mfma_f32_16x16x32_bf16 v[28:31], v[136:139], v[192:195], 0
	v_mfma_f32_16x16x32_bf16 v[8:11], v[128:131], v[204:207], 0
	v_mfma_f32_16x16x32_bf16 v[12:15], v[136:139], v[204:207], 0
	v_mfma_f32_16x16x32_bf16 v[56:59], v[132:135], v[180:183], v[56:59]
	v_mfma_f32_16x16x32_bf16 v[60:63], v[140:143], v[180:183], v[60:63]
	v_mfma_f32_16x16x32_bf16 v[40:43], v[132:135], v[188:191], v[40:43]
	v_mfma_f32_16x16x32_bf16 v[44:47], v[140:143], v[188:191], v[44:47]
	v_mfma_f32_16x16x32_bf16 v[24:27], v[132:135], v[200:203], v[24:27]
	v_mfma_f32_16x16x32_bf16 v[28:31], v[140:143], v[200:203], v[28:31]
	v_mfma_f32_16x16x32_bf16 v[8:11], v[132:135], v[208:211], v[8:11]
	v_mfma_f32_16x16x32_bf16 v[12:15], v[140:143], v[208:211], v[12:15]
	s_setprio 0
	s_setprio 1
	v_mfma_f32_16x16x32_bf16 v[48:51], v[144:147], v[160:163], 0
	v_mfma_f32_16x16x32_bf16 v[52:55], v[152:155], v[160:163], 0
	v_mfma_f32_16x16x32_bf16 v[32:35], v[144:147], v[184:187], 0
	v_mfma_f32_16x16x32_bf16 v[36:39], v[152:155], v[184:187], 0
	v_mfma_f32_16x16x32_bf16 v[16:19], v[144:147], v[192:195], 0
	v_mfma_f32_16x16x32_bf16 v[20:23], v[152:155], v[192:195], 0
	v_mfma_f32_16x16x32_bf16 v[0:3], v[144:147], v[204:207], 0
	v_mfma_f32_16x16x32_bf16 v[4:7], v[152:155], v[204:207], 0
	v_mfma_f32_16x16x32_bf16 v[48:51], v[148:151], v[180:183], v[48:51]
	v_mfma_f32_16x16x32_bf16 v[52:55], v[156:159], v[180:183], v[52:55]
	v_mfma_f32_16x16x32_bf16 v[32:35], v[148:151], v[188:191], v[32:35]
	v_mfma_f32_16x16x32_bf16 v[36:39], v[156:159], v[188:191], v[36:39]
	s_waitcnt vmcnt(8)
	s_setprio 2
	s_barrier
	v_mfma_f32_16x16x32_bf16 v[16:19], v[148:151], v[200:203], v[16:19]
	v_mfma_f32_16x16x32_bf16 v[20:23], v[156:159], v[200:203], v[20:23]
	v_mfma_f32_16x16x32_bf16 v[0:3], v[148:151], v[208:211], v[0:3]
	v_mfma_f32_16x16x32_bf16 v[4:7], v[156:159], v[208:211], v[4:7]
	s_setprio 0
	s_add_i32 s54, 0, 0x18000
	s_add_i32 s55, 0, 0x1c000
	v_add_u32_e32 v140, s54, v196
	v_add_u32_e32 v156, s55, v196
	ds_read_b128 v[128:131], v140
	ds_read_b128 v[132:135], v140 offset:1024
	ds_read_b128 v[136:139], v140 offset:2048
	ds_read_b128 v[140:143], v140 offset:3072
	ds_read_b128 v[144:147], v156
	ds_read_b128 v[148:151], v156 offset:1024
	ds_read_b128 v[152:155], v156 offset:2048
	ds_read_b128 v[156:159], v156 offset:3072
	s_add_u32 s24, s28, 0xb0000
	s_addc_u32 s25, s29, 0
	s_mov_b32 m0, s38
	v_lshl_add_u64 v[220:221], s[24:25], 0, v[164:165]
	ds_read_b128 v[160:163], v199 offset:32768
	ds_read_b128 v[180:183], v199 offset:33792
	ds_read_b128 v[184:187], v199 offset:34816
	ds_read_b128 v[188:191], v199 offset:35840
	ds_read_b128 v[192:195], v199 offset:36864
	ds_read_b128 v[200:203], v199 offset:37888
	ds_read_b128 v[204:207], v199 offset:38912
	ds_read_b128 v[208:211], v199 offset:39936
	global_load_lds_dwordx4 v[220:221], off
	s_mov_b32 m0, s39
	v_lshl_add_u64 v[220:221], s[24:25], 0, v[168:169]
	global_load_lds_dwordx4 v[220:221], off
	s_cmp_eq_u32 s100, 0
	s_waitcnt lgkmcnt(0)
	s_cbranch_scc1 .Ldw_59
	s_waitcnt vmcnt(8)
.Ldw_59:
	s_barrier
	s_setprio 1
	v_mfma_f32_16x16x32_bf16 v[124:127], v[128:131], v[160:163], v[124:127]
	v_mfma_f32_16x16x32_bf16 v[120:123], v[136:139], v[160:163], v[120:123]
	v_mfma_f32_16x16x32_bf16 v[116:119], v[128:131], v[184:187], v[116:119]
	v_mfma_f32_16x16x32_bf16 v[108:111], v[136:139], v[184:187], v[108:111]
	v_mfma_f32_16x16x32_bf16 v[88:91], v[128:131], v[192:195], v[88:91]
	v_mfma_f32_16x16x32_bf16 v[100:103], v[136:139], v[192:195], v[100:103]
	v_mfma_f32_16x16x32_bf16 v[72:75], v[128:131], v[204:207], v[72:75]
	v_mfma_f32_16x16x32_bf16 v[76:79], v[136:139], v[204:207], v[76:79]
	v_mfma_f32_16x16x32_bf16 v[124:127], v[132:135], v[180:183], v[124:127]
	v_mfma_f32_16x16x32_bf16 v[120:123], v[140:143], v[180:183], v[120:123]
	v_mfma_f32_16x16x32_bf16 v[116:119], v[132:135], v[188:191], v[116:119]
	v_mfma_f32_16x16x32_bf16 v[108:111], v[140:143], v[188:191], v[108:111]
	v_mfma_f32_16x16x32_bf16 v[88:91], v[132:135], v[200:203], v[88:91]
	v_mfma_f32_16x16x32_bf16 v[100:103], v[140:143], v[200:203], v[100:103]
	v_mfma_f32_16x16x32_bf16 v[72:75], v[132:135], v[208:211], v[72:75]
	v_mfma_f32_16x16x32_bf16 v[76:79], v[140:143], v[208:211], v[76:79]
	s_setprio 0
	s_setprio 1
	v_mfma_f32_16x16x32_bf16 v[112:115], v[144:147], v[160:163], v[112:115]
	v_mfma_f32_16x16x32_bf16 v[104:107], v[152:155], v[160:163], v[104:107]
	v_mfma_f32_16x16x32_bf16 v[96:99], v[144:147], v[184:187], v[96:99]
	v_mfma_f32_16x16x32_bf16 v[92:95], v[152:155], v[184:187], v[92:95]
	v_mfma_f32_16x16x32_bf16 v[80:83], v[144:147], v[192:195], v[80:83]
	v_mfma_f32_16x16x32_bf16 v[84:87], v[152:155], v[192:195], v[84:87]
	v_mfma_f32_16x16x32_bf16 v[64:67], v[144:147], v[204:207], v[64:67]
	v_mfma_f32_16x16x32_bf16 v[68:71], v[152:155], v[204:207], v[68:71]
	v_mfma_f32_16x16x32_bf16 v[112:115], v[148:151], v[180:183], v[112:115]
	v_mfma_f32_16x16x32_bf16 v[104:107], v[156:159], v[180:183], v[104:107]
	v_mfma_f32_16x16x32_bf16 v[96:99], v[148:151], v[188:191], v[96:99]
	v_mfma_f32_16x16x32_bf16 v[92:95], v[156:159], v[188:191], v[92:95]
	s_waitcnt vmcnt(8)
	s_setprio 2
	s_barrier
	v_mfma_f32_16x16x32_bf16 v[80:83], v[148:151], v[200:203], v[80:83]
	v_mfma_f32_16x16x32_bf16 v[84:87], v[156:159], v[200:203], v[84:87]
	v_mfma_f32_16x16x32_bf16 v[64:67], v[148:151], v[208:211], v[64:67]
	v_mfma_f32_16x16x32_bf16 v[68:71], v[156:159], v[208:211], v[68:71]
	s_setprio 2
	s_add_i32 s24, s54, s35
	v_lshl_add_u64 v[212:213], v[212:213], 0, s[16:17]
	s_mov_b32 m0, s24
	ds_read_b128 v[160:163], v199 offset:49152
	ds_read_b128 v[180:183], v199 offset:50176
	ds_read_b128 v[184:187], v199 offset:51200
	ds_read_b128 v[188:191], v199 offset:52224
	ds_read_b128 v[192:195], v199 offset:53248
	ds_read_b128 v[200:203], v199 offset:54272
	ds_read_b128 v[204:207], v199 offset:55296
	ds_read_b128 v[208:211], v199 offset:56320
	global_load_lds_dwordx4 v[212:213], off
	s_add_i32 m0, s24, 0x2000
	s_add_u32 s24, s26, 0xb0080
	v_lshl_add_u64 v[212:213], v[214:215], 0, s[16:17]
	s_addc_u32 s25, s27, 0
	s_add_i32 s26, s55, s35
	global_load_lds_dwordx4 v[212:213], off
	s_mov_b32 m0, s26
	v_lshl_add_u64 v[212:213], s[24:25], 0, v[166:167]
	global_load_lds_dwordx4 v[212:213], off
	s_add_i32 m0, s26, 0x2000
	v_lshl_add_u64 v[212:213], s[24:25], 0, v[170:171]
	global_load_lds_dwordx4 v[212:213], off
	s_mov_b32 m0, s41
	v_lshl_add_u64 v[212:213], v[216:217], 0, s[16:17]
	global_load_lds_dwordx4 v[212:213], off
	s_mov_b32 m0, s42
	v_lshl_add_u64 v[212:213], v[218:219], 0, s[16:17]
	global_load_lds_dwordx4 v[212:213], off
	s_cmp_eq_u32 s100, 0
	s_waitcnt lgkmcnt(0)
	s_cbranch_scc1 .Ldw_60
	s_waitcnt vmcnt(8)
.Ldw_60:
	s_barrier
	s_setprio 1
	v_mfma_f32_16x16x32_bf16 v[56:59], v[128:131], v[160:163], v[56:59]
	v_mfma_f32_16x16x32_bf16 v[60:63], v[136:139], v[160:163], v[60:63]
	v_mfma_f32_16x16x32_bf16 v[40:43], v[128:131], v[184:187], v[40:43]
	v_mfma_f32_16x16x32_bf16 v[44:47], v[136:139], v[184:187], v[44:47]
	v_mfma_f32_16x16x32_bf16 v[24:27], v[128:131], v[192:195], v[24:27]
	v_mfma_f32_16x16x32_bf16 v[28:31], v[136:139], v[192:195], v[28:31]
	v_mfma_f32_16x16x32_bf16 v[8:11], v[128:131], v[204:207], v[8:11]
	v_mfma_f32_16x16x32_bf16 v[12:15], v[136:139], v[204:207], v[12:15]
	v_mfma_f32_16x16x32_bf16 v[56:59], v[132:135], v[180:183], v[56:59]
	v_mfma_f32_16x16x32_bf16 v[60:63], v[140:143], v[180:183], v[60:63]
	v_mfma_f32_16x16x32_bf16 v[40:43], v[132:135], v[188:191], v[40:43]
	v_mfma_f32_16x16x32_bf16 v[44:47], v[140:143], v[188:191], v[44:47]
	v_mfma_f32_16x16x32_bf16 v[24:27], v[132:135], v[200:203], v[24:27]
	v_mfma_f32_16x16x32_bf16 v[28:31], v[140:143], v[200:203], v[28:31]
	v_mfma_f32_16x16x32_bf16 v[8:11], v[132:135], v[208:211], v[8:11]
	v_mfma_f32_16x16x32_bf16 v[12:15], v[140:143], v[208:211], v[12:15]
	s_setprio 0
	s_setprio 1
	v_mfma_f32_16x16x32_bf16 v[48:51], v[144:147], v[160:163], v[48:51]
	v_mfma_f32_16x16x32_bf16 v[52:55], v[152:155], v[160:163], v[52:55]
	v_mfma_f32_16x16x32_bf16 v[32:35], v[144:147], v[184:187], v[32:35]
	v_mfma_f32_16x16x32_bf16 v[36:39], v[152:155], v[184:187], v[36:39]
	v_mfma_f32_16x16x32_bf16 v[16:19], v[144:147], v[192:195], v[16:19]
	v_mfma_f32_16x16x32_bf16 v[20:23], v[152:155], v[192:195], v[20:23]
	v_mfma_f32_16x16x32_bf16 v[0:3], v[144:147], v[204:207], v[0:3]
	v_mfma_f32_16x16x32_bf16 v[4:7], v[152:155], v[204:207], v[4:7]
	v_mfma_f32_16x16x32_bf16 v[48:51], v[148:151], v[180:183], v[48:51]
	v_mfma_f32_16x16x32_bf16 v[52:55], v[156:159], v[180:183], v[52:55]
	v_mfma_f32_16x16x32_bf16 v[32:35], v[148:151], v[188:191], v[32:35]
	v_mfma_f32_16x16x32_bf16 v[36:39], v[156:159], v[188:191], v[36:39]
	s_waitcnt vmcnt(8)
	s_setprio 2
	s_barrier
	v_mfma_f32_16x16x32_bf16 v[16:19], v[148:151], v[200:203], v[16:19]
	v_mfma_f32_16x16x32_bf16 v[20:23], v[156:159], v[200:203], v[20:23]
	v_mfma_f32_16x16x32_bf16 v[0:3], v[148:151], v[208:211], v[0:3]
	v_mfma_f32_16x16x32_bf16 v[4:7], v[156:159], v[208:211], v[4:7]
	s_setprio 0
	s_add_i32 s53, s53, 2
	s_add_u32 s51, s51, 0x100
	s_addc_u32 s52, s52, 0
	s_cmp_gt_u32 s53, 41
	s_mov_b64 s[24:25], s[4:5]
.LBB0_1310:
	ds_read_b128 v[128:131], v197
	ds_read_b128 v[132:135], v197 offset:1024
	ds_read_b128 v[136:139], v197 offset:2048
	ds_read_b128 v[140:143], v197 offset:3072
	ds_read_b128 v[144:147], v198
	ds_read_b128 v[148:151], v198 offset:1024
	ds_read_b128 v[152:155], v198 offset:2048
	ds_read_b128 v[156:159], v198 offset:3072
	s_add_u32 s4, s24, 0x100
	s_addc_u32 s5, s25, 0
	s_cmp_eq_u32 s53, 40
	s_cselect_b32 s29, s21, s5
	s_cselect_b32 s28, s20, s4
	s_cselect_b32 s27, s23, s52
	s_cselect_b32 s26, s22, s51
	v_lshl_add_u64 v[212:213], s[24:25], 0, v[172:173]
	s_add_i32 m0, s36, 0xc000
	ds_read_b128 v[160:163], v199
	ds_read_b128 v[180:183], v199 offset:1024
	ds_read_b128 v[184:187], v199 offset:2048
	ds_read_b128 v[188:191], v199 offset:3072
	ds_read_b128 v[192:195], v199 offset:4096
	ds_read_b128 v[200:203], v199 offset:5120
	ds_read_b128 v[204:207], v199 offset:6144
	ds_read_b128 v[208:211], v199 offset:7168
	global_load_lds_dwordx4 v[212:213], off
	s_add_i32 m0, s36, 0xe000
	v_lshl_add_u64 v[212:213], s[24:25], 0, v[174:175]
	global_load_lds_dwordx4 v[212:213], off
	s_cmp_eq_u32 s100, 0
	s_waitcnt lgkmcnt(0)
	s_cbranch_scc1 .Ldw_61
	s_waitcnt vmcnt(8)
.Ldw_61:
	s_barrier
	s_setprio 1
	v_mfma_f32_16x16x32_bf16 v[124:127], v[128:131], v[160:163], v[124:127]
	v_mfma_f32_16x16x32_bf16 v[120:123], v[136:139], v[160:163], v[120:123]
	v_mfma_f32_16x16x32_bf16 v[116:119], v[128:131], v[184:187], v[116:119]
	v_mfma_f32_16x16x32_bf16 v[108:111], v[136:139], v[184:187], v[108:111]
	v_mfma_f32_16x16x32_bf16 v[88:91], v[128:131], v[192:195], v[88:91]
	v_mfma_f32_16x16x32_bf16 v[100:103], v[136:139], v[192:195], v[100:103]
	v_mfma_f32_16x16x32_bf16 v[72:75], v[128:131], v[204:207], v[72:75]
	v_mfma_f32_16x16x32_bf16 v[76:79], v[136:139], v[204:207], v[76:79]
	v_mfma_f32_16x16x32_bf16 v[124:127], v[132:135], v[180:183], v[124:127]
	v_mfma_f32_16x16x32_bf16 v[120:123], v[140:143], v[180:183], v[120:123]
	v_mfma_f32_16x16x32_bf16 v[116:119], v[132:135], v[188:191], v[116:119]
	v_mfma_f32_16x16x32_bf16 v[108:111], v[140:143], v[188:191], v[108:111]
	v_mfma_f32_16x16x32_bf16 v[88:91], v[132:135], v[200:203], v[88:91]
	v_mfma_f32_16x16x32_bf16 v[100:103], v[140:143], v[200:203], v[100:103]
	v_mfma_f32_16x16x32_bf16 v[72:75], v[132:135], v[208:211], v[72:75]
	v_mfma_f32_16x16x32_bf16 v[76:79], v[140:143], v[208:211], v[76:79]
	s_setprio 0
	s_setprio 1
	v_mfma_f32_16x16x32_bf16 v[112:115], v[144:147], v[160:163], v[112:115]
	v_mfma_f32_16x16x32_bf16 v[104:107], v[152:155], v[160:163], v[104:107]
	v_mfma_f32_16x16x32_bf16 v[96:99], v[144:147], v[184:187], v[96:99]
	v_mfma_f32_16x16x32_bf16 v[92:95], v[152:155], v[184:187], v[92:95]
	v_mfma_f32_16x16x32_bf16 v[80:83], v[144:147], v[192:195], v[80:83]
	v_mfma_f32_16x16x32_bf16 v[84:87], v[152:155], v[192:195], v[84:87]
	v_mfma_f32_16x16x32_bf16 v[64:67], v[144:147], v[204:207], v[64:67]
	v_mfma_f32_16x16x32_bf16 v[68:71], v[152:155], v[204:207], v[68:71]
	v_mfma_f32_16x16x32_bf16 v[112:115], v[148:151], v[180:183], v[112:115]
	v_mfma_f32_16x16x32_bf16 v[104:107], v[156:159], v[180:183], v[104:107]
	v_mfma_f32_16x16x32_bf16 v[96:99], v[148:151], v[188:191], v[96:99]
	v_mfma_f32_16x16x32_bf16 v[92:95], v[156:159], v[188:191], v[92:95]
	s_waitcnt vmcnt(8)
	s_setprio 2
	s_barrier
	v_mfma_f32_16x16x32_bf16 v[80:83], v[148:151], v[200:203], v[80:83]
	v_mfma_f32_16x16x32_bf16 v[84:87], v[156:159], v[200:203], v[84:87]
	v_mfma_f32_16x16x32_bf16 v[64:67], v[148:151], v[208:211], v[64:67]
	v_mfma_f32_16x16x32_bf16 v[68:71], v[156:159], v[208:211], v[68:71]
	s_setprio 2
	s_add_i32 s24, s45, s35
	v_lshl_add_u64 v[212:213], s[26:27], 0, v[166:167]
	s_mov_b32 m0, s24
	ds_read_b128 v[160:163], v199 offset:16384
	ds_read_b128 v[180:183], v199 offset:17408
	ds_read_b128 v[184:187], v199 offset:18432
	ds_read_b128 v[188:191], v199 offset:19456
	ds_read_b128 v[192:195], v199 offset:20480
	ds_read_b128 v[200:203], v199 offset:21504
	ds_read_b128 v[204:207], v199 offset:22528
	ds_read_b128 v[208:211], v199 offset:23552
	global_load_lds_dwordx4 v[212:213], off
	s_add_i32 m0, s24, 0x2000
	s_add_u32 s24, s26, 0xb0000
	v_lshl_add_u64 v[214:215], s[26:27], 0, v[170:171]
	s_addc_u32 s25, s27, 0
	s_add_i32 s54, s46, s35
	global_load_lds_dwordx4 v[214:215], off
	v_lshl_add_u64 v[216:217], s[24:25], 0, v[166:167]
	s_mov_b32 m0, s54
	v_lshl_add_u64 v[218:219], s[28:29], 0, v[168:169]
	global_load_lds_dwordx4 v[216:217], off
	s_add_i32 m0, s54, 0x2000
	v_lshl_add_u64 v[216:217], s[24:25], 0, v[170:171]
	global_load_lds_dwordx4 v[216:217], off
	s_mov_b32 m0, s36
	v_lshl_add_u64 v[216:217], s[28:29], 0, v[164:165]
	global_load_lds_dwordx4 v[216:217], off
	s_mov_b32 m0, s37
	s_nop 0
	global_load_lds_dwordx4 v[218:219], off
	s_cmp_eq_u32 s100, 0
	s_waitcnt lgkmcnt(0)
	s_cbranch_scc1 .Ldw_62
	s_waitcnt vmcnt(8)
.Ldw_62:
	s_barrier
	s_setprio 1
	v_mfma_f32_16x16x32_bf16 v[56:59], v[128:131], v[160:163], v[56:59]
	v_mfma_f32_16x16x32_bf16 v[60:63], v[136:139], v[160:163], v[60:63]
	v_mfma_f32_16x16x32_bf16 v[40:43], v[128:131], v[184:187], v[40:43]
	v_mfma_f32_16x16x32_bf16 v[44:47], v[136:139], v[184:187], v[44:47]
	v_mfma_f32_16x16x32_bf16 v[24:27], v[128:131], v[192:195], v[24:27]
	v_mfma_f32_16x16x32_bf16 v[28:31], v[136:139], v[192:195], v[28:31]
	v_mfma_f32_16x16x32_bf16 v[8:11], v[128:131], v[204:207], v[8:11]
	v_mfma_f32_16x16x32_bf16 v[12:15], v[136:139], v[204:207], v[12:15]
	v_mfma_f32_16x16x32_bf16 v[56:59], v[132:135], v[180:183], v[56:59]
	v_mfma_f32_16x16x32_bf16 v[60:63], v[140:143], v[180:183], v[60:63]
	v_mfma_f32_16x16x32_bf16 v[40:43], v[132:135], v[188:191], v[40:43]
	v_mfma_f32_16x16x32_bf16 v[44:47], v[140:143], v[188:191], v[44:47]
	v_mfma_f32_16x16x32_bf16 v[24:27], v[132:135], v[200:203], v[24:27]
	v_mfma_f32_16x16x32_bf16 v[28:31], v[140:143], v[200:203], v[28:31]
	v_mfma_f32_16x16x32_bf16 v[8:11], v[132:135], v[208:211], v[8:11]
	v_mfma_f32_16x16x32_bf16 v[12:15], v[140:143], v[208:211], v[12:15]
	s_setprio 0
	s_setprio 1
	v_mfma_f32_16x16x32_bf16 v[48:51], v[144:147], v[160:163], v[48:51]
	v_mfma_f32_16x16x32_bf16 v[52:55], v[152:155], v[160:163], v[52:55]
	v_mfma_f32_16x16x32_bf16 v[32:35], v[144:147], v[184:187], v[32:35]
	v_mfma_f32_16x16x32_bf16 v[36:39], v[152:155], v[184:187], v[36:39]
	v_mfma_f32_16x16x32_bf16 v[16:19], v[144:147], v[192:195], v[16:19]
	v_mfma_f32_16x16x32_bf16 v[20:23], v[152:155], v[192:195], v[20:23]
	v_mfma_f32_16x16x32_bf16 v[0:3], v[144:147], v[204:207], v[0:3]
	v_mfma_f32_16x16x32_bf16 v[4:7], v[152:155], v[204:207], v[4:7]
	v_mfma_f32_16x16x32_bf16 v[48:51], v[148:151], v[180:183], v[48:51]
	v_mfma_f32_16x16x32_bf16 v[52:55], v[156:159], v[180:183], v[52:55]
	v_mfma_f32_16x16x32_bf16 v[32:35], v[148:151], v[188:191], v[32:35]
	v_mfma_f32_16x16x32_bf16 v[36:39], v[156:159], v[188:191], v[36:39]
	s_waitcnt vmcnt(8)
	s_setprio 2
	s_barrier
	v_mfma_f32_16x16x32_bf16 v[16:19], v[148:151], v[200:203], v[16:19]
	v_mfma_f32_16x16x32_bf16 v[20:23], v[156:159], v[200:203], v[20:23]
	v_mfma_f32_16x16x32_bf16 v[0:3], v[148:151], v[208:211], v[0:3]
	v_mfma_f32_16x16x32_bf16 v[4:7], v[156:159], v[208:211], v[4:7]
	s_setprio 0
	s_add_i32 s54, 0, 0x18000
	s_add_i32 s55, 0, 0x1c000
	v_add_u32_e32 v140, s54, v196
	v_add_u32_e32 v156, s55, v196
	ds_read_b128 v[128:131], v140
	ds_read_b128 v[132:135], v140 offset:1024
	ds_read_b128 v[136:139], v140 offset:2048
	ds_read_b128 v[140:143], v140 offset:3072
	ds_read_b128 v[144:147], v156
	ds_read_b128 v[148:151], v156 offset:1024
	ds_read_b128 v[152:155], v156 offset:2048
	ds_read_b128 v[156:159], v156 offset:3072
	s_add_u32 s24, s28, 0xb0000
	s_addc_u32 s25, s29, 0
	s_mov_b32 m0, s38
	v_lshl_add_u64 v[220:221], s[24:25], 0, v[164:165]
	ds_read_b128 v[160:163], v199 offset:32768
	ds_read_b128 v[180:183], v199 offset:33792
	ds_read_b128 v[184:187], v199 offset:34816
	ds_read_b128 v[188:191], v199 offset:35840
	ds_read_b128 v[192:195], v199 offset:36864
	ds_read_b128 v[200:203], v199 offset:37888
	ds_read_b128 v[204:207], v199 offset:38912
	ds_read_b128 v[208:211], v199 offset:39936
	global_load_lds_dwordx4 v[220:221], off
	s_mov_b32 m0, s39
	v_lshl_add_u64 v[220:221], s[24:25], 0, v[168:169]
	global_load_lds_dwordx4 v[220:221], off
	s_cmp_eq_u32 s100, 0
	s_waitcnt lgkmcnt(0)
	s_cbranch_scc1 .Ldw_63
	s_waitcnt vmcnt(8)

.Ldw_64:
	s_barrier
	s_setprio 1
	v_mfma_f32_16x16x32_bf16 v[56:59], v[128:131], v[160:163], v[56:59]
	v_mfma_f32_16x16x32_bf16 v[60:63], v[136:139], v[160:163], v[60:63]
	v_mfma_f32_16x16x32_bf16 v[40:43], v[128:131], v[184:187], v[40:43]
	v_mfma_f32_16x16x32_bf16 v[44:47], v[136:139], v[184:187], v[44:47]
	v_mfma_f32_16x16x32_bf16 v[24:27], v[128:131], v[192:195], v[24:27]
	v_mfma_f32_16x16x32_bf16 v[28:31], v[136:139], v[192:195], v[28:31]
	v_mfma_f32_16x16x32_bf16 v[8:11], v[128:131], v[204:207], v[8:11]
	v_mfma_f32_16x16x32_bf16 v[12:15], v[136:139], v[204:207], v[12:15]
	v_mfma_f32_16x16x32_bf16 v[56:59], v[132:135], v[180:183], v[56:59]
	v_mfma_f32_16x16x32_bf16 v[60:63], v[140:143], v[180:183], v[60:63]
	v_mfma_f32_16x16x32_bf16 v[40:43], v[132:135], v[188:191], v[40:43]
	v_mfma_f32_16x16x32_bf16 v[44:47], v[140:143], v[188:191], v[44:47]
	v_mfma_f32_16x16x32_bf16 v[24:27], v[132:135], v[200:203], v[24:27]
	v_mfma_f32_16x16x32_bf16 v[28:31], v[140:143], v[200:203], v[28:31]
	v_mfma_f32_16x16x32_bf16 v[8:11], v[132:135], v[208:211], v[8:11]
	v_mfma_f32_16x16x32_bf16 v[12:15], v[140:143], v[208:211], v[12:15]
	s_setprio 0
	s_setprio 1
	v_mfma_f32_16x16x32_bf16 v[48:51], v[144:147], v[160:163], v[48:51]
	v_mfma_f32_16x16x32_bf16 v[52:55], v[152:155], v[160:163], v[52:55]
	v_mfma_f32_16x16x32_bf16 v[32:35], v[144:147], v[184:187], v[32:35]
	v_mfma_f32_16x16x32_bf16 v[36:39], v[152:155], v[184:187], v[36:39]
	v_mfma_f32_16x16x32_bf16 v[16:19], v[144:147], v[192:195], v[16:19]
	v_mfma_f32_16x16x32_bf16 v[20:23], v[152:155], v[192:195], v[20:23]
	v_mfma_f32_16x16x32_bf16 v[0:3], v[144:147], v[204:207], v[0:3]
	v_mfma_f32_16x16x32_bf16 v[4:7], v[152:155], v[204:207], v[4:7]
	v_mfma_f32_16x16x32_bf16 v[48:51], v[148:151], v[180:183], v[48:51]
	v_mfma_f32_16x16x32_bf16 v[52:55], v[156:159], v[180:183], v[52:55]
	v_mfma_f32_16x16x32_bf16 v[32:35], v[148:151], v[188:191], v[32:35]
	v_mfma_f32_16x16x32_bf16 v[36:39], v[156:159], v[188:191], v[36:39]
	s_waitcnt vmcnt(8)
	s_setprio 2
	s_barrier
	v_mfma_f32_16x16x32_bf16 v[16:19], v[148:151], v[200:203], v[16:19]
	v_mfma_f32_16x16x32_bf16 v[20:23], v[156:159], v[200:203], v[20:23]
	v_mfma_f32_16x16x32_bf16 v[0:3], v[148:151], v[208:211], v[0:3]
	v_mfma_f32_16x16x32_bf16 v[4:7], v[156:159], v[208:211], v[4:7]
	s_setprio 0
	s_add_i32 s53, s53, 2
	s_add_u32 s51, s51, 0x100
	s_addc_u32 s52, s52, 0
	s_cmp_gt_u32 s53, 41
	s_mov_b64 s[24:25], s[4:5]
	s_cbranch_scc0 .LBB0_1310

	.amdhsa_kernel _Z4mega5MArgs
		.amdhsa_group_segment_fixed_size 0
		.amdhsa_private_segment_fixed_size 0
		.amdhsa_kernarg_size 424
		.amdhsa_user_sgpr_count 2
		.amdhsa_user_sgpr_dispatch_ptr 0
		.amdhsa_user_sgpr_queue_ptr 0
		.amdhsa_user_sgpr_kernarg_segment_ptr 1
		.amdhsa_user_sgpr_dispatch_id 0
		.amdhsa_user_sgpr_kernarg_preload_length 0
		.amdhsa_user_sgpr_kernarg_preload_offset 0
		.amdhsa_user_sgpr_private_segment_size 0
		.amdhsa_uses_dynamic_stack 0
		.amdhsa_enable_private_segment 0
		.amdhsa_system_sgpr_workgroup_id_x 1
		.amdhsa_system_sgpr_workgroup_id_y 0
		.amdhsa_system_sgpr_workgroup_id_z 0
		.amdhsa_system_sgpr_workgroup_info 0
		.amdhsa_system_vgpr_workitem_id 0
		.amdhsa_next_free_vgpr 255
		.amdhsa_next_free_sgpr 101
		.amdhsa_accum_offset 256
		.amdhsa_reserve_vcc 1
		.amdhsa_float_round_mode_32 0
		.amdhsa_float_round_mode_16_64 0
		.amdhsa_float_denorm_mode_32 3
		.amdhsa_float_denorm_mode_16_64 3
		.amdhsa_dx10_clamp 1
		.amdhsa_ieee_mode 1
		.amdhsa_fp16_overflow 0
		.amdhsa_tg_split 0
		.amdhsa_exception_fp_ieee_invalid_op 0
		.amdhsa_exception_fp_denorm_src 0
		.amdhsa_exception_fp_ieee_div_zero 0
		.amdhsa_exception_fp_ieee_overflow 0
		.amdhsa_exception_fp_ieee_underflow 0
		.amdhsa_exception_fp_ieee_inexact 0
		.amdhsa_exception_int_div_zero 0
	.end_amdhsa_kernel

amdhsa.kernels:
  - .agpr_count:     0
    .args:
      - .offset:         0
        .size:           168
        .value_kind:     by_value
      - .offset:         168
        .size:           4
        .value_kind:     hidden_block_count_x
      - .offset:         172
        .size:           4
        .value_kind:     hidden_block_count_y
      - .offset:         176
        .size:           4
        .value_kind:     hidden_block_count_z
      - .offset:         180
        .size:           2
        .value_kind:     hidden_group_size_x
      - .offset:         182
        .size:           2
        .value_kind:     hidden_group_size_y
      - .offset:         184
        .size:           2
        .value_kind:     hidden_group_size_z
      - .offset:         186
        .size:           2
        .value_kind:     hidden_remainder_x
      - .offset:         188
        .size:           2
        .value_kind:     hidden_remainder_y
      - .offset:         190
        .size:           2
        .value_kind:     hidden_remainder_z
      - .offset:         208
        .size:           8
        .value_kind:     hidden_global_offset_x
      - .offset:         216
        .size:           8
        .value_kind:     hidden_global_offset_y
      - .offset:         224
        .size:           8
        .value_kind:     hidden_global_offset_z
      - .offset:         232
        .size:           2
        .value_kind:     hidden_grid_dims
      - .offset:         288
        .size:           4
        .value_kind:     hidden_dynamic_lds_size
    .group_segment_fixed_size: 0
    .kernarg_segment_align: 8
    .kernarg_segment_size: 424
    .language:       OpenCL C
    .language_version:
      - 2
      - 0
    .max_flat_workgroup_size: 512
    .name:           _Z4mega5MArgs
    .private_segment_fixed_size: 0
    .sgpr_count:     107
    .sgpr_spill_count: 8
    .symbol:         _Z4mega5MArgs.kd
    .uniform_work_group_size: 1
    .uses_dynamic_stack: false
    .vgpr_count:     255
    .vgpr_spill_count: 0
    .wavefront_size: 64
